# strategy 4: one static s_setprio 1 for the younger wave half (waves 4-7) per GEMM phase, all 160 per-segment s_setprio flips deleted
# baseline (speedup 1.0000x reference)
; #define PG8_STAGE(bufoff, gbase, voff) do { _Pragma("unroll") for (int _i = 0; _i < 2; ++_i) \
;         __builtin_amdgcn_global_load_lds((const unsigned*)((const char*)(gbase) + (voff)[_i]), (LAS unsigned*)(lds + (bufoff) + ldsw + _i * 8192), 16, 0, 0); } while (0)
; #define PG8_BAR __builtin_amdgcn_s_barrier()
;     __device__ __forceinline__ bool next(int i, Unit& u) const {
;         const long L = (long)i * G + c; if (L >= (long)nM * nN) return false;
;         tile_of((int)L, nM, nN, u.pm, u.pn); u.sub = 0;
;         u.A = A + (size_t)u.pm * BM * lda * 2; u.B = B + (size_t)u.pn * BM * ldb * 2; return true;
; template <class Epi, class Sched>
; __device__ __forceinline__ void gemm_phase(LAS unsigned char* lds, const int lda, const int ldb, const int K, const Sched& S, const Epi& E) {
;     const int tid = threadIdx.x, wid = __builtin_amdgcn_readfirstlane(tid >> 6), lane = tid & 63, wr = wid >> 2, wc = wid & 3, fr = lane & 15, fq = lane >> 4;
;     const int nt = K / BK;
;     unsigned voffA[2], voffB[2];
; #pragma unroll
;     for (int i = 0; i < 2; ++i) { int R, C; stage_rc(tid * 16 + i * 8192, R, C); const int Rb = (R & ~31) + perm32(R & 31);
;         voffA[i] = (unsigned)(R * lda + C) * 2u; voffB[i] = (unsigned)(Rb * ldb + C) * 2u; }
;     const size_t kstep = (size_t)(BK * 2);
;     const size_t hstepA = (size_t)HALF * lda * 2, hstepB = (size_t)HALF * ldb * 2;
;     const unsigned ldsw = (unsigned)wid * 1024u;
;     const int aoff = lds_byte(wr * 64 + fr, fq * 8), boff = lds_byte(wc * 32 + fr, fq * 8);
;     ...
;     Unit cur, nxt; int ui = 0;
;     if (!S.next(0, cur)) return;
;     f32x4 acc[2][2][4][2];
; #pragma unroll
;     for (int a = 0; a < 2; ++a)
; #pragma unroll
;         for (int b = 0; b < 2; ++b)
; #pragma unroll
;             for (int m = 0; m < 4; ++m)
; #pragma unroll
;                 for (int n = 0; n < 2; ++n) acc[a][b][m][n] = (f32x4){0.f, 0.f, 0.f, 0.f};
;     bf16x8 At[4][2], B0[2][2], B1[2][2];
;     float rsv[8];
; #pragma unroll
;     for (int i = 0; i < 8; ++i) rsv[i] = 0.f;
;     const char* cA = cur.A; const char* cB = cur.B;
;     PG8_STAGE(PG8_SB(0, 0), cB, voffB); PG8_STAGE(PG8_SB(0, 1), cB + hstepB, voffB); PG8_STAGE(PG8_SA(0, 0), cA, voffA); PG8_STAGE(PG8_SA(0, 1), cA + hstepA, voffA);
;     if (wr == 1) PG8_BAR;
.LBB0_230:
.LBB0_231:
	s_cmp_lt_i32 s56, 2
	s_cselect_b64 s[4:5], -1, 0
	s_add_u32 s46, s54, 0xf6a8000
	s_addc_u32 s47, s55, 0
	s_and_b64 s[4:5], s[4:5], s[0:1]
	s_andn2_b64 vcc, exec, s[4:5]
	s_cbranch_vccnz .LBB0_250
	s_cmpk_gt_i32 s2, 0x20ff
	v_readfirstlane_b32 s1, v194
	s_cbranch_scc1 .LBB0_250
	v_lshrrev_b32_e32 v1, 5, v194
	v_lshrrev_b32_e32 v3, 1, v194
	v_and_b32_e32 v1, 4, v1
	v_bfe_u32 v2, v194, 2, 2
	v_and_b32_e32 v13, 24, v3
	v_or3_b32 v1, v1, v2, v13
	v_lshlrev_b32_e32 v2, 4, v194
	v_add_u32_e32 v10, 0x2000, v2
	v_lshrrev_b32_e32 v3, 7, v10
	s_movk_i32 s0, 0xe0
	v_and_b32_e32 v5, 32, v194
	v_and_or_b32 v4, v3, s0, v1
	v_bitop3_b32 v11, v2, v5, 48 bitop3:0x6c
	v_and_b32_e32 v12, 64, v194
	v_bfe_u32 v14, v194, 2, 4
	s_movk_i32 s0, 0xf0
	v_or_b32_e32 v2, v11, v12
	v_and_or_b32 v3, v3, s0, v14
	v_lshl_or_b32 v198, v3, 11, v2
	v_lshrrev_b32_e32 v3, 3, v194
	s_movk_i32 s0, 0x60
	v_and_or_b32 v1, v3, s0, v1
	s_movk_i32 s0, 0x70
	s_ashr_i32 s33, s2, 31
	v_lshl_or_b32 v200, v1, 11, v2
	v_and_or_b32 v1, v3, s0, v14
	s_lshr_b32 s0, s33, 29
	s_add_i32 s0, s2, s0
	s_lshr_b32 s8, s1, 6
	s_and_b32 s6, s0, -8
	s_lshr_b32 s10, s1, 8
	s_lshl_b32 s3, s8, 10
	s_sub_i32 s6, s2, s6
	s_cmp_lt_i32 s6, 0
	s_movk_i32 s36, 0x421
	s_cselect_b32 s7, s36, 0x420
	s_mul_i32 s6, s6, s7
	s_ashr_i32 s0, s0, 3
	s_add_i32 s6, s6, s0
	s_mul_hi_i32 s0, s6, 0x2e8ba2e9
	s_lshr_b32 s7, s0, 31
	s_ashr_i32 s0, s0, 5
	s_add_i32 s0, s0, s7
	s_lshl_b32 s7, s0, 3
	s_mulk_i32 s0, 0xb0
	s_sub_i32 s0, s6, s0
	s_bfe_u32 s6, s0, 0x3001c
	s_add_i32 s6, s0, s6
	s_and_b32 s9, s6, 0xfff8
	s_sub_i32 s0, s0, s9
	s_sext_i32_i16 s0, s0
	s_add_i32 s20, s7, s0
	s_sext_i32_i16 s0, s6
	s_ashr_i32 s21, s20, 31
	s_lshr_b32 s0, s0, 3
	s_lshl_b64 s[6:7], s[20:21], 19
	s_add_u32 s22, s60, s6
	s_addc_u32 s23, s61, s7
	s_bfe_i64 s[6:7], s[0:1], 0x100000
	s_lshl_b64 s[6:7], s[6:7], 19
	s_add_u32 s24, s54, s6
	s_addc_u32 s25, s55, s7
	s_add_i32 s37, s3, 0
	s_add_i32 m0, s37, 0x10000
	v_lshl_or_b32 v196, v4, 11, v2
	global_load_lds_dwordx4 v200, s[24:25]
	s_add_i32 m0, s37, 0x12000
	s_add_u32 s6, s24, 0x40000
	global_load_lds_dwordx4 v196, s[24:25]
	s_addc_u32 s7, s25, 0
	s_add_i32 m0, s37, 0x14000
	s_add_i32 s38, s37, 0x2000
	global_load_lds_dwordx4 v200, s[6:7]
	s_add_i32 m0, s37, 0x16000
	v_lshl_or_b32 v202, v1, 11, v2
	global_load_lds_dwordx4 v196, s[6:7]
	s_mov_b32 m0, s37
	s_add_u32 s6, s22, 0x40000
	global_load_lds_dwordx4 v202, s[22:23]
	s_mov_b32 m0, s38
	s_addc_u32 s7, s23, 0
	s_add_i32 s39, s37, 0x4000
	global_load_lds_dwordx4 v198, s[22:23]
	s_mov_b32 m0, s39
	s_add_i32 s40, s37, 0x6000
	global_load_lds_dwordx4 v202, s[6:7]
	s_mov_b32 m0, s40
	v_mov_b32_e32 v201, 0
	global_load_lds_dwordx4 v198, s[6:7]
	v_mov_b32_e32 v197, v201
	v_mov_b32_e32 v203, v201
	v_mov_b32_e32 v199, v201
	s_cmp_eq_u32 s10, 1
	s_mov_b32 s41, 0
	v_lshl_add_u64 v[8:9], s[24:25], 0, v[200:201]
	v_lshl_add_u64 v[6:7], s[24:25], 0, v[196:197]
	v_lshl_add_u64 v[2:3], s[22:23], 0, v[202:203]
	s_cselect_b64 s[6:7], -1, 0
	s_cmp_lg_u32 s10, 1
	v_lshl_add_u64 v[4:5], s[22:23], 0, v[198:199]
	s_cbranch_scc1 .LBB0_235
	s_setprio 1
	s_barrier

; #define PG8_STAGE(bufoff, gbase, voff) do { _Pragma("unroll") for (int _i = 0; _i < 2; ++_i) \
;         __builtin_amdgcn_global_load_lds((const unsigned*)((const char*)(gbase) + (voff)[_i]), (LAS unsigned*)(lds + (bufoff) + ldsw + _i * 8192), 16, 0, 0); } while (0)
; #define PG8_LDA(dst, b, h) do { _Pragma("unroll") for (int m = 0; m < 4; ++m) _Pragma("unroll") for (int k = 0; k < 2; ++k) dst[m][k] = *(const LAS bf16x8*)(lds + PG8_SA(b, h) + aoff + m * 2048 + k * 1024); } while (0)
; #define PG8_LDB(dst, b, h) do { _Pragma("unroll") for (int n = 0; n < 2; ++n) _Pragma("unroll") for (int k = 0; k < 2; ++k) dst[n][k] = *(const LAS bf16x8*)(lds + PG8_SB(b, h) + boff + n * 2048 + k * 1024); } while (0)
; #define PG8_MMA(ai, bj, At, Bt) do { __builtin_amdgcn_s_setprio(1); _Pragma("unroll") for (int m = 0; m < 4; ++m) _Pragma("unroll") for (int n = 0; n < 2; ++n) _Pragma("unroll") for (int k = 0; k < 2; ++k) \
;         acc[ai][bj][m][n] = __builtin_amdgcn_mfma_f32_16x16x32_bf16(Bt[n][k], At[m][k], acc[ai][bj][m][n], 0, 0, 0); __builtin_amdgcn_s_setprio(0); } while (0)
; #define PG8_WAIT_V(n) asm volatile("s_waitcnt vmcnt(" #n ")" ::: "memory")
; template <class Epi, class Sched>
; __device__ __forceinline__ void gemm_phase(LAS unsigned char* lds, const int lda, const int ldb, const int K, const Sched& S, const Epi& E) {
;     ...
;         const bool has_next = S.next(ui + 1, nxt);
;         const char* nA = has_next ? nxt.A : cA; const char* nB = has_next ? nxt.B : cB;
;         for (int t = 0; t < nt; t += 2) {
;             const bool last = (t == nt - 2);
;             const char* a1 = cA + (size_t)(t + 1) * kstep;
;             const char* a2 = last ? nA : cA + (size_t)(t + 2) * kstep; const char* b2 = last ? nB : cB + (size_t)(t + 2) * kstep;
;             const char* a3 = a2 + kstep; const char* b3 = b2 + kstep;
;             PG8_LDB(B0, 0, 0); PG8_LDB(B1, 0, 1); PG8_SCHED; PG8_LDA(At, 0, 0); PG8_STAGE(PG8_SA(1, 1), a1 + hstepA, voffA);
;             PG8_WAIT_V(8); PG8_WAIT_L(0); PG8_BAR; PG8_MMA(0, 0, At, B0); PG8_MMA(0, 1, At, B1); PG8_BAR; PG8_SCHED;
;             PG8_LDA(At, 0, 1); PG8_STAGE(PG8_SB(0, 0), b2, voffB); PG8_STAGE(PG8_SB(0, 1), b2 + hstepB, voffB); PG8_STAGE(PG8_SA(0, 0), a2, voffA);
;             PG8_WAIT_V(8); PG8_WAIT_L(0); PG8_BAR; PG8_MMA(1, 0, At, B0); PG8_MMA(1, 1, At, B1); PG8_BAR; PG8_SCHED;
.LBB0_240:
	s_lshl_b32 s20, s20, 8
	s_ashr_i32 s21, s20, 31
	s_add_u32 s22, s22, 0x40080
	s_addc_u32 s23, s23, 0
	s_add_u32 s13, s24, 0x100
	s_addc_u32 s15, s25, 0
	s_mov_b32 s65, -2
	v_lshl_add_u64 v[214:215], s[20:21], 2, v[204:205]
	v_add_u32_e32 v230, 0x80, v200
	v_add_u32_e32 v231, 0x80, v196
	v_add_u32_e32 v232, 0x80, v202
	v_add_u32_e32 v233, 0x80, v198
	s_add_u32 s21, s22, 0xfffc0080
	s_addc_u32 s24, s23, -1
	s_cmp_eq_u32 s65, 12
	s_cselect_b32 s29, s17, s24
	s_cselect_b32 s28, s16, s21
	s_cselect_b32 s31, s19, s15
	s_cselect_b32 s30, s18, s13
	s_add_i32 s72, s50, s3
	s_add_i32 m0, s37, 0xc000
	s_add_i32 s71, s37, 0xe000
	s_add_i32 s73, s72, 0x2000
	s_add_u32 s48, s30, 0x40000
	s_addc_u32 s49, s31, 0
	s_add_i32 s74, s51, s3
	s_add_i32 s75, s74, 0x2000
	s_add_i32 s76, 0, 0x18000
	s_add_i32 s77, 0, 0x1c000
	s_add_u32 s26, s28, 0x40000
	s_addc_u32 s27, s29, 0
	s_add_i32 s68, s76, s3
	s_add_i32 s21, s68, 0x2000
	s_add_u32 s24, s30, 0x40080
	s_addc_u32 s25, s31, 0
	s_add_i32 s70, s77, s3
	s_add_i32 s69, s70, 0x2000
	s_cmp_lg_u32 s65, 12
	global_load_lds_dwordx4 v206, s[22:23]
	s_mov_b32 m0, s71
	s_nop 0
	global_load_lds_dwordx4 v208, s[22:23]
	s_waitcnt vmcnt(8)
	s_waitcnt lgkmcnt(0)
	s_barrier
	s_waitcnt lgkmcnt(0)
	v_mfma_f32_16x16x32_bf16 v[126:129], v[130:133], v[162:165], 0
	v_mfma_f32_16x16x32_bf16 v[118:121], v[138:141], v[162:165], 0
	v_mfma_f32_16x16x32_bf16 v[110:113], v[130:133], v[170:173], 0
	v_mfma_f32_16x16x32_bf16 v[102:105], v[138:141], v[170:173], 0
	v_mfma_f32_16x16x32_bf16 v[94:97], v[130:133], v[178:181], 0
	v_mfma_f32_16x16x32_bf16 v[86:89], v[138:141], v[178:181], 0
	v_mfma_f32_16x16x32_bf16 v[78:81], v[130:133], v[186:189], 0
	v_mfma_f32_16x16x32_bf16 v[70:73], v[138:141], v[186:189], 0
	v_mfma_f32_16x16x32_bf16 v[126:129], v[134:137], v[166:169], v[126:129]
	v_mfma_f32_16x16x32_bf16 v[118:121], v[142:145], v[166:169], v[118:121]
	v_mfma_f32_16x16x32_bf16 v[110:113], v[134:137], v[174:177], v[110:113]
	v_mfma_f32_16x16x32_bf16 v[102:105], v[142:145], v[174:177], v[102:105]
	v_mfma_f32_16x16x32_bf16 v[94:97], v[134:137], v[182:185], v[94:97]
	v_mfma_f32_16x16x32_bf16 v[86:89], v[142:145], v[182:185], v[86:89]
	v_mfma_f32_16x16x32_bf16 v[78:81], v[134:137], v[190:193], v[78:81]
	v_mfma_f32_16x16x32_bf16 v[70:73], v[142:145], v[190:193], v[70:73]
	v_mfma_f32_16x16x32_bf16 v[122:125], v[146:149], v[162:165], 0
	v_mfma_f32_16x16x32_bf16 v[114:117], v[154:157], v[162:165], 0
	v_mfma_f32_16x16x32_bf16 v[106:109], v[146:149], v[170:173], 0
	v_mfma_f32_16x16x32_bf16 v[98:101], v[154:157], v[170:173], 0
	v_mfma_f32_16x16x32_bf16 v[90:93], v[146:149], v[178:181], 0
	v_mfma_f32_16x16x32_bf16 v[82:85], v[154:157], v[178:181], 0
	v_mfma_f32_16x16x32_bf16 v[74:77], v[146:149], v[186:189], 0
	v_mfma_f32_16x16x32_bf16 v[66:69], v[154:157], v[186:189], 0
	v_mfma_f32_16x16x32_bf16 v[122:125], v[150:153], v[166:169], v[122:125]
	v_mfma_f32_16x16x32_bf16 v[114:117], v[158:161], v[166:169], v[114:117]
	v_mfma_f32_16x16x32_bf16 v[106:109], v[150:153], v[174:177], v[106:109]
	v_mfma_f32_16x16x32_bf16 v[98:101], v[158:161], v[174:177], v[98:101]
	v_mfma_f32_16x16x32_bf16 v[90:93], v[150:153], v[182:185], v[90:93]
	v_mfma_f32_16x16x32_bf16 v[82:85], v[158:161], v[182:185], v[82:85]
	v_mfma_f32_16x16x32_bf16 v[74:77], v[150:153], v[190:193], v[74:77]
	v_mfma_f32_16x16x32_bf16 v[66:69], v[158:161], v[190:193], v[66:69]
	s_barrier
	s_mov_b32 m0, s72
	ds_read_b128 v[162:165], v219 offset:16384
	ds_read_b128 v[166:169], v219 offset:17408
	ds_read_b128 v[170:173], v219 offset:18432
	ds_read_b128 v[174:177], v219 offset:19456
	ds_read_b128 v[178:181], v219 offset:20480
	ds_read_b128 v[182:185], v219 offset:21504
	ds_read_b128 v[186:189], v219 offset:22528
	ds_read_b128 v[190:193], v219 offset:23552
	global_load_lds_dwordx4 v200, s[30:31]
	s_mov_b32 m0, s73
	s_nop 0
	global_load_lds_dwordx4 v196, s[30:31]
	s_mov_b32 m0, s74
	s_nop 0
	global_load_lds_dwordx4 v200, s[48:49]
	s_mov_b32 m0, s75
	s_nop 0
	global_load_lds_dwordx4 v196, s[48:49]
	s_mov_b32 m0, s37
	s_nop 0
	global_load_lds_dwordx4 v202, s[28:29]
	s_mov_b32 m0, s38
	s_nop 0
	global_load_lds_dwordx4 v198, s[28:29]
	s_waitcnt vmcnt(8)
	s_waitcnt lgkmcnt(0)
	s_barrier
	s_waitcnt lgkmcnt(0)
	v_mfma_f32_16x16x32_bf16 v[62:65], v[130:133], v[162:165], 0
	v_mfma_f32_16x16x32_bf16 v[54:57], v[138:141], v[162:165], 0
	v_mfma_f32_16x16x32_bf16 v[46:49], v[130:133], v[170:173], 0
	v_mfma_f32_16x16x32_bf16 v[38:41], v[138:141], v[170:173], 0
	v_mfma_f32_16x16x32_bf16 v[30:33], v[130:133], v[178:181], 0
	v_mfma_f32_16x16x32_bf16 v[22:25], v[138:141], v[178:181], 0
	v_mfma_f32_16x16x32_bf16 v[14:17], v[130:133], v[186:189], 0
	v_mfma_f32_16x16x32_bf16 v[6:9], v[138:141], v[186:189], 0
	v_mfma_f32_16x16x32_bf16 v[62:65], v[134:137], v[166:169], v[62:65]
	v_mfma_f32_16x16x32_bf16 v[54:57], v[142:145], v[166:169], v[54:57]
	v_mfma_f32_16x16x32_bf16 v[46:49], v[134:137], v[174:177], v[46:49]
	v_mfma_f32_16x16x32_bf16 v[38:41], v[142:145], v[174:177], v[38:41]
	v_mfma_f32_16x16x32_bf16 v[30:33], v[134:137], v[182:185], v[30:33]
	v_mfma_f32_16x16x32_bf16 v[22:25], v[142:145], v[182:185], v[22:25]
	v_mfma_f32_16x16x32_bf16 v[14:17], v[134:137], v[190:193], v[14:17]
	v_mfma_f32_16x16x32_bf16 v[6:9], v[142:145], v[190:193], v[6:9]
	v_mfma_f32_16x16x32_bf16 v[58:61], v[146:149], v[162:165], 0
	v_mfma_f32_16x16x32_bf16 v[50:53], v[154:157], v[162:165], 0
	v_mfma_f32_16x16x32_bf16 v[42:45], v[146:149], v[170:173], 0
	v_mfma_f32_16x16x32_bf16 v[34:37], v[154:157], v[170:173], 0
	v_mfma_f32_16x16x32_bf16 v[26:29], v[146:149], v[178:181], 0
	v_mfma_f32_16x16x32_bf16 v[18:21], v[154:157], v[178:181], 0
	v_mfma_f32_16x16x32_bf16 v[10:13], v[146:149], v[186:189], 0
	v_mfma_f32_16x16x32_bf16 v[2:5], v[154:157], v[186:189], 0
	v_mfma_f32_16x16x32_bf16 v[58:61], v[150:153], v[166:169], v[58:61]
	v_mfma_f32_16x16x32_bf16 v[50:53], v[158:161], v[166:169], v[50:53]
	v_mfma_f32_16x16x32_bf16 v[42:45], v[150:153], v[174:177], v[42:45]
	v_mfma_f32_16x16x32_bf16 v[34:37], v[158:161], v[174:177], v[34:37]
	v_mfma_f32_16x16x32_bf16 v[26:29], v[150:153], v[182:185], v[26:29]
	v_mfma_f32_16x16x32_bf16 v[18:21], v[158:161], v[182:185], v[18:21]
	v_mfma_f32_16x16x32_bf16 v[10:13], v[150:153], v[190:193], v[10:13]
	v_mfma_f32_16x16x32_bf16 v[2:5], v[158:161], v[190:193], v[2:5]
	s_barrier
	s_branch .Lpeel1_join
; #define PG8_STAGE(bufoff, gbase, voff) do { _Pragma("unroll") for (int _i = 0; _i < 2; ++_i) \
;         __builtin_amdgcn_global_load_lds((const unsigned*)((const char*)(gbase) + (voff)[_i]), (LAS unsigned*)(lds + (bufoff) + ldsw + _i * 8192), 16, 0, 0); } while (0)
; #define PG8_LDA(dst, b, h) do { _Pragma("unroll") for (int m = 0; m < 4; ++m) _Pragma("unroll") for (int k = 0; k < 2; ++k) dst[m][k] = *(const LAS bf16x8*)(lds + PG8_SA(b, h) + aoff + m * 2048 + k * 1024); } while (0)
; #define PG8_LDB(dst, b, h) do { _Pragma("unroll") for (int n = 0; n < 2; ++n) _Pragma("unroll") for (int k = 0; k < 2; ++k) dst[n][k] = *(const LAS bf16x8*)(lds + PG8_SB(b, h) + boff + n * 2048 + k * 1024); } while (0)
; #define PG8_MMA(ai, bj, At, Bt) do { __builtin_amdgcn_s_setprio(1); _Pragma("unroll") for (int m = 0; m < 4; ++m) _Pragma("unroll") for (int n = 0; n < 2; ++n) _Pragma("unroll") for (int k = 0; k < 2; ++k) \
;         acc[ai][bj][m][n] = __builtin_amdgcn_mfma_f32_16x16x32_bf16(Bt[n][k], At[m][k], acc[ai][bj][m][n], 0, 0, 0); __builtin_amdgcn_s_setprio(0); } while (0)
; template <class Epi, class Sched>
; __device__ __forceinline__ void gemm_phase(LAS unsigned char* lds, const int lda, const int ldb, const int K, const Sched& S, const Epi& E) {
;     ...
;             PG8_LDB(B0, 0, 0); PG8_LDB(B1, 0, 1); PG8_SCHED; PG8_LDA(At, 0, 0); PG8_STAGE(PG8_SA(1, 1), a1 + hstepA, voffA);
;             PG8_WAIT_V(8); PG8_WAIT_L(0); PG8_BAR; PG8_MMA(0, 0, At, B0); PG8_MMA(0, 1, At, B1); PG8_BAR; PG8_SCHED;
;             PG8_LDA(At, 0, 1); PG8_STAGE(PG8_SB(0, 0), b2, voffB); PG8_STAGE(PG8_SB(0, 1), b2 + hstepB, voffB); PG8_STAGE(PG8_SA(0, 0), a2, voffA);
;             PG8_WAIT_V(8); PG8_WAIT_L(0); PG8_BAR; PG8_MMA(1, 0, At, B0); PG8_MMA(1, 1, At, B1); PG8_BAR; PG8_SCHED;
;             PG8_LDB(B0, 1, 0); PG8_LDB(B1, 1, 1); PG8_SCHED; PG8_LDA(At, 1, 0); PG8_STAGE(PG8_SA(0, 1), a2 + hstepA, voffA);
;             PG8_WAIT_V(8); PG8_WAIT_L(0); PG8_BAR; PG8_MMA(0, 0, At, B0); PG8_MMA(0, 1, At, B1); PG8_BAR; PG8_SCHED;
;             PG8_LDA(At, 1, 1); PG8_STAGE(PG8_SB(1, 0), b3, voffB); PG8_STAGE(PG8_SB(1, 1), b3 + hstepB, voffB); PG8_STAGE(PG8_SA(1, 0), a3, voffA);
;             PG8_WAIT_V(8); PG8_WAIT_L(0); PG8_BAR;
;             if (last) E.pre(cur, wr, fr, rsv);
;             PG8_MMA(1, 0, At, B0); PG8_MMA(1, 1, At, B1); PG8_BAR; PG8_SCHED;
.LBB0_241:
	s_waitcnt lgkmcnt(0)
	v_mfma_f32_16x16x32_bf16 v[62:65], v[146:149], v[186:189], v[62:65]
	v_mfma_f32_16x16x32_bf16 v[54:57], v[154:157], v[186:189], v[54:57]
	v_mfma_f32_16x16x32_bf16 v[46:49], v[146:149], v[178:181], v[46:49]
	v_mfma_f32_16x16x32_bf16 v[38:41], v[154:157], v[178:181], v[38:41]
	v_mfma_f32_16x16x32_bf16 v[30:33], v[146:149], v[170:173], v[30:33]
	v_mfma_f32_16x16x32_bf16 v[22:25], v[154:157], v[170:173], v[22:25]
	v_mfma_f32_16x16x32_bf16 v[14:17], v[146:149], v[162:165], v[14:17]
	v_mfma_f32_16x16x32_bf16 v[6:9], v[154:157], v[162:165], v[6:9]
	v_mfma_f32_16x16x32_bf16 v[62:65], v[150:153], v[190:193], v[62:65]
	v_mfma_f32_16x16x32_bf16 v[54:57], v[158:161], v[190:193], v[54:57]
	v_mfma_f32_16x16x32_bf16 v[46:49], v[150:153], v[182:185], v[46:49]
	v_mfma_f32_16x16x32_bf16 v[38:41], v[158:161], v[182:185], v[38:41]
	v_mfma_f32_16x16x32_bf16 v[30:33], v[150:153], v[174:177], v[30:33]
	v_mfma_f32_16x16x32_bf16 v[22:25], v[158:161], v[174:177], v[22:25]
	v_mfma_f32_16x16x32_bf16 v[14:17], v[150:153], v[166:169], v[14:17]
	v_mfma_f32_16x16x32_bf16 v[6:9], v[158:161], v[166:169], v[6:9]
	v_mfma_f32_16x16x32_bf16 v[58:61], v[130:133], v[186:189], v[58:61]
	v_mfma_f32_16x16x32_bf16 v[50:53], v[138:141], v[186:189], v[50:53]
	v_mfma_f32_16x16x32_bf16 v[42:45], v[130:133], v[178:181], v[42:45]
	v_mfma_f32_16x16x32_bf16 v[34:37], v[138:141], v[178:181], v[34:37]
	v_mfma_f32_16x16x32_bf16 v[26:29], v[130:133], v[170:173], v[26:29]
	v_mfma_f32_16x16x32_bf16 v[18:21], v[138:141], v[170:173], v[18:21]
	v_mfma_f32_16x16x32_bf16 v[10:13], v[130:133], v[162:165], v[10:13]
	v_mfma_f32_16x16x32_bf16 v[2:5], v[138:141], v[162:165], v[2:5]
	v_mfma_f32_16x16x32_bf16 v[58:61], v[134:137], v[190:193], v[58:61]
	v_mfma_f32_16x16x32_bf16 v[50:53], v[142:145], v[190:193], v[50:53]
	v_mfma_f32_16x16x32_bf16 v[42:45], v[134:137], v[182:185], v[42:45]
	v_mfma_f32_16x16x32_bf16 v[34:37], v[142:145], v[182:185], v[34:37]
	v_mfma_f32_16x16x32_bf16 v[26:29], v[134:137], v[174:177], v[26:29]
	v_mfma_f32_16x16x32_bf16 v[18:21], v[142:145], v[174:177], v[18:21]
	v_mfma_f32_16x16x32_bf16 v[10:13], v[134:137], v[166:169], v[10:13]
	v_mfma_f32_16x16x32_bf16 v[2:5], v[142:145], v[166:169], v[2:5]
	s_barrier
	s_add_i32 s65, s65, 2
	s_add_u32 s22, s22, 0x100
	s_addc_u32 s23, s23, 0
	s_add_u32 s13, s13, 0x100
	s_addc_u32 s15, s15, 0
	s_cmp_gt_u32 s65, 13
	s_cbranch_scc1 .LBB0_244
.LBB0_242:
	s_add_u32 s21, s22, 0xfffc0080
	s_addc_u32 s24, s23, -1
	s_cmp_eq_u32 s65, 12
	s_cselect_b32 s29, s17, s24
	s_cselect_b32 s28, s16, s21
	s_cselect_b32 s31, s19, s15
	s_cselect_b32 s30, s18, s13
	s_add_i32 s72, s50, s3
	ds_read_b128 v[130:133], v217
	ds_read_b128 v[134:137], v217 offset:1024
	ds_read_b128 v[138:141], v217 offset:2048
	ds_read_b128 v[142:145], v217 offset:3072
	ds_read_b128 v[146:149], v218
	ds_read_b128 v[150:153], v218 offset:1024
	ds_read_b128 v[154:157], v218 offset:2048
	ds_read_b128 v[158:161], v218 offset:3072
	s_add_i32 m0, s37, 0xc000
	s_add_i32 s71, s37, 0xe000
	s_add_i32 s73, s72, 0x2000
	s_add_u32 s48, s30, 0x40000
	s_addc_u32 s49, s31, 0
	s_add_i32 s74, s51, s3
	s_add_i32 s75, s74, 0x2000
	s_add_i32 s76, 0, 0x18000
	s_add_i32 s77, 0, 0x1c000
	s_add_u32 s26, s28, 0x40000
	s_addc_u32 s27, s29, 0
	s_add_i32 s68, s76, s3
	s_add_i32 s21, s68, 0x2000
	s_add_u32 s24, s30, 0x40080
	s_addc_u32 s25, s31, 0
	s_add_i32 s70, s77, s3
	s_add_i32 s69, s70, 0x2000
	s_cmp_lg_u32 s65, 12
	ds_read_b128 v[162:165], v219
	ds_read_b128 v[166:169], v219 offset:1024
	ds_read_b128 v[170:173], v219 offset:2048
	ds_read_b128 v[174:177], v219 offset:3072
	ds_read_b128 v[178:181], v219 offset:4096
	ds_read_b128 v[182:185], v219 offset:5120
	ds_read_b128 v[186:189], v219 offset:6144
	ds_read_b128 v[190:193], v219 offset:7168
	global_load_lds_dwordx4 v206, s[22:23]
	s_mov_b32 m0, s71
	s_nop 0
	global_load_lds_dwordx4 v208, s[22:23]
	s_waitcnt vmcnt(8)
	s_waitcnt lgkmcnt(0)
	s_barrier
	s_waitcnt lgkmcnt(0)
	v_mfma_f32_16x16x32_bf16 v[126:129], v[130:133], v[162:165], v[126:129]
	v_mfma_f32_16x16x32_bf16 v[118:121], v[138:141], v[162:165], v[118:121]
	v_mfma_f32_16x16x32_bf16 v[110:113], v[130:133], v[170:173], v[110:113]
	v_mfma_f32_16x16x32_bf16 v[102:105], v[138:141], v[170:173], v[102:105]
	v_mfma_f32_16x16x32_bf16 v[94:97], v[130:133], v[178:181], v[94:97]
	v_mfma_f32_16x16x32_bf16 v[86:89], v[138:141], v[178:181], v[86:89]
	v_mfma_f32_16x16x32_bf16 v[78:81], v[130:133], v[186:189], v[78:81]
	v_mfma_f32_16x16x32_bf16 v[70:73], v[138:141], v[186:189], v[70:73]
	v_mfma_f32_16x16x32_bf16 v[126:129], v[134:137], v[166:169], v[126:129]
	v_mfma_f32_16x16x32_bf16 v[118:121], v[142:145], v[166:169], v[118:121]
	v_mfma_f32_16x16x32_bf16 v[110:113], v[134:137], v[174:177], v[110:113]
	v_mfma_f32_16x16x32_bf16 v[102:105], v[142:145], v[174:177], v[102:105]
	v_mfma_f32_16x16x32_bf16 v[94:97], v[134:137], v[182:185], v[94:97]
	v_mfma_f32_16x16x32_bf16 v[86:89], v[142:145], v[182:185], v[86:89]
	v_mfma_f32_16x16x32_bf16 v[78:81], v[134:137], v[190:193], v[78:81]
	v_mfma_f32_16x16x32_bf16 v[70:73], v[142:145], v[190:193], v[70:73]
	v_mfma_f32_16x16x32_bf16 v[122:125], v[146:149], v[162:165], v[122:125]
	v_mfma_f32_16x16x32_bf16 v[114:117], v[154:157], v[162:165], v[114:117]
	v_mfma_f32_16x16x32_bf16 v[106:109], v[146:149], v[170:173], v[106:109]
	v_mfma_f32_16x16x32_bf16 v[98:101], v[154:157], v[170:173], v[98:101]
	v_mfma_f32_16x16x32_bf16 v[90:93], v[146:149], v[178:181], v[90:93]
	v_mfma_f32_16x16x32_bf16 v[82:85], v[154:157], v[178:181], v[82:85]
	v_mfma_f32_16x16x32_bf16 v[74:77], v[146:149], v[186:189], v[74:77]
	v_mfma_f32_16x16x32_bf16 v[66:69], v[154:157], v[186:189], v[66:69]
	v_mfma_f32_16x16x32_bf16 v[122:125], v[150:153], v[166:169], v[122:125]
	v_mfma_f32_16x16x32_bf16 v[114:117], v[158:161], v[166:169], v[114:117]
	v_mfma_f32_16x16x32_bf16 v[106:109], v[150:153], v[174:177], v[106:109]
	v_mfma_f32_16x16x32_bf16 v[98:101], v[158:161], v[174:177], v[98:101]
	v_mfma_f32_16x16x32_bf16 v[90:93], v[150:153], v[182:185], v[90:93]
	v_mfma_f32_16x16x32_bf16 v[82:85], v[158:161], v[182:185], v[82:85]
	v_mfma_f32_16x16x32_bf16 v[74:77], v[150:153], v[190:193], v[74:77]
	v_mfma_f32_16x16x32_bf16 v[66:69], v[158:161], v[190:193], v[66:69]
	s_barrier
; #define PG8_STAGE(bufoff, gbase, voff) do { _Pragma("unroll") for (int _i = 0; _i < 2; ++_i) \
;         __builtin_amdgcn_global_load_lds((const unsigned*)((const char*)(gbase) + (voff)[_i]), (LAS unsigned*)(lds + (bufoff) + ldsw + _i * 8192), 16, 0, 0); } while (0)
; #define PG8_LDA(dst, b, h) do { _Pragma("unroll") for (int m = 0; m < 4; ++m) _Pragma("unroll") for (int k = 0; k < 2; ++k) dst[m][k] = *(const LAS bf16x8*)(lds + PG8_SA(b, h) + aoff + m * 2048 + k * 1024); } while (0)
; #define PG8_MMA(ai, bj, At, Bt) do { __builtin_amdgcn_s_setprio(1); _Pragma("unroll") for (int m = 0; m < 4; ++m) _Pragma("unroll") for (int n = 0; n < 2; ++n) _Pragma("unroll") for (int k = 0; k < 2; ++k) \
;         acc[ai][bj][m][n] = __builtin_amdgcn_mfma_f32_16x16x32_bf16(Bt[n][k], At[m][k], acc[ai][bj][m][n], 0, 0, 0); __builtin_amdgcn_s_setprio(0); } while (0)
; #define PG8_WAIT_V(n) asm volatile("s_waitcnt vmcnt(" #n ")" ::: "memory")
; #define PG8_WAIT_L(n) asm volatile("s_waitcnt lgkmcnt(" #n ")" ::: "memory")
; #define PG8_BAR __builtin_amdgcn_s_barrier()
; #define PG8_SCHED __builtin_amdgcn_sched_barrier(0)
; template <class Epi, class Sched>
; __device__ __forceinline__ void gemm_phase(LAS unsigned char* lds, const int lda, const int ldb, const int K, const Sched& S, const Epi& E) {
;     ...
;             PG8_LDA(At, 0, 1); PG8_STAGE(PG8_SB(0, 0), b2, voffB); PG8_STAGE(PG8_SB(0, 1), b2 + hstepB, voffB); PG8_STAGE(PG8_SA(0, 0), a2, voffA);
;             PG8_WAIT_V(8); PG8_WAIT_L(0); PG8_BAR; PG8_MMA(1, 0, At, B0); PG8_MMA(1, 1, At, B1); PG8_BAR; PG8_SCHED;
	s_mov_b32 m0, s72
	ds_read_b128 v[162:165], v219 offset:16384
	ds_read_b128 v[166:169], v219 offset:17408
	ds_read_b128 v[170:173], v219 offset:18432
	ds_read_b128 v[174:177], v219 offset:19456
	ds_read_b128 v[178:181], v219 offset:20480
	ds_read_b128 v[182:185], v219 offset:21504
	ds_read_b128 v[186:189], v219 offset:22528
	ds_read_b128 v[190:193], v219 offset:23552
	global_load_lds_dwordx4 v200, s[30:31]
	s_mov_b32 m0, s73
	s_nop 0
	global_load_lds_dwordx4 v196, s[30:31]
	s_mov_b32 m0, s74
	s_nop 0
	global_load_lds_dwordx4 v200, s[48:49]
	s_mov_b32 m0, s75
	s_nop 0
	global_load_lds_dwordx4 v196, s[48:49]
	s_mov_b32 m0, s37
	s_nop 0
	global_load_lds_dwordx4 v202, s[28:29]
	s_mov_b32 m0, s38
	s_nop 0
	global_load_lds_dwordx4 v198, s[28:29]
	s_waitcnt vmcnt(8)
	s_waitcnt lgkmcnt(0)
	s_barrier
	s_waitcnt lgkmcnt(0)
	v_mfma_f32_16x16x32_bf16 v[62:65], v[130:133], v[162:165], v[62:65]
	v_mfma_f32_16x16x32_bf16 v[54:57], v[138:141], v[162:165], v[54:57]
	v_mfma_f32_16x16x32_bf16 v[46:49], v[130:133], v[170:173], v[46:49]
	v_mfma_f32_16x16x32_bf16 v[38:41], v[138:141], v[170:173], v[38:41]
	v_mfma_f32_16x16x32_bf16 v[30:33], v[130:133], v[178:181], v[30:33]
	v_mfma_f32_16x16x32_bf16 v[22:25], v[138:141], v[178:181], v[22:25]
	v_mfma_f32_16x16x32_bf16 v[14:17], v[130:133], v[186:189], v[14:17]
	v_mfma_f32_16x16x32_bf16 v[6:9], v[138:141], v[186:189], v[6:9]
	v_mfma_f32_16x16x32_bf16 v[62:65], v[134:137], v[166:169], v[62:65]
	v_mfma_f32_16x16x32_bf16 v[54:57], v[142:145], v[166:169], v[54:57]
	v_mfma_f32_16x16x32_bf16 v[46:49], v[134:137], v[174:177], v[46:49]
	v_mfma_f32_16x16x32_bf16 v[38:41], v[142:145], v[174:177], v[38:41]
	v_mfma_f32_16x16x32_bf16 v[30:33], v[134:137], v[182:185], v[30:33]
	v_mfma_f32_16x16x32_bf16 v[22:25], v[142:145], v[182:185], v[22:25]
	v_mfma_f32_16x16x32_bf16 v[14:17], v[134:137], v[190:193], v[14:17]
	v_mfma_f32_16x16x32_bf16 v[6:9], v[142:145], v[190:193], v[6:9]
	v_mfma_f32_16x16x32_bf16 v[58:61], v[146:149], v[162:165], v[58:61]
	v_mfma_f32_16x16x32_bf16 v[50:53], v[154:157], v[162:165], v[50:53]
	v_mfma_f32_16x16x32_bf16 v[42:45], v[146:149], v[170:173], v[42:45]
	v_mfma_f32_16x16x32_bf16 v[34:37], v[154:157], v[170:173], v[34:37]
	v_mfma_f32_16x16x32_bf16 v[26:29], v[146:149], v[178:181], v[26:29]
	v_mfma_f32_16x16x32_bf16 v[18:21], v[154:157], v[178:181], v[18:21]
	v_mfma_f32_16x16x32_bf16 v[10:13], v[146:149], v[186:189], v[10:13]
	v_mfma_f32_16x16x32_bf16 v[2:5], v[154:157], v[186:189], v[2:5]
	v_mfma_f32_16x16x32_bf16 v[58:61], v[150:153], v[166:169], v[58:61]
	v_mfma_f32_16x16x32_bf16 v[50:53], v[158:161], v[166:169], v[50:53]
	v_mfma_f32_16x16x32_bf16 v[42:45], v[150:153], v[174:177], v[42:45]
	v_mfma_f32_16x16x32_bf16 v[34:37], v[158:161], v[174:177], v[34:37]
	v_mfma_f32_16x16x32_bf16 v[26:29], v[150:153], v[182:185], v[26:29]
	v_mfma_f32_16x16x32_bf16 v[18:21], v[158:161], v[182:185], v[18:21]
	v_mfma_f32_16x16x32_bf16 v[10:13], v[150:153], v[190:193], v[10:13]
	v_mfma_f32_16x16x32_bf16 v[2:5], v[158:161], v[190:193], v[2:5]
	s_barrier
; #define PG8_STAGE(bufoff, gbase, voff) do { _Pragma("unroll") for (int _i = 0; _i < 2; ++_i) \
;         __builtin_amdgcn_global_load_lds((const unsigned*)((const char*)(gbase) + (voff)[_i]), (LAS unsigned*)(lds + (bufoff) + ldsw + _i * 8192), 16, 0, 0); } while (0)
; #define PG8_LDA(dst, b, h) do { _Pragma("unroll") for (int m = 0; m < 4; ++m) _Pragma("unroll") for (int k = 0; k < 2; ++k) dst[m][k] = *(const LAS bf16x8*)(lds + PG8_SA(b, h) + aoff + m * 2048 + k * 1024); } while (0)
; #define PG8_LDB(dst, b, h) do { _Pragma("unroll") for (int n = 0; n < 2; ++n) _Pragma("unroll") for (int k = 0; k < 2; ++k) dst[n][k] = *(const LAS bf16x8*)(lds + PG8_SB(b, h) + boff + n * 2048 + k * 1024); } while (0)
; #define PG8_MMA(ai, bj, At, Bt) do { __builtin_amdgcn_s_setprio(1); _Pragma("unroll") for (int m = 0; m < 4; ++m) _Pragma("unroll") for (int n = 0; n < 2; ++n) _Pragma("unroll") for (int k = 0; k < 2; ++k) \
;         acc[ai][bj][m][n] = __builtin_amdgcn_mfma_f32_16x16x32_bf16(Bt[n][k], At[m][k], acc[ai][bj][m][n], 0, 0, 0); __builtin_amdgcn_s_setprio(0); } while (0)
; #define PG8_WAIT_V(n) asm volatile("s_waitcnt vmcnt(" #n ")" ::: "memory")
; #define PG8_WAIT_L(n) asm volatile("s_waitcnt lgkmcnt(" #n ")" ::: "memory")
; #define PG8_BAR __builtin_amdgcn_s_barrier()
; #define PG8_SCHED __builtin_amdgcn_sched_barrier(0)
; template <class Epi, class Sched>
; __device__ __forceinline__ void gemm_phase(LAS unsigned char* lds, const int lda, const int ldb, const int K, const Sched& S, const Epi& E) {
;     ...
;             PG8_LDB(B0, 1, 0); PG8_LDB(B1, 1, 1); PG8_SCHED; PG8_LDA(At, 1, 0); PG8_STAGE(PG8_SA(0, 1), a2 + hstepA, voffA);
;             PG8_WAIT_V(8); PG8_WAIT_L(0); PG8_BAR; PG8_MMA(0, 0, At, B0); PG8_MMA(0, 1, At, B1); PG8_BAR; PG8_SCHED;
;             PG8_LDA(At, 1, 1); PG8_STAGE(PG8_SB(1, 0), b3, voffB); PG8_STAGE(PG8_SB(1, 1), b3 + hstepB, voffB); PG8_STAGE(PG8_SA(1, 0), a3, voffA);
;             PG8_WAIT_V(8); PG8_WAIT_L(0); PG8_BAR;
;             if (last) E.pre(cur, wr, fr, rsv);
;     __device__ __forceinline__ void pre(const pg8::Unit& u, int wr, int fr, float (&rsv)[8]) const {
;         const float* p = ss + u.pm * 256 + wr * 64 + fr;
; #pragma unroll
;         for (int ai = 0; ai < 2; ++ai)
; #pragma unroll
;             for (int m = 0; m < 4; ++m) rsv[ai * 4 + m] = p[ai * 128 + m * 16];
;     }
.Lpeel1_join:
	v_add_u32_e32 v130, s76, v195
	v_add_u32_e32 v142, s77, v195
	ds_read_b128 v[146:149], v130
	ds_read_b128 v[150:153], v130 offset:1024
	ds_read_b128 v[154:157], v130 offset:2048
	ds_read_b128 v[158:161], v130 offset:3072
	ds_read_b128 v[130:133], v142
	ds_read_b128 v[134:137], v142 offset:1024
	ds_read_b128 v[138:141], v142 offset:2048
	ds_read_b128 v[142:145], v142 offset:3072
	s_mov_b32 m0, s39
	ds_read_b128 v[162:165], v219 offset:32768
	ds_read_b128 v[166:169], v219 offset:33792
	ds_read_b128 v[170:173], v219 offset:34816
	ds_read_b128 v[174:177], v219 offset:35840
	ds_read_b128 v[178:181], v219 offset:36864
	ds_read_b128 v[182:185], v219 offset:37888
	ds_read_b128 v[186:189], v219 offset:38912
	ds_read_b128 v[190:193], v219 offset:39936
	global_load_lds_dwordx4 v202, s[26:27]
	s_mov_b32 m0, s40
	s_nop 0
	global_load_lds_dwordx4 v198, s[26:27]
	s_waitcnt vmcnt(8)
	s_waitcnt lgkmcnt(0)
	s_barrier
	s_waitcnt lgkmcnt(0)
	v_mfma_f32_16x16x32_bf16 v[126:129], v[146:149], v[162:165], v[126:129]
	v_mfma_f32_16x16x32_bf16 v[118:121], v[154:157], v[162:165], v[118:121]
	v_mfma_f32_16x16x32_bf16 v[110:113], v[146:149], v[170:173], v[110:113]
	v_mfma_f32_16x16x32_bf16 v[102:105], v[154:157], v[170:173], v[102:105]
	v_mfma_f32_16x16x32_bf16 v[94:97], v[146:149], v[178:181], v[94:97]
	v_mfma_f32_16x16x32_bf16 v[86:89], v[154:157], v[178:181], v[86:89]
	v_mfma_f32_16x16x32_bf16 v[78:81], v[146:149], v[186:189], v[78:81]
	v_mfma_f32_16x16x32_bf16 v[70:73], v[154:157], v[186:189], v[70:73]
	v_mfma_f32_16x16x32_bf16 v[126:129], v[150:153], v[166:169], v[126:129]
	v_mfma_f32_16x16x32_bf16 v[118:121], v[158:161], v[166:169], v[118:121]
	v_mfma_f32_16x16x32_bf16 v[110:113], v[150:153], v[174:177], v[110:113]
	v_mfma_f32_16x16x32_bf16 v[102:105], v[158:161], v[174:177], v[102:105]
	v_mfma_f32_16x16x32_bf16 v[94:97], v[150:153], v[182:185], v[94:97]
	v_mfma_f32_16x16x32_bf16 v[86:89], v[158:161], v[182:185], v[86:89]
	v_mfma_f32_16x16x32_bf16 v[78:81], v[150:153], v[190:193], v[78:81]
	v_mfma_f32_16x16x32_bf16 v[70:73], v[158:161], v[190:193], v[70:73]
	v_mfma_f32_16x16x32_bf16 v[122:125], v[130:133], v[162:165], v[122:125]
	v_mfma_f32_16x16x32_bf16 v[114:117], v[138:141], v[162:165], v[114:117]
	v_mfma_f32_16x16x32_bf16 v[106:109], v[130:133], v[170:173], v[106:109]
	v_mfma_f32_16x16x32_bf16 v[98:101], v[138:141], v[170:173], v[98:101]
	v_mfma_f32_16x16x32_bf16 v[90:93], v[130:133], v[178:181], v[90:93]
	v_mfma_f32_16x16x32_bf16 v[82:85], v[138:141], v[178:181], v[82:85]
	v_mfma_f32_16x16x32_bf16 v[74:77], v[130:133], v[186:189], v[74:77]
	v_mfma_f32_16x16x32_bf16 v[66:69], v[138:141], v[186:189], v[66:69]
	v_mfma_f32_16x16x32_bf16 v[122:125], v[134:137], v[166:169], v[122:125]
	v_mfma_f32_16x16x32_bf16 v[114:117], v[142:145], v[166:169], v[114:117]
	v_mfma_f32_16x16x32_bf16 v[106:109], v[134:137], v[174:177], v[106:109]
	v_mfma_f32_16x16x32_bf16 v[98:101], v[142:145], v[174:177], v[98:101]
	v_mfma_f32_16x16x32_bf16 v[90:93], v[134:137], v[182:185], v[90:93]
	v_mfma_f32_16x16x32_bf16 v[82:85], v[142:145], v[182:185], v[82:85]
	v_mfma_f32_16x16x32_bf16 v[74:77], v[134:137], v[190:193], v[74:77]
	v_mfma_f32_16x16x32_bf16 v[66:69], v[142:145], v[190:193], v[66:69]
	s_barrier
	s_mov_b32 m0, s68
	ds_read_b128 v[186:189], v219 offset:49152
	ds_read_b128 v[190:193], v219 offset:50176
	ds_read_b128 v[178:181], v219 offset:51200
	ds_read_b128 v[182:185], v219 offset:52224
	ds_read_b128 v[170:173], v219 offset:53248
	ds_read_b128 v[174:177], v219 offset:54272
	ds_read_b128 v[162:165], v219 offset:55296
	ds_read_b128 v[166:169], v219 offset:56320
	global_load_lds_dwordx4 v230, s[30:31]
	s_mov_b32 m0, s21
	s_nop 0
	global_load_lds_dwordx4 v231, s[30:31]
	s_mov_b32 m0, s70
	s_nop 0
	global_load_lds_dwordx4 v200, s[24:25]
	s_mov_b32 m0, s69
	s_nop 0
	global_load_lds_dwordx4 v196, s[24:25]
	s_mov_b32 m0, s42
	s_nop 0
	global_load_lds_dwordx4 v232, s[28:29]
	s_mov_b32 m0, s43
	s_nop 0
	global_load_lds_dwordx4 v233, s[28:29]
	s_waitcnt vmcnt(8)
	s_waitcnt lgkmcnt(0)
	s_barrier
	s_cbranch_scc1 .LBB0_241
	global_load_dword v228, v[214:215], off
	global_load_dword v227, v[214:215], off offset:64
	global_load_dword v226, v[214:215], off offset:128
	global_load_dword v225, v[214:215], off offset:192
	global_load_dword v224, v[214:215], off offset:512
	global_load_dword v223, v[214:215], off offset:576
	global_load_dword v222, v[214:215], off offset:640
	global_load_dword v221, v[214:215], off offset:704
	s_branch .LBB0_241

; #define PG8_WAIT_V(n) asm volatile("s_waitcnt vmcnt(" #n ")" ::: "memory")
; #define PG8_BAR __builtin_amdgcn_s_barrier()
; template <class Epi, class Sched>
; __device__ __forceinline__ void gemm_phase(LAS unsigned char* lds, const int lda, const int ldb, const int K, const Sched& S, const Epi& E) {
;     ...
;     PG8_WAIT_V(0);
;     PG8_BAR;
.LBB0_249:
	s_waitcnt vmcnt(0) lgkmcnt(0)
	s_barrier
	s_setprio 0

; #define PG8_STAGE(bufoff, gbase, voff) do { _Pragma("unroll") for (int _i = 0; _i < 2; ++_i) \
;         __builtin_amdgcn_global_load_lds((const unsigned*)((const char*)(gbase) + (voff)[_i]), (LAS unsigned*)(lds + (bufoff) + ldsw + _i * 8192), 16, 0, 0); } while (0)
; #define PG8_BAR __builtin_amdgcn_s_barrier()
; template <class Epi, class Sched>
; __device__ __forceinline__ void gemm_phase(LAS unsigned char* lds, const int lda, const int ldb, const int K, const Sched& S, const Epi& E) {
;     const int tid = threadIdx.x, wid = __builtin_amdgcn_readfirstlane(tid >> 6), lane = tid & 63, wr = wid >> 2, wc = wid & 3, fr = lane & 15, fq = lane >> 4;
;     const int nt = K / BK;
;     unsigned voffA[2], voffB[2];
; #pragma unroll
;     for (int i = 0; i < 2; ++i) { int R, C; stage_rc(tid * 16 + i * 8192, R, C); const int Rb = (R & ~31) + perm32(R & 31);
;         voffA[i] = (unsigned)(R * lda + C) * 2u; voffB[i] = (unsigned)(Rb * ldb + C) * 2u; }
;     const size_t kstep = (size_t)(BK * 2);
;     const size_t hstepA = (size_t)HALF * lda * 2, hstepB = (size_t)HALF * ldb * 2;
;     const unsigned ldsw = (unsigned)wid * 1024u;
;     const int aoff = lds_byte(wr * 64 + fr, fq * 8), boff = lds_byte(wc * 32 + fr, fq * 8);
;     ...
;     Unit cur, nxt; int ui = 0;
;     if (!S.next(0, cur)) return;
;     f32x4 acc[2][2][4][2];
; #pragma unroll
;     for (int a = 0; a < 2; ++a)
; #pragma unroll
;         for (int b = 0; b < 2; ++b)
; #pragma unroll
;             for (int m = 0; m < 4; ++m)
; #pragma unroll
;                 for (int n = 0; n < 2; ++n) acc[a][b][m][n] = (f32x4){0.f, 0.f, 0.f, 0.f};
;     bf16x8 At[4][2], B0[2][2], B1[2][2];
;     float rsv[8];
; #pragma unroll
;     for (int i = 0; i < 8; ++i) rsv[i] = 0.f;
;     const char* cA = cur.A; const char* cB = cur.B;
;     PG8_STAGE(PG8_SB(0, 0), cB, voffB); PG8_STAGE(PG8_SB(0, 1), cB + hstepB, voffB); PG8_STAGE(PG8_SA(0, 0), cA, voffA); PG8_STAGE(PG8_SA(0, 1), cA + hstepA, voffA);
;     if (wr == 1) PG8_BAR;
.LBB0_318:
	v_lshrrev_b32_e32 v4, 1, v194
	v_lshrrev_b32_e32 v5, 5, v194
	v_and_b32_e32 v4, 24, v4
	v_and_b32_e32 v5, 4, v5
	v_bfe_u32 v6, v194, 2, 2
	v_lshlrev_b32_e32 v1, 4, v194
	v_and_b32_e32 v2, 32, v194
	v_bfe_u32 v3, v194, 2, 4
	v_or3_b32 v4, v5, v6, v4
	v_lshrrev_b32_e32 v5, 3, v194
	s_movk_i32 s1, 0x70
	v_bitop3_b32 v10, v1, v2, 48 bitop3:0x6c
	v_and_or_b32 v6, v5, s1, v3
	s_movk_i32 s1, 0x60
	v_add_u32_e32 v1, 0x2000, v1
	v_and_or_b32 v5, v5, s1, v4
	v_lshrrev_b32_e32 v1, 7, v1
	s_movk_i32 s1, 0xf0
	v_and_b32_e32 v11, 64, v194
	v_and_or_b32 v3, v1, s1, v3
	s_movk_i32 s1, 0xe0
	v_or_b32_e32 v2, v10, v11
	v_and_or_b32 v1, v1, s1, v4
	s_lshr_b32 s1, s4, 6
	v_lshrrev_b32_e32 v2, 1, v2
	v_mul_u32_u24_e32 v5, 0xb00, v5
	s_lshl_b32 s25, s1, 10
	v_or_b32_e32 v5, v5, v2
	s_add_i32 s26, s25, 0
	v_lshlrev_b32_e32 v156, 1, v5
	v_mul_u32_u24_e32 v1, 0xb00, v1
	s_add_i32 m0, s26, 0x10000
	s_lshr_b32 s0, s4, 8
	v_or_b32_e32 v1, v1, v2
	global_load_lds_dwordx4 v156, s[20:21]
	s_add_i32 m0, s26, 0x12000
	v_lshlrev_b32_e32 v160, 1, v1
	s_add_u32 s8, s20, 0xb0000
	v_mul_u32_u24_e32 v12, 0xb00, v6
	global_load_lds_dwordx4 v160, s[20:21]
	s_addc_u32 s9, s21, 0
	s_add_i32 m0, s26, 0x14000
	v_or_b32_e32 v6, v2, v12
	v_mul_u32_u24_e32 v13, 0xb00, v3
	global_load_lds_dwordx4 v156, s[8:9]
	s_add_i32 m0, s26, 0x16000
	s_add_i32 s27, s26, 0x2000
	v_lshlrev_b32_e32 v154, 1, v6
	v_or_b32_e32 v3, v13, v2
	global_load_lds_dwordx4 v160, s[8:9]
	s_mov_b32 m0, s26
	s_add_u32 s8, s18, 0xb0000
	v_lshlrev_b32_e32 v158, 1, v3
	global_load_lds_dwordx4 v154, s[18:19]
	s_mov_b32 m0, s27
	s_addc_u32 s9, s19, 0
	s_add_i32 s28, s26, 0x4000
	global_load_lds_dwordx4 v158, s[18:19]
	s_mov_b32 m0, s28
	s_add_i32 s29, s26, 0x6000
	global_load_lds_dwordx4 v154, s[8:9]
	s_mov_b32 m0, s29
	v_mov_b32_e32 v157, 0
	global_load_lds_dwordx4 v158, s[8:9]
	v_mov_b32_e32 v161, v157
	v_mov_b32_e32 v155, v157
	v_mov_b32_e32 v159, v157
	s_cmp_eq_u32 s0, 1
	s_mov_b32 s30, 0
	v_lshl_add_u64 v[8:9], s[20:21], 0, v[156:157]
	v_lshl_add_u64 v[6:7], s[20:21], 0, v[160:161]
	v_lshl_add_u64 v[2:3], s[18:19], 0, v[154:155]
	s_cselect_b64 s[8:9], -1, 0
	s_cmp_lg_u32 s0, 1
	v_lshl_add_u64 v[4:5], s[18:19], 0, v[158:159]
	s_cbranch_scc1 .LBB0_320
	s_setprio 1
	s_barrier

; #define PG8_STAGE(bufoff, gbase, voff) do { _Pragma("unroll") for (int _i = 0; _i < 2; ++_i) \
;         __builtin_amdgcn_global_load_lds((const unsigned*)((const char*)(gbase) + (voff)[_i]), (LAS unsigned*)(lds + (bufoff) + ldsw + _i * 8192), 16, 0, 0); } while (0)
; #define PG8_LDA(dst, b, h) do { _Pragma("unroll") for (int m = 0; m < 4; ++m) _Pragma("unroll") for (int k = 0; k < 2; ++k) dst[m][k] = *(const LAS bf16x8*)(lds + PG8_SA(b, h) + aoff + m * 2048 + k * 1024); } while (0)
; #define PG8_LDB(dst, b, h) do { _Pragma("unroll") for (int n = 0; n < 2; ++n) _Pragma("unroll") for (int k = 0; k < 2; ++k) dst[n][k] = *(const LAS bf16x8*)(lds + PG8_SB(b, h) + boff + n * 2048 + k * 1024); } while (0)
; #define PG8_MMA(ai, bj, At, Bt) do { __builtin_amdgcn_s_setprio(1); _Pragma("unroll") for (int m = 0; m < 4; ++m) _Pragma("unroll") for (int n = 0; n < 2; ++n) _Pragma("unroll") for (int k = 0; k < 2; ++k) \
;         acc[ai][bj][m][n] = __builtin_amdgcn_mfma_f32_16x16x32_bf16(Bt[n][k], At[m][k], acc[ai][bj][m][n], 0, 0, 0); __builtin_amdgcn_s_setprio(0); } while (0)
; #define PG8_WAIT_V(n) asm volatile("s_waitcnt vmcnt(" #n ")" ::: "memory")
; #define PG8_WAIT_L(n) asm volatile("s_waitcnt lgkmcnt(" #n ")" ::: "memory")
; #define PG8_BAR __builtin_amdgcn_s_barrier()
; #define PG8_SCHED __builtin_amdgcn_sched_barrier(0)
; template <class Epi, class Sched>
; __device__ __forceinline__ void gemm_phase(LAS unsigned char* lds, const int lda, const int ldb, const int K, const Sched& S, const Epi& E) {
;     ...
;         for (int t = 0; t < nt; t += 2) {
;             const bool last = (t == nt - 2);
;             const char* a1 = cA + (size_t)(t + 1) * kstep;
;             const char* a2 = last ? nA : cA + (size_t)(t + 2) * kstep; const char* b2 = last ? nB : cB + (size_t)(t + 2) * kstep;
;             const char* a3 = a2 + kstep; const char* b3 = b2 + kstep;
;             PG8_LDB(B0, 0, 0); PG8_LDB(B1, 0, 1); PG8_SCHED; PG8_LDA(At, 0, 0); PG8_STAGE(PG8_SA(1, 1), a1 + hstepA, voffA);
;             PG8_WAIT_V(8); PG8_WAIT_L(0); PG8_BAR; PG8_MMA(0, 0, At, B0); PG8_MMA(0, 1, At, B1); PG8_BAR; PG8_SCHED;
;             PG8_LDA(At, 0, 1); PG8_STAGE(PG8_SB(0, 0), b2, voffB); PG8_STAGE(PG8_SB(0, 1), b2 + hstepB, voffB); PG8_STAGE(PG8_SA(0, 0), a2, voffA);
;             PG8_WAIT_V(8); PG8_WAIT_L(0); PG8_BAR; PG8_MMA(1, 0, At, B0); PG8_MMA(1, 1, At, B1); PG8_BAR; PG8_SCHED;
.LBB0_325:
	s_add_u32 s18, s18, 0xb0080
	s_addc_u32 s19, s19, 0
	s_add_u32 s48, s20, 0x100
	s_addc_u32 s49, s21, 0
	s_mov_b32 s50, -2
	s_waitcnt lgkmcnt(0)
	v_add_u32_e32 v192, 0x80, v156
	v_add_u32_e32 v193, 0x80, v160
	v_add_u32_e32 v220, 0x80, v154
	v_add_u32_e32 v221, 0x80, v158
	ds_read_b128 v[130:133], v188
	ds_read_b128 v[134:137], v188 offset:1024
	ds_read_b128 v[138:141], v188 offset:2048
	ds_read_b128 v[142:145], v188 offset:3072
	ds_read_b128 v[146:149], v189
	ds_read_b128 v[150:153], v189 offset:1024
	ds_read_b128 v[170:173], v189 offset:2048
	ds_read_b128 v[174:177], v189 offset:3072
	s_add_u32 s20, s18, 0xfff50080
	s_addc_u32 s21, s19, -1
	s_cmp_eq_u32 s50, 40
	s_cselect_b32 s23, s15, s21
	s_cselect_b32 s22, s14, s20
	s_cselect_b32 s21, s17, s49
	s_cselect_b32 s20, s16, s48
	s_add_i32 m0, s26, 0xc000
	ds_read_b128 v[178:181], v190
	ds_read_b128 v[182:185], v190 offset:1024
	ds_read_b128 v[196:199], v190 offset:2048
	ds_read_b128 v[200:203], v190 offset:3072
	ds_read_b128 v[204:207], v190 offset:4096
	ds_read_b128 v[208:211], v190 offset:5120
	ds_read_b128 v[212:215], v190 offset:6144
	ds_read_b128 v[216:219], v190 offset:7168
	global_load_lds_dwordx4 v162, s[18:19]
	s_add_i32 m0, s26, 0xe000
	s_nop 0
	global_load_lds_dwordx4 v164, s[18:19]
	s_waitcnt vmcnt(8)
	s_waitcnt lgkmcnt(0)
	s_barrier
	s_waitcnt lgkmcnt(0)
	v_mfma_f32_16x16x32_bf16 v[126:129], v[130:133], v[178:181], 0
	v_mfma_f32_16x16x32_bf16 v[122:125], v[138:141], v[178:181], 0
	v_mfma_f32_16x16x32_bf16 v[110:113], v[130:133], v[196:199], 0
	v_mfma_f32_16x16x32_bf16 v[106:109], v[138:141], v[196:199], 0
	v_mfma_f32_16x16x32_bf16 v[94:97], v[130:133], v[204:207], 0
	v_mfma_f32_16x16x32_bf16 v[90:93], v[138:141], v[204:207], 0
	v_mfma_f32_16x16x32_bf16 v[78:81], v[130:133], v[212:215], 0
	v_mfma_f32_16x16x32_bf16 v[74:77], v[138:141], v[212:215], 0
	v_mfma_f32_16x16x32_bf16 v[126:129], v[134:137], v[182:185], v[126:129]
	v_mfma_f32_16x16x32_bf16 v[122:125], v[142:145], v[182:185], v[122:125]
	v_mfma_f32_16x16x32_bf16 v[110:113], v[134:137], v[200:203], v[110:113]
	v_mfma_f32_16x16x32_bf16 v[106:109], v[142:145], v[200:203], v[106:109]
	v_mfma_f32_16x16x32_bf16 v[94:97], v[134:137], v[208:211], v[94:97]
	v_mfma_f32_16x16x32_bf16 v[90:93], v[142:145], v[208:211], v[90:93]
	v_mfma_f32_16x16x32_bf16 v[78:81], v[134:137], v[216:219], v[78:81]
	v_mfma_f32_16x16x32_bf16 v[74:77], v[142:145], v[216:219], v[74:77]
	v_mfma_f32_16x16x32_bf16 v[118:121], v[146:149], v[178:181], 0
	v_mfma_f32_16x16x32_bf16 v[114:117], v[170:173], v[178:181], 0
	v_mfma_f32_16x16x32_bf16 v[102:105], v[146:149], v[196:199], 0
	v_mfma_f32_16x16x32_bf16 v[98:101], v[170:173], v[196:199], 0
	v_mfma_f32_16x16x32_bf16 v[86:89], v[146:149], v[204:207], 0
	v_mfma_f32_16x16x32_bf16 v[82:85], v[170:173], v[204:207], 0
	v_mfma_f32_16x16x32_bf16 v[70:73], v[146:149], v[212:215], 0
	v_mfma_f32_16x16x32_bf16 v[66:69], v[170:173], v[212:215], 0
	v_mfma_f32_16x16x32_bf16 v[118:121], v[150:153], v[182:185], v[118:121]
	v_mfma_f32_16x16x32_bf16 v[114:117], v[174:177], v[182:185], v[114:117]
	v_mfma_f32_16x16x32_bf16 v[102:105], v[150:153], v[200:203], v[102:105]
	v_mfma_f32_16x16x32_bf16 v[98:101], v[174:177], v[200:203], v[98:101]
	v_mfma_f32_16x16x32_bf16 v[86:89], v[150:153], v[208:211], v[86:89]
	v_mfma_f32_16x16x32_bf16 v[82:85], v[174:177], v[208:211], v[82:85]
	v_mfma_f32_16x16x32_bf16 v[70:73], v[150:153], v[216:219], v[70:73]
	v_mfma_f32_16x16x32_bf16 v[66:69], v[174:177], v[216:219], v[66:69]
	s_barrier
	s_add_i32 s51, s40, s25
	s_mov_b32 m0, s51
	ds_read_b128 v[178:181], v190 offset:16384
	ds_read_b128 v[182:185], v190 offset:17408
	ds_read_b128 v[196:199], v190 offset:18432
	ds_read_b128 v[200:203], v190 offset:19456
	ds_read_b128 v[204:207], v190 offset:20480
	ds_read_b128 v[208:211], v190 offset:21504
	ds_read_b128 v[212:215], v190 offset:22528
	ds_read_b128 v[216:219], v190 offset:23552
	global_load_lds_dwordx4 v156, s[20:21]
	s_add_i32 m0, s51, 0x2000
	s_add_u32 s62, s20, 0xb0000
	s_mov_b64 s[98:99], s[20:21]
	s_addc_u32 s63, s21, 0
	s_add_i32 s51, s41, s25
	global_load_lds_dwordx4 v160, s[20:21]
	s_mov_b32 m0, s51
	s_mov_b64 s[100:101], s[22:23]
	global_load_lds_dwordx4 v156, s[62:63]
	s_add_i32 m0, s51, 0x2000
	s_nop 0
	global_load_lds_dwordx4 v160, s[62:63]
	s_mov_b32 m0, s26
	s_nop 0
	global_load_lds_dwordx4 v154, s[22:23]
	s_mov_b32 m0, s27
	s_nop 0
	global_load_lds_dwordx4 v158, s[22:23]
	s_waitcnt vmcnt(8)
	s_waitcnt lgkmcnt(0)
	s_barrier
	s_waitcnt lgkmcnt(0)
	v_mfma_f32_16x16x32_bf16 v[62:65], v[130:133], v[178:181], 0
	v_mfma_f32_16x16x32_bf16 v[58:61], v[138:141], v[178:181], 0
	v_mfma_f32_16x16x32_bf16 v[46:49], v[130:133], v[196:199], 0
	v_mfma_f32_16x16x32_bf16 v[42:45], v[138:141], v[196:199], 0
	v_mfma_f32_16x16x32_bf16 v[30:33], v[130:133], v[204:207], 0
	v_mfma_f32_16x16x32_bf16 v[26:29], v[138:141], v[204:207], 0
	v_mfma_f32_16x16x32_bf16 v[14:17], v[130:133], v[212:215], 0
	v_mfma_f32_16x16x32_bf16 v[10:13], v[138:141], v[212:215], 0
	v_mfma_f32_16x16x32_bf16 v[62:65], v[134:137], v[182:185], v[62:65]
	v_mfma_f32_16x16x32_bf16 v[58:61], v[142:145], v[182:185], v[58:61]
	v_mfma_f32_16x16x32_bf16 v[46:49], v[134:137], v[200:203], v[46:49]
	v_mfma_f32_16x16x32_bf16 v[42:45], v[142:145], v[200:203], v[42:45]
	v_mfma_f32_16x16x32_bf16 v[30:33], v[134:137], v[208:211], v[30:33]
	v_mfma_f32_16x16x32_bf16 v[26:29], v[142:145], v[208:211], v[26:29]
	v_mfma_f32_16x16x32_bf16 v[14:17], v[134:137], v[216:219], v[14:17]
	v_mfma_f32_16x16x32_bf16 v[10:13], v[142:145], v[216:219], v[10:13]
	v_mfma_f32_16x16x32_bf16 v[54:57], v[146:149], v[178:181], 0
	v_mfma_f32_16x16x32_bf16 v[50:53], v[170:173], v[178:181], 0
	v_mfma_f32_16x16x32_bf16 v[38:41], v[146:149], v[196:199], 0
	v_mfma_f32_16x16x32_bf16 v[34:37], v[170:173], v[196:199], 0
	v_mfma_f32_16x16x32_bf16 v[22:25], v[146:149], v[204:207], 0
	v_mfma_f32_16x16x32_bf16 v[18:21], v[170:173], v[204:207], 0
	v_mfma_f32_16x16x32_bf16 v[6:9], v[146:149], v[212:215], 0
	v_mfma_f32_16x16x32_bf16 v[2:5], v[170:173], v[212:215], 0
	v_mfma_f32_16x16x32_bf16 v[54:57], v[150:153], v[182:185], v[54:57]
	v_mfma_f32_16x16x32_bf16 v[50:53], v[174:177], v[182:185], v[50:53]
	v_mfma_f32_16x16x32_bf16 v[38:41], v[150:153], v[200:203], v[38:41]
	v_mfma_f32_16x16x32_bf16 v[34:37], v[174:177], v[200:203], v[34:37]
	v_mfma_f32_16x16x32_bf16 v[22:25], v[150:153], v[208:211], v[22:25]
	v_mfma_f32_16x16x32_bf16 v[18:21], v[174:177], v[208:211], v[18:21]
	v_mfma_f32_16x16x32_bf16 v[6:9], v[150:153], v[216:219], v[6:9]
	v_mfma_f32_16x16x32_bf16 v[2:5], v[174:177], v[216:219], v[2:5]
	s_barrier
	s_branch .Lpeel2_join
; #define PG8_STAGE(bufoff, gbase, voff) do { _Pragma("unroll") for (int _i = 0; _i < 2; ++_i) \
;         __builtin_amdgcn_global_load_lds((const unsigned*)((const char*)(gbase) + (voff)[_i]), (LAS unsigned*)(lds + (bufoff) + ldsw + _i * 8192), 16, 0, 0); } while (0)
; #define PG8_LDA(dst, b, h) do { _Pragma("unroll") for (int m = 0; m < 4; ++m) _Pragma("unroll") for (int k = 0; k < 2; ++k) dst[m][k] = *(const LAS bf16x8*)(lds + PG8_SA(b, h) + aoff + m * 2048 + k * 1024); } while (0)
; #define PG8_LDB(dst, b, h) do { _Pragma("unroll") for (int n = 0; n < 2; ++n) _Pragma("unroll") for (int k = 0; k < 2; ++k) dst[n][k] = *(const LAS bf16x8*)(lds + PG8_SB(b, h) + boff + n * 2048 + k * 1024); } while (0)
; #define PG8_MMA(ai, bj, At, Bt) do { __builtin_amdgcn_s_setprio(1); _Pragma("unroll") for (int m = 0; m < 4; ++m) _Pragma("unroll") for (int n = 0; n < 2; ++n) _Pragma("unroll") for (int k = 0; k < 2; ++k) \
;         acc[ai][bj][m][n] = __builtin_amdgcn_mfma_f32_16x16x32_bf16(Bt[n][k], At[m][k], acc[ai][bj][m][n], 0, 0, 0); __builtin_amdgcn_s_setprio(0); } while (0)
; #define PG8_WAIT_V(n) asm volatile("s_waitcnt vmcnt(" #n ")" ::: "memory")
; #define PG8_WAIT_L(n) asm volatile("s_waitcnt lgkmcnt(" #n ")" ::: "memory")
; #define PG8_BAR __builtin_amdgcn_s_barrier()
; #define PG8_SCHED __builtin_amdgcn_sched_barrier(0)
; template <class Epi, class Sched>
; __device__ __forceinline__ void gemm_phase(LAS unsigned char* lds, const int lda, const int ldb, const int K, const Sched& S, const Epi& E) {
;     ...
;             PG8_LDB(B0, 0, 0); PG8_LDB(B1, 0, 1); PG8_SCHED; PG8_LDA(At, 0, 0); PG8_STAGE(PG8_SA(1, 1), a1 + hstepA, voffA);
;             PG8_WAIT_V(8); PG8_WAIT_L(0); PG8_BAR; PG8_MMA(0, 0, At, B0); PG8_MMA(0, 1, At, B1); PG8_BAR; PG8_SCHED;
;             PG8_LDA(At, 0, 1); PG8_STAGE(PG8_SB(0, 0), b2, voffB); PG8_STAGE(PG8_SB(0, 1), b2 + hstepB, voffB); PG8_STAGE(PG8_SA(0, 0), a2, voffA);
;             PG8_WAIT_V(8); PG8_WAIT_L(0); PG8_BAR; PG8_MMA(1, 0, At, B0); PG8_MMA(1, 1, At, B1); PG8_BAR; PG8_SCHED;
.LBB0_326:
	ds_read_b128 v[130:133], v188
	ds_read_b128 v[134:137], v188 offset:1024
	ds_read_b128 v[138:141], v188 offset:2048
	ds_read_b128 v[142:145], v188 offset:3072
	ds_read_b128 v[146:149], v189
	ds_read_b128 v[150:153], v189 offset:1024
	ds_read_b128 v[170:173], v189 offset:2048
	ds_read_b128 v[174:177], v189 offset:3072
	s_add_u32 s20, s18, 0xfff50080
	s_addc_u32 s21, s19, -1
	s_cmp_eq_u32 s50, 40
	s_cselect_b32 s23, s15, s21
	s_cselect_b32 s22, s14, s20
	s_cselect_b32 s21, s17, s49
	s_cselect_b32 s20, s16, s48
	s_add_i32 m0, s26, 0xc000
	ds_read_b128 v[178:181], v190
	ds_read_b128 v[182:185], v190 offset:1024
	ds_read_b128 v[196:199], v190 offset:2048
	ds_read_b128 v[200:203], v190 offset:3072
	ds_read_b128 v[204:207], v190 offset:4096
	ds_read_b128 v[208:211], v190 offset:5120
	ds_read_b128 v[212:215], v190 offset:6144
	ds_read_b128 v[216:219], v190 offset:7168
	global_load_lds_dwordx4 v162, s[18:19]
	s_add_i32 m0, s26, 0xe000
	s_nop 0
	global_load_lds_dwordx4 v164, s[18:19]
	s_waitcnt vmcnt(8)
	s_waitcnt lgkmcnt(0)
	s_barrier
	s_waitcnt lgkmcnt(0)
	v_mfma_f32_16x16x32_bf16 v[126:129], v[130:133], v[178:181], v[126:129]
	v_mfma_f32_16x16x32_bf16 v[122:125], v[138:141], v[178:181], v[122:125]
	v_mfma_f32_16x16x32_bf16 v[110:113], v[130:133], v[196:199], v[110:113]
	v_mfma_f32_16x16x32_bf16 v[106:109], v[138:141], v[196:199], v[106:109]
	v_mfma_f32_16x16x32_bf16 v[94:97], v[130:133], v[204:207], v[94:97]
	v_mfma_f32_16x16x32_bf16 v[90:93], v[138:141], v[204:207], v[90:93]
	v_mfma_f32_16x16x32_bf16 v[78:81], v[130:133], v[212:215], v[78:81]
	v_mfma_f32_16x16x32_bf16 v[74:77], v[138:141], v[212:215], v[74:77]
	v_mfma_f32_16x16x32_bf16 v[126:129], v[134:137], v[182:185], v[126:129]
	v_mfma_f32_16x16x32_bf16 v[122:125], v[142:145], v[182:185], v[122:125]
	v_mfma_f32_16x16x32_bf16 v[110:113], v[134:137], v[200:203], v[110:113]
	v_mfma_f32_16x16x32_bf16 v[106:109], v[142:145], v[200:203], v[106:109]
	v_mfma_f32_16x16x32_bf16 v[94:97], v[134:137], v[208:211], v[94:97]
	v_mfma_f32_16x16x32_bf16 v[90:93], v[142:145], v[208:211], v[90:93]
	v_mfma_f32_16x16x32_bf16 v[78:81], v[134:137], v[216:219], v[78:81]
	v_mfma_f32_16x16x32_bf16 v[74:77], v[142:145], v[216:219], v[74:77]
	v_mfma_f32_16x16x32_bf16 v[118:121], v[146:149], v[178:181], v[118:121]
	v_mfma_f32_16x16x32_bf16 v[114:117], v[170:173], v[178:181], v[114:117]
	v_mfma_f32_16x16x32_bf16 v[102:105], v[146:149], v[196:199], v[102:105]
	v_mfma_f32_16x16x32_bf16 v[98:101], v[170:173], v[196:199], v[98:101]
	v_mfma_f32_16x16x32_bf16 v[86:89], v[146:149], v[204:207], v[86:89]
	v_mfma_f32_16x16x32_bf16 v[82:85], v[170:173], v[204:207], v[82:85]
	v_mfma_f32_16x16x32_bf16 v[70:73], v[146:149], v[212:215], v[70:73]
	v_mfma_f32_16x16x32_bf16 v[66:69], v[170:173], v[212:215], v[66:69]
	v_mfma_f32_16x16x32_bf16 v[118:121], v[150:153], v[182:185], v[118:121]
	v_mfma_f32_16x16x32_bf16 v[114:117], v[174:177], v[182:185], v[114:117]
	v_mfma_f32_16x16x32_bf16 v[102:105], v[150:153], v[200:203], v[102:105]
	v_mfma_f32_16x16x32_bf16 v[98:101], v[174:177], v[200:203], v[98:101]
	v_mfma_f32_16x16x32_bf16 v[86:89], v[150:153], v[208:211], v[86:89]
	v_mfma_f32_16x16x32_bf16 v[82:85], v[174:177], v[208:211], v[82:85]
	v_mfma_f32_16x16x32_bf16 v[70:73], v[150:153], v[216:219], v[70:73]
	v_mfma_f32_16x16x32_bf16 v[66:69], v[174:177], v[216:219], v[66:69]
	s_barrier
	s_add_i32 s51, s40, s25
	s_mov_b32 m0, s51
	ds_read_b128 v[178:181], v190 offset:16384
	ds_read_b128 v[182:185], v190 offset:17408
	ds_read_b128 v[196:199], v190 offset:18432
	ds_read_b128 v[200:203], v190 offset:19456
	ds_read_b128 v[204:207], v190 offset:20480
	ds_read_b128 v[208:211], v190 offset:21504
	ds_read_b128 v[212:215], v190 offset:22528
	ds_read_b128 v[216:219], v190 offset:23552
	global_load_lds_dwordx4 v156, s[20:21]
	s_add_i32 m0, s51, 0x2000
	s_add_u32 s62, s20, 0xb0000
	s_mov_b64 s[98:99], s[20:21]
	s_addc_u32 s63, s21, 0
	s_add_i32 s51, s41, s25
	global_load_lds_dwordx4 v160, s[20:21]
	s_mov_b32 m0, s51
	s_mov_b64 s[100:101], s[22:23]
	global_load_lds_dwordx4 v156, s[62:63]
	s_add_i32 m0, s51, 0x2000
	s_nop 0
	global_load_lds_dwordx4 v160, s[62:63]
	s_mov_b32 m0, s26
	s_nop 0
	global_load_lds_dwordx4 v154, s[22:23]
	s_mov_b32 m0, s27
	s_nop 0
	global_load_lds_dwordx4 v158, s[22:23]
	s_waitcnt vmcnt(8)
	s_waitcnt lgkmcnt(0)
	s_barrier
	s_waitcnt lgkmcnt(0)
	v_mfma_f32_16x16x32_bf16 v[62:65], v[130:133], v[178:181], v[62:65]
	v_mfma_f32_16x16x32_bf16 v[58:61], v[138:141], v[178:181], v[58:61]
	v_mfma_f32_16x16x32_bf16 v[46:49], v[130:133], v[196:199], v[46:49]
	v_mfma_f32_16x16x32_bf16 v[42:45], v[138:141], v[196:199], v[42:45]
	v_mfma_f32_16x16x32_bf16 v[30:33], v[130:133], v[204:207], v[30:33]
	v_mfma_f32_16x16x32_bf16 v[26:29], v[138:141], v[204:207], v[26:29]
	v_mfma_f32_16x16x32_bf16 v[14:17], v[130:133], v[212:215], v[14:17]
	v_mfma_f32_16x16x32_bf16 v[10:13], v[138:141], v[212:215], v[10:13]
	v_mfma_f32_16x16x32_bf16 v[62:65], v[134:137], v[182:185], v[62:65]
	v_mfma_f32_16x16x32_bf16 v[58:61], v[142:145], v[182:185], v[58:61]
	v_mfma_f32_16x16x32_bf16 v[46:49], v[134:137], v[200:203], v[46:49]
	v_mfma_f32_16x16x32_bf16 v[42:45], v[142:145], v[200:203], v[42:45]
	v_mfma_f32_16x16x32_bf16 v[30:33], v[134:137], v[208:211], v[30:33]
	v_mfma_f32_16x16x32_bf16 v[26:29], v[142:145], v[208:211], v[26:29]
	v_mfma_f32_16x16x32_bf16 v[14:17], v[134:137], v[216:219], v[14:17]
	v_mfma_f32_16x16x32_bf16 v[10:13], v[142:145], v[216:219], v[10:13]
	v_mfma_f32_16x16x32_bf16 v[54:57], v[146:149], v[178:181], v[54:57]
	v_mfma_f32_16x16x32_bf16 v[50:53], v[170:173], v[178:181], v[50:53]
	v_mfma_f32_16x16x32_bf16 v[38:41], v[146:149], v[196:199], v[38:41]
	v_mfma_f32_16x16x32_bf16 v[34:37], v[170:173], v[196:199], v[34:37]
	v_mfma_f32_16x16x32_bf16 v[22:25], v[146:149], v[204:207], v[22:25]
	v_mfma_f32_16x16x32_bf16 v[18:21], v[170:173], v[204:207], v[18:21]
	v_mfma_f32_16x16x32_bf16 v[6:9], v[146:149], v[212:215], v[6:9]
	v_mfma_f32_16x16x32_bf16 v[2:5], v[170:173], v[212:215], v[2:5]
	v_mfma_f32_16x16x32_bf16 v[54:57], v[150:153], v[182:185], v[54:57]
	v_mfma_f32_16x16x32_bf16 v[50:53], v[174:177], v[182:185], v[50:53]
	v_mfma_f32_16x16x32_bf16 v[38:41], v[150:153], v[200:203], v[38:41]
	v_mfma_f32_16x16x32_bf16 v[34:37], v[174:177], v[200:203], v[34:37]
	v_mfma_f32_16x16x32_bf16 v[22:25], v[150:153], v[208:211], v[22:25]
	v_mfma_f32_16x16x32_bf16 v[18:21], v[174:177], v[208:211], v[18:21]
	v_mfma_f32_16x16x32_bf16 v[6:9], v[150:153], v[216:219], v[6:9]
	v_mfma_f32_16x16x32_bf16 v[2:5], v[174:177], v[216:219], v[2:5]
	s_barrier
; #define PG8_STAGE(bufoff, gbase, voff) do { _Pragma("unroll") for (int _i = 0; _i < 2; ++_i) \
;         __builtin_amdgcn_global_load_lds((const unsigned*)((const char*)(gbase) + (voff)[_i]), (LAS unsigned*)(lds + (bufoff) + ldsw + _i * 8192), 16, 0, 0); } while (0)
; #define PG8_LDA(dst, b, h) do { _Pragma("unroll") for (int m = 0; m < 4; ++m) _Pragma("unroll") for (int k = 0; k < 2; ++k) dst[m][k] = *(const LAS bf16x8*)(lds + PG8_SA(b, h) + aoff + m * 2048 + k * 1024); } while (0)
; #define PG8_LDB(dst, b, h) do { _Pragma("unroll") for (int n = 0; n < 2; ++n) _Pragma("unroll") for (int k = 0; k < 2; ++k) dst[n][k] = *(const LAS bf16x8*)(lds + PG8_SB(b, h) + boff + n * 2048 + k * 1024); } while (0)
; #define PG8_MMA(ai, bj, At, Bt) do { __builtin_amdgcn_s_setprio(1); _Pragma("unroll") for (int m = 0; m < 4; ++m) _Pragma("unroll") for (int n = 0; n < 2; ++n) _Pragma("unroll") for (int k = 0; k < 2; ++k) \
;         acc[ai][bj][m][n] = __builtin_amdgcn_mfma_f32_16x16x32_bf16(Bt[n][k], At[m][k], acc[ai][bj][m][n], 0, 0, 0); __builtin_amdgcn_s_setprio(0); } while (0)
; #define PG8_WAIT_V(n) asm volatile("s_waitcnt vmcnt(" #n ")" ::: "memory")
; #define PG8_WAIT_L(n) asm volatile("s_waitcnt lgkmcnt(" #n ")" ::: "memory")
; #define PG8_BAR __builtin_amdgcn_s_barrier()
; #define PG8_SCHED __builtin_amdgcn_sched_barrier(0)
; template <class Epi, class Sched>
; __device__ __forceinline__ void gemm_phase(LAS unsigned char* lds, const int lda, const int ldb, const int K, const Sched& S, const Epi& E) {
;     ...
;             PG8_LDB(B0, 1, 0); PG8_LDB(B1, 1, 1); PG8_SCHED; PG8_LDA(At, 1, 0); PG8_STAGE(PG8_SA(0, 1), a2 + hstepA, voffA);
;             PG8_WAIT_V(8); PG8_WAIT_L(0); PG8_BAR; PG8_MMA(0, 0, At, B0); PG8_MMA(0, 1, At, B1); PG8_BAR; PG8_SCHED;
;             PG8_LDA(At, 1, 1); PG8_STAGE(PG8_SB(1, 0), b3, voffB); PG8_STAGE(PG8_SB(1, 1), b3 + hstepB, voffB); PG8_STAGE(PG8_SA(1, 0), a3, voffA);
;             PG8_WAIT_V(8); PG8_WAIT_L(0); PG8_BAR;
;             if (last) E.pre(cur, wr, fr, rsv);
;             PG8_MMA(1, 0, At, B0); PG8_MMA(1, 1, At, B1); PG8_BAR; PG8_SCHED;
;         }
.Lpeel2_join:
	s_add_i32 s51, 0, 0x18000
	s_add_i32 s62, 0, 0x1c000
	v_add_u32_e32 v142, s51, v186
	v_add_u32_e32 v174, s62, v186
	ds_read_b128 v[130:133], v142
	ds_read_b128 v[134:137], v142 offset:1024
	ds_read_b128 v[138:141], v142 offset:2048
	ds_read_b128 v[142:145], v142 offset:3072
	ds_read_b128 v[146:149], v174
	ds_read_b128 v[150:153], v174 offset:1024
	ds_read_b128 v[170:173], v174 offset:2048
	ds_read_b128 v[174:177], v174 offset:3072
	s_add_u32 s22, s22, 0xb0000
	s_addc_u32 s23, s23, 0
	s_mov_b32 m0, s28
	ds_read_b128 v[178:181], v190 offset:32768
	ds_read_b128 v[182:185], v190 offset:33792
	ds_read_b128 v[196:199], v190 offset:34816
	ds_read_b128 v[200:203], v190 offset:35840
	ds_read_b128 v[204:207], v190 offset:36864
	ds_read_b128 v[208:211], v190 offset:37888
	ds_read_b128 v[212:215], v190 offset:38912
	ds_read_b128 v[216:219], v190 offset:39936
	global_load_lds_dwordx4 v154, s[22:23]
	s_mov_b32 m0, s29
	s_nop 0
	global_load_lds_dwordx4 v158, s[22:23]
	s_waitcnt vmcnt(8)
	s_waitcnt lgkmcnt(0)
	s_barrier
	s_waitcnt lgkmcnt(0)
	v_mfma_f32_16x16x32_bf16 v[126:129], v[130:133], v[178:181], v[126:129]
	v_mfma_f32_16x16x32_bf16 v[122:125], v[138:141], v[178:181], v[122:125]
	v_mfma_f32_16x16x32_bf16 v[110:113], v[130:133], v[196:199], v[110:113]
	v_mfma_f32_16x16x32_bf16 v[106:109], v[138:141], v[196:199], v[106:109]
	v_mfma_f32_16x16x32_bf16 v[94:97], v[130:133], v[204:207], v[94:97]
	v_mfma_f32_16x16x32_bf16 v[90:93], v[138:141], v[204:207], v[90:93]
	v_mfma_f32_16x16x32_bf16 v[78:81], v[130:133], v[212:215], v[78:81]
	v_mfma_f32_16x16x32_bf16 v[74:77], v[138:141], v[212:215], v[74:77]
	v_mfma_f32_16x16x32_bf16 v[126:129], v[134:137], v[182:185], v[126:129]
	v_mfma_f32_16x16x32_bf16 v[122:125], v[142:145], v[182:185], v[122:125]
	v_mfma_f32_16x16x32_bf16 v[110:113], v[134:137], v[200:203], v[110:113]
	v_mfma_f32_16x16x32_bf16 v[106:109], v[142:145], v[200:203], v[106:109]
	v_mfma_f32_16x16x32_bf16 v[94:97], v[134:137], v[208:211], v[94:97]
	v_mfma_f32_16x16x32_bf16 v[90:93], v[142:145], v[208:211], v[90:93]
	v_mfma_f32_16x16x32_bf16 v[78:81], v[134:137], v[216:219], v[78:81]
	v_mfma_f32_16x16x32_bf16 v[74:77], v[142:145], v[216:219], v[74:77]
	v_mfma_f32_16x16x32_bf16 v[118:121], v[146:149], v[178:181], v[118:121]
	v_mfma_f32_16x16x32_bf16 v[114:117], v[170:173], v[178:181], v[114:117]
	v_mfma_f32_16x16x32_bf16 v[102:105], v[146:149], v[196:199], v[102:105]
	v_mfma_f32_16x16x32_bf16 v[98:101], v[170:173], v[196:199], v[98:101]
	v_mfma_f32_16x16x32_bf16 v[86:89], v[146:149], v[204:207], v[86:89]
	v_mfma_f32_16x16x32_bf16 v[82:85], v[170:173], v[204:207], v[82:85]
	v_mfma_f32_16x16x32_bf16 v[70:73], v[146:149], v[212:215], v[70:73]
	v_mfma_f32_16x16x32_bf16 v[66:69], v[170:173], v[212:215], v[66:69]
	v_mfma_f32_16x16x32_bf16 v[118:121], v[150:153], v[182:185], v[118:121]
	v_mfma_f32_16x16x32_bf16 v[114:117], v[174:177], v[182:185], v[114:117]
	v_mfma_f32_16x16x32_bf16 v[102:105], v[150:153], v[200:203], v[102:105]
	v_mfma_f32_16x16x32_bf16 v[98:101], v[174:177], v[200:203], v[98:101]
	v_mfma_f32_16x16x32_bf16 v[86:89], v[150:153], v[208:211], v[86:89]
	v_mfma_f32_16x16x32_bf16 v[82:85], v[174:177], v[208:211], v[82:85]
	v_mfma_f32_16x16x32_bf16 v[70:73], v[150:153], v[216:219], v[70:73]
	v_mfma_f32_16x16x32_bf16 v[66:69], v[174:177], v[216:219], v[66:69]
	s_barrier
	s_add_i32 s22, s51, s25
	s_mov_b32 m0, s22
	ds_read_b128 v[178:181], v190 offset:49152
	ds_read_b128 v[182:185], v190 offset:50176
	ds_read_b128 v[196:199], v190 offset:51200
	ds_read_b128 v[200:203], v190 offset:52224
	ds_read_b128 v[204:207], v190 offset:53248
	ds_read_b128 v[208:211], v190 offset:54272
	ds_read_b128 v[212:215], v190 offset:55296
	ds_read_b128 v[216:219], v190 offset:56320
	global_load_lds_dwordx4 v192, s[20:21]
	s_add_i32 m0, s22, 0x2000
	s_add_u32 s20, s20, 0xb0080
	s_addc_u32 s21, s21, 0
	s_add_i32 s22, s62, s25
	global_load_lds_dwordx4 v193, s[98:99]
	s_mov_b32 m0, s22
	s_nop 0
	global_load_lds_dwordx4 v156, s[20:21]
	s_add_i32 m0, s22, 0x2000
	s_nop 0
	global_load_lds_dwordx4 v160, s[20:21]
	s_mov_b32 m0, s33
	s_nop 0
	global_load_lds_dwordx4 v220, s[100:101]
	s_mov_b32 m0, s36
	s_nop 0
	global_load_lds_dwordx4 v221, s[100:101]
	s_waitcnt vmcnt(8)
	s_waitcnt lgkmcnt(0)
	s_barrier
	s_waitcnt lgkmcnt(0)
	v_mfma_f32_16x16x32_bf16 v[62:65], v[130:133], v[178:181], v[62:65]
	v_mfma_f32_16x16x32_bf16 v[58:61], v[138:141], v[178:181], v[58:61]
	v_mfma_f32_16x16x32_bf16 v[46:49], v[130:133], v[196:199], v[46:49]
	v_mfma_f32_16x16x32_bf16 v[42:45], v[138:141], v[196:199], v[42:45]
	v_mfma_f32_16x16x32_bf16 v[30:33], v[130:133], v[204:207], v[30:33]
	v_mfma_f32_16x16x32_bf16 v[26:29], v[138:141], v[204:207], v[26:29]
	v_mfma_f32_16x16x32_bf16 v[14:17], v[130:133], v[212:215], v[14:17]
	v_mfma_f32_16x16x32_bf16 v[10:13], v[138:141], v[212:215], v[10:13]
	v_mfma_f32_16x16x32_bf16 v[62:65], v[134:137], v[182:185], v[62:65]
	v_mfma_f32_16x16x32_bf16 v[58:61], v[142:145], v[182:185], v[58:61]
	v_mfma_f32_16x16x32_bf16 v[46:49], v[134:137], v[200:203], v[46:49]
	v_mfma_f32_16x16x32_bf16 v[42:45], v[142:145], v[200:203], v[42:45]
	v_mfma_f32_16x16x32_bf16 v[30:33], v[134:137], v[208:211], v[30:33]
	v_mfma_f32_16x16x32_bf16 v[26:29], v[142:145], v[208:211], v[26:29]
	v_mfma_f32_16x16x32_bf16 v[14:17], v[134:137], v[216:219], v[14:17]
	v_mfma_f32_16x16x32_bf16 v[10:13], v[142:145], v[216:219], v[10:13]
	v_mfma_f32_16x16x32_bf16 v[54:57], v[146:149], v[178:181], v[54:57]
	v_mfma_f32_16x16x32_bf16 v[50:53], v[170:173], v[178:181], v[50:53]
	v_mfma_f32_16x16x32_bf16 v[38:41], v[146:149], v[196:199], v[38:41]
	v_mfma_f32_16x16x32_bf16 v[34:37], v[170:173], v[196:199], v[34:37]
	v_mfma_f32_16x16x32_bf16 v[22:25], v[146:149], v[204:207], v[22:25]
	v_mfma_f32_16x16x32_bf16 v[18:21], v[170:173], v[204:207], v[18:21]
	v_mfma_f32_16x16x32_bf16 v[6:9], v[146:149], v[212:215], v[6:9]
	v_mfma_f32_16x16x32_bf16 v[2:5], v[170:173], v[212:215], v[2:5]
	v_mfma_f32_16x16x32_bf16 v[54:57], v[150:153], v[182:185], v[54:57]
	v_mfma_f32_16x16x32_bf16 v[50:53], v[174:177], v[182:185], v[50:53]
	v_mfma_f32_16x16x32_bf16 v[38:41], v[150:153], v[200:203], v[38:41]
	v_mfma_f32_16x16x32_bf16 v[34:37], v[174:177], v[200:203], v[34:37]
	v_mfma_f32_16x16x32_bf16 v[22:25], v[150:153], v[208:211], v[22:25]
	v_mfma_f32_16x16x32_bf16 v[18:21], v[174:177], v[208:211], v[18:21]
	v_mfma_f32_16x16x32_bf16 v[6:9], v[150:153], v[216:219], v[6:9]
	v_mfma_f32_16x16x32_bf16 v[2:5], v[174:177], v[216:219], v[2:5]
	s_barrier
	s_add_i32 s50, s50, 2
	s_add_u32 s18, s18, 0x100
	s_addc_u32 s19, s19, 0
	s_add_u32 s48, s48, 0x100
	s_addc_u32 s49, s49, 0
	s_cmp_gt_u32 s50, 41
	s_cbranch_scc0 .LBB0_326
	s_and_b64 vcc, exec, s[12:13]
	s_cbranch_vccz .LBB0_329
	s_barrier

; #define PG8_WAIT_V(n) asm volatile("s_waitcnt vmcnt(" #n ")" ::: "memory")
; #define PG8_BAR __builtin_amdgcn_s_barrier()
; template <class Epi, class Sched>
; __device__ __forceinline__ void gemm_phase(LAS unsigned char* lds, const int lda, const int ldb, const int K, const Sched& S, const Epi& E) {
;     ...
;     PG8_WAIT_V(0);
;     PG8_BAR;
.LBB0_348:
	s_waitcnt vmcnt(0)
	s_barrier
	s_setprio 0

; #define PG8_STAGE(bufoff, gbase, voff) do { _Pragma("unroll") for (int _i = 0; _i < 2; ++_i) \
;         __builtin_amdgcn_global_load_lds((const unsigned*)((const char*)(gbase) + (voff)[_i]), (LAS unsigned*)(lds + (bufoff) + ldsw + _i * 8192), 16, 0, 0); } while (0)
; #define PG8_BAR __builtin_amdgcn_s_barrier()
; template <class Epi, class Sched>
; __device__ __forceinline__ void gemm_phase(LAS unsigned char* lds, const int lda, const int ldb, const int K, const Sched& S, const Epi& E) {
;     const int tid = threadIdx.x, wid = __builtin_amdgcn_readfirstlane(tid >> 6), lane = tid & 63, wr = wid >> 2, wc = wid & 3, fr = lane & 15, fq = lane >> 4;
;     const int nt = K / BK;
;     unsigned voffA[2], voffB[2];
; #pragma unroll
;     for (int i = 0; i < 2; ++i) { int R, C; stage_rc(tid * 16 + i * 8192, R, C); const int Rb = (R & ~31) + perm32(R & 31);
;         voffA[i] = (unsigned)(R * lda + C) * 2u; voffB[i] = (unsigned)(Rb * ldb + C) * 2u; }
;     const size_t kstep = (size_t)(BK * 2);
;     const size_t hstepA = (size_t)HALF * lda * 2, hstepB = (size_t)HALF * ldb * 2;
;     const unsigned ldsw = (unsigned)wid * 1024u;
;     const int aoff = lds_byte(wr * 64 + fr, fq * 8), boff = lds_byte(wc * 32 + fr, fq * 8);
;     ...
;     Unit cur, nxt; int ui = 0;
;     if (!S.next(0, cur)) return;
;     f32x4 acc[2][2][4][2];
; #pragma unroll
;     for (int a = 0; a < 2; ++a)
; #pragma unroll
;         for (int b = 0; b < 2; ++b)
; #pragma unroll
;             for (int m = 0; m < 4; ++m)
; #pragma unroll
;                 for (int n = 0; n < 2; ++n) acc[a][b][m][n] = (f32x4){0.f, 0.f, 0.f, 0.f};
;     bf16x8 At[4][2], B0[2][2], B1[2][2];
;     float rsv[8];
; #pragma unroll
;     for (int i = 0; i < 8; ++i) rsv[i] = 0.f;
;     const char* cA = cur.A; const char* cB = cur.B;
;     PG8_STAGE(PG8_SB(0, 0), cB, voffB); PG8_STAGE(PG8_SB(0, 1), cB + hstepB, voffB); PG8_STAGE(PG8_SA(0, 0), cA, voffA); PG8_STAGE(PG8_SA(0, 1), cA + hstepA, voffA);
;     if (wr == 1) PG8_BAR;
.LBB0_416:
.LBB0_417:
	v_lshrrev_b32_e32 v1, 5, v194
	s_waitcnt lgkmcnt(0)
	v_lshrrev_b32_e32 v3, 1, v194
	v_and_b32_e32 v1, 4, v1
	v_bfe_u32 v2, v194, 2, 2
	v_and_b32_e32 v3, 24, v3
	v_or3_b32 v1, v1, v2, v3
	v_lshlrev_b32_e32 v2, 4, v194
	v_add_u32_e32 v10, 0x2000, v2
	v_lshrrev_b32_e32 v3, 7, v10
	s_movk_i32 s0, 0xe0
	v_and_b32_e32 v5, 32, v194
	v_and_or_b32 v4, v3, s0, v1
	v_bitop3_b32 v11, v2, v5, 48 bitop3:0x6c
	v_and_b32_e32 v12, 64, v194
	v_bfe_u32 v13, v194, 2, 4
	s_movk_i32 s0, 0xf0
	v_or_b32_e32 v2, v11, v12
	v_and_or_b32 v3, v3, s0, v13
	s_add_u32 s3, s54, 0x1080000
	v_lshl_or_b32 v200, v3, 11, v2
	v_lshrrev_b32_e32 v3, 3, v194
	s_movk_i32 s0, 0x60
	s_addc_u32 s33, s55, 0
	v_and_or_b32 v1, v3, s0, v1
	s_movk_i32 s0, 0x70
	s_ashr_i32 s37, s2, 31
	v_lshl_or_b32 v202, v1, 11, v2
	v_and_or_b32 v1, v3, s0, v13
	s_lshr_b32 s0, s37, 29
	s_add_i32 s0, s2, s0
	s_lshr_b32 s11, s10, 6
	s_and_b32 s4, s0, -8
	s_lshr_b32 s1, s10, 8
	s_lshl_b32 s36, s11, 10
	s_sub_i32 s4, s2, s4
	s_cmp_lt_i32 s4, 0
	s_movk_i32 s38, 0x391
	s_cselect_b32 s5, s38, 0x390
	s_mul_i32 s4, s4, s5
	s_ashr_i32 s0, s0, 3
	s_add_i32 s4, s4, s0
	s_mul_hi_i32 s0, s4, 0x6bca1af3
	s_lshr_b32 s5, s0, 31
	s_ashr_i32 s0, s0, 6
	s_add_i32 s0, s0, s5
	s_lshl_b32 s5, s0, 3
	s_mulk_i32 s0, 0x98
	s_sub_i32 s0, s4, s0
	s_bfe_u32 s4, s0, 0x3001c
	s_add_i32 s6, s0, s4
	s_and_b32 s4, s6, 0xfff8
	s_sub_i32 s0, s0, s4
	s_sext_i32_i16 s0, s0
	s_add_i32 s4, s5, s0
	s_sext_i32_i16 s0, s6
	s_ashr_i32 s5, s4, 31
	s_lshr_b32 s0, s0, 3
	s_lshl_b64 s[6:7], s[4:5], 19
	s_add_u32 s6, s60, s6
	s_addc_u32 s7, s61, s7
	s_bfe_i64 s[8:9], s[0:1], 0x100000
	s_lshl_b64 s[8:9], s[8:9], 19
	s_add_u32 s8, s3, s8
	s_addc_u32 s9, s33, s9
	s_add_i32 s39, s36, 0
	s_add_i32 m0, s39, 0x10000
	v_lshl_or_b32 v198, v4, 11, v2
	global_load_lds_dwordx4 v202, s[8:9]
	s_add_i32 m0, s39, 0x12000
	s_add_u32 s12, s8, 0x40000
	global_load_lds_dwordx4 v198, s[8:9]
	s_addc_u32 s13, s9, 0
	s_add_i32 m0, s39, 0x14000
	s_add_i32 s40, s39, 0x2000
	global_load_lds_dwordx4 v202, s[12:13]
	s_add_i32 m0, s39, 0x16000
	v_lshl_or_b32 v204, v1, 11, v2
	global_load_lds_dwordx4 v198, s[12:13]
	s_mov_b32 m0, s39
	s_add_u32 s12, s6, 0x40000
	global_load_lds_dwordx4 v204, s[6:7]
	s_mov_b32 m0, s40
	s_addc_u32 s13, s7, 0
	s_add_i32 s41, s39, 0x4000
	global_load_lds_dwordx4 v200, s[6:7]
	s_mov_b32 m0, s41
	s_add_i32 s42, s39, 0x6000
	global_load_lds_dwordx4 v204, s[12:13]
	s_mov_b32 m0, s42
	v_mov_b32_e32 v203, 0
	global_load_lds_dwordx4 v200, s[12:13]
	v_mov_b32_e32 v199, v203
	v_mov_b32_e32 v205, v203
	v_mov_b32_e32 v201, v203
	s_cmp_eq_u32 s1, 1
	s_mov_b32 s21, 0
	v_lshl_add_u64 v[8:9], s[8:9], 0, v[202:203]
	v_lshl_add_u64 v[6:7], s[8:9], 0, v[198:199]
	v_lshl_add_u64 v[2:3], s[6:7], 0, v[204:205]
	s_cselect_b64 s[22:23], -1, 0
	s_cmp_lg_u32 s1, 1
	v_lshl_add_u64 v[4:5], s[6:7], 0, v[200:201]
	s_cbranch_scc1 .LBB0_419
	s_setprio 1
	s_barrier

; #define PG8_STAGE(bufoff, gbase, voff) do { _Pragma("unroll") for (int _i = 0; _i < 2; ++_i) \
;         __builtin_amdgcn_global_load_lds((const unsigned*)((const char*)(gbase) + (voff)[_i]), (LAS unsigned*)(lds + (bufoff) + ldsw + _i * 8192), 16, 0, 0); } while (0)
; #define PG8_LDA(dst, b, h) do { _Pragma("unroll") for (int m = 0; m < 4; ++m) _Pragma("unroll") for (int k = 0; k < 2; ++k) dst[m][k] = *(const LAS bf16x8*)(lds + PG8_SA(b, h) + aoff + m * 2048 + k * 1024); } while (0)
; #define PG8_LDB(dst, b, h) do { _Pragma("unroll") for (int n = 0; n < 2; ++n) _Pragma("unroll") for (int k = 0; k < 2; ++k) dst[n][k] = *(const LAS bf16x8*)(lds + PG8_SB(b, h) + boff + n * 2048 + k * 1024); } while (0)
; #define PG8_MMA(ai, bj, At, Bt) do { __builtin_amdgcn_s_setprio(1); _Pragma("unroll") for (int m = 0; m < 4; ++m) _Pragma("unroll") for (int n = 0; n < 2; ++n) _Pragma("unroll") for (int k = 0; k < 2; ++k) \
;         acc[ai][bj][m][n] = __builtin_amdgcn_mfma_f32_16x16x32_bf16(Bt[n][k], At[m][k], acc[ai][bj][m][n], 0, 0, 0); __builtin_amdgcn_s_setprio(0); } while (0)
; #define PG8_WAIT_V(n) asm volatile("s_waitcnt vmcnt(" #n ")" ::: "memory")
; template <class Epi, class Sched>
; __device__ __forceinline__ void gemm_phase(LAS unsigned char* lds, const int lda, const int ldb, const int K, const Sched& S, const Epi& E) {
;     ...
;         const bool has_next = S.next(ui + 1, nxt);
;         const char* nA = has_next ? nxt.A : cA; const char* nB = has_next ? nxt.B : cB;
;         for (int t = 0; t < nt; t += 2) {
;             const bool last = (t == nt - 2);
;             const char* a1 = cA + (size_t)(t + 1) * kstep;
;             const char* a2 = last ? nA : cA + (size_t)(t + 2) * kstep; const char* b2 = last ? nB : cB + (size_t)(t + 2) * kstep;
;             const char* a3 = a2 + kstep; const char* b3 = b2 + kstep;
;             PG8_LDB(B0, 0, 0); PG8_LDB(B1, 0, 1); PG8_SCHED; PG8_LDA(At, 0, 0); PG8_STAGE(PG8_SA(1, 1), a1 + hstepA, voffA);
;             PG8_WAIT_V(8); PG8_WAIT_L(0); PG8_BAR; PG8_MMA(0, 0, At, B0); PG8_MMA(0, 1, At, B1); PG8_BAR; PG8_SCHED;
;             PG8_LDA(At, 0, 1); PG8_STAGE(PG8_SB(0, 0), b2, voffB); PG8_STAGE(PG8_SB(0, 1), b2 + hstepB, voffB); PG8_STAGE(PG8_SA(0, 0), a2, voffA);
;             PG8_WAIT_V(8); PG8_WAIT_L(0); PG8_BAR; PG8_MMA(1, 0, At, B0); PG8_MMA(1, 1, At, B1); PG8_BAR; PG8_SCHED;
.LBB0_424:
	s_lshl_b32 s4, s4, 8
	s_ashr_i32 s5, s4, 31
	s_add_u32 s6, s6, 0x40080
	s_addc_u32 s7, s7, 0
	v_lshl_add_u64 v[220:221], s[4:5], 2, v[206:207]
	s_add_u32 s5, s8, 0x100
	s_addc_u32 s51, s9, 0
	s_mov_b32 s69, -2
	v_add_u32_e32 v234, 0x80, v202
	v_add_u32_e32 v235, 0x80, v198
	v_add_u32_e32 v236, 0x80, v204
	v_add_u32_e32 v237, 0x80, v200
	s_add_u32 s8, s6, 0xfffc0080
	s_addc_u32 s9, s7, -1
	s_cmp_eq_u32 s69, 12
	s_cselect_b32 s13, s71, s9
	s_cselect_b32 s12, s70, s8
	s_cselect_b32 s15, s73, s51
	s_cselect_b32 s14, s72, s5
	s_add_i32 s81, s63, s36
	ds_read_b128 v[130:133], v222
	ds_read_b128 v[134:137], v222 offset:1024
	ds_read_b128 v[138:141], v222 offset:2048
	ds_read_b128 v[142:145], v222 offset:3072
	ds_read_b128 v[146:149], v223
	ds_read_b128 v[150:153], v223 offset:1024
	ds_read_b128 v[154:157], v223 offset:2048
	ds_read_b128 v[158:161], v223 offset:3072
	s_add_i32 m0, s39, 0xc000
	s_add_i32 s80, s39, 0xe000
	s_add_i32 s82, s81, 0x2000
	s_add_u32 s16, s14, 0x40000
	s_addc_u32 s17, s15, 0
	s_add_i32 s83, s64, s36
	s_add_i32 s84, s83, 0x2000
	s_add_i32 s85, 0, 0x18000
	s_add_i32 s86, 0, 0x1c000
	s_add_u32 s10, s12, 0x40000
	s_addc_u32 s11, s13, 0
	s_add_i32 s75, s85, s36
	s_add_i32 s74, s75, 0x2000
	s_add_u32 s8, s14, 0x40080
	s_addc_u32 s9, s15, 0
	s_add_i32 s79, s86, s36
	s_add_i32 s78, s79, 0x2000
	s_cmp_lg_u32 s69, 12
	ds_read_b128 v[162:165], v224
	ds_read_b128 v[166:169], v224 offset:1024
	ds_read_b128 v[170:173], v224 offset:2048
	ds_read_b128 v[174:177], v224 offset:3072
	ds_read_b128 v[178:181], v224 offset:4096
	ds_read_b128 v[182:185], v224 offset:5120
	ds_read_b128 v[186:189], v224 offset:6144
	ds_read_b128 v[190:193], v224 offset:7168
	global_load_lds_dwordx4 v212, s[6:7]
	s_mov_b32 m0, s80
	s_nop 0
	global_load_lds_dwordx4 v214, s[6:7]
	s_waitcnt vmcnt(8)
	s_waitcnt lgkmcnt(0)
	s_barrier
	s_waitcnt lgkmcnt(0)
	v_mfma_f32_16x16x32_bf16 v[126:129], v[130:133], v[162:165], 0
	v_mfma_f32_16x16x32_bf16 v[118:121], v[138:141], v[162:165], 0
	v_mfma_f32_16x16x32_bf16 v[110:113], v[130:133], v[170:173], 0
	v_mfma_f32_16x16x32_bf16 v[102:105], v[138:141], v[170:173], 0
	v_mfma_f32_16x16x32_bf16 v[94:97], v[130:133], v[178:181], 0
	v_mfma_f32_16x16x32_bf16 v[86:89], v[138:141], v[178:181], 0
	v_mfma_f32_16x16x32_bf16 v[78:81], v[130:133], v[186:189], 0
	v_mfma_f32_16x16x32_bf16 v[70:73], v[138:141], v[186:189], 0
	v_mfma_f32_16x16x32_bf16 v[126:129], v[134:137], v[166:169], v[126:129]
	v_mfma_f32_16x16x32_bf16 v[118:121], v[142:145], v[166:169], v[118:121]
	v_mfma_f32_16x16x32_bf16 v[110:113], v[134:137], v[174:177], v[110:113]
	v_mfma_f32_16x16x32_bf16 v[102:105], v[142:145], v[174:177], v[102:105]
	v_mfma_f32_16x16x32_bf16 v[94:97], v[134:137], v[182:185], v[94:97]
	v_mfma_f32_16x16x32_bf16 v[86:89], v[142:145], v[182:185], v[86:89]
	v_mfma_f32_16x16x32_bf16 v[78:81], v[134:137], v[190:193], v[78:81]
	v_mfma_f32_16x16x32_bf16 v[70:73], v[142:145], v[190:193], v[70:73]
	v_mfma_f32_16x16x32_bf16 v[122:125], v[146:149], v[162:165], 0
	v_mfma_f32_16x16x32_bf16 v[114:117], v[154:157], v[162:165], 0
	v_mfma_f32_16x16x32_bf16 v[106:109], v[146:149], v[170:173], 0
	v_mfma_f32_16x16x32_bf16 v[98:101], v[154:157], v[170:173], 0
	v_mfma_f32_16x16x32_bf16 v[90:93], v[146:149], v[178:181], 0
	v_mfma_f32_16x16x32_bf16 v[82:85], v[154:157], v[178:181], 0
	v_mfma_f32_16x16x32_bf16 v[74:77], v[146:149], v[186:189], 0
	v_mfma_f32_16x16x32_bf16 v[66:69], v[154:157], v[186:189], 0
	v_mfma_f32_16x16x32_bf16 v[122:125], v[150:153], v[166:169], v[122:125]
	v_mfma_f32_16x16x32_bf16 v[114:117], v[158:161], v[166:169], v[114:117]
	v_mfma_f32_16x16x32_bf16 v[106:109], v[150:153], v[174:177], v[106:109]
	v_mfma_f32_16x16x32_bf16 v[98:101], v[158:161], v[174:177], v[98:101]
	v_mfma_f32_16x16x32_bf16 v[90:93], v[150:153], v[182:185], v[90:93]
	v_mfma_f32_16x16x32_bf16 v[82:85], v[158:161], v[182:185], v[82:85]
	v_mfma_f32_16x16x32_bf16 v[74:77], v[150:153], v[190:193], v[74:77]
	v_mfma_f32_16x16x32_bf16 v[66:69], v[158:161], v[190:193], v[66:69]
	s_barrier
	s_mov_b32 m0, s81
	ds_read_b128 v[162:165], v224 offset:16384
	ds_read_b128 v[166:169], v224 offset:17408
	ds_read_b128 v[170:173], v224 offset:18432
	ds_read_b128 v[174:177], v224 offset:19456
	ds_read_b128 v[178:181], v224 offset:20480
	ds_read_b128 v[182:185], v224 offset:21504
	ds_read_b128 v[186:189], v224 offset:22528
	ds_read_b128 v[190:193], v224 offset:23552
	global_load_lds_dwordx4 v202, s[14:15]
	s_mov_b32 m0, s82
	s_nop 0
	global_load_lds_dwordx4 v198, s[14:15]
	s_mov_b32 m0, s83
	s_nop 0
	global_load_lds_dwordx4 v202, s[16:17]
	s_mov_b32 m0, s84
	s_nop 0
	global_load_lds_dwordx4 v198, s[16:17]
	s_mov_b32 m0, s39
	s_nop 0
	global_load_lds_dwordx4 v204, s[12:13]
	s_mov_b32 m0, s40
	s_nop 0
	global_load_lds_dwordx4 v200, s[12:13]
	s_waitcnt vmcnt(8)
	s_waitcnt lgkmcnt(0)
	s_barrier
	s_waitcnt lgkmcnt(0)
	v_mfma_f32_16x16x32_bf16 v[62:65], v[130:133], v[162:165], 0
	v_mfma_f32_16x16x32_bf16 v[54:57], v[138:141], v[162:165], 0
	v_mfma_f32_16x16x32_bf16 v[46:49], v[130:133], v[170:173], 0
	v_mfma_f32_16x16x32_bf16 v[38:41], v[138:141], v[170:173], 0
	v_mfma_f32_16x16x32_bf16 v[30:33], v[130:133], v[178:181], 0
	v_mfma_f32_16x16x32_bf16 v[22:25], v[138:141], v[178:181], 0
	v_mfma_f32_16x16x32_bf16 v[14:17], v[130:133], v[186:189], 0
	v_mfma_f32_16x16x32_bf16 v[6:9], v[138:141], v[186:189], 0
	v_mfma_f32_16x16x32_bf16 v[62:65], v[134:137], v[166:169], v[62:65]
	v_mfma_f32_16x16x32_bf16 v[54:57], v[142:145], v[166:169], v[54:57]
	v_mfma_f32_16x16x32_bf16 v[46:49], v[134:137], v[174:177], v[46:49]
	v_mfma_f32_16x16x32_bf16 v[38:41], v[142:145], v[174:177], v[38:41]
	v_mfma_f32_16x16x32_bf16 v[30:33], v[134:137], v[182:185], v[30:33]
	v_mfma_f32_16x16x32_bf16 v[22:25], v[142:145], v[182:185], v[22:25]
	v_mfma_f32_16x16x32_bf16 v[14:17], v[134:137], v[190:193], v[14:17]
	v_mfma_f32_16x16x32_bf16 v[6:9], v[142:145], v[190:193], v[6:9]
	v_mfma_f32_16x16x32_bf16 v[58:61], v[146:149], v[162:165], 0
	v_mfma_f32_16x16x32_bf16 v[50:53], v[154:157], v[162:165], 0
	v_mfma_f32_16x16x32_bf16 v[42:45], v[146:149], v[170:173], 0
	v_mfma_f32_16x16x32_bf16 v[34:37], v[154:157], v[170:173], 0
	v_mfma_f32_16x16x32_bf16 v[26:29], v[146:149], v[178:181], 0
	v_mfma_f32_16x16x32_bf16 v[18:21], v[154:157], v[178:181], 0
	v_mfma_f32_16x16x32_bf16 v[10:13], v[146:149], v[186:189], 0
	v_mfma_f32_16x16x32_bf16 v[2:5], v[154:157], v[186:189], 0
	v_mfma_f32_16x16x32_bf16 v[58:61], v[150:153], v[166:169], v[58:61]
	v_mfma_f32_16x16x32_bf16 v[50:53], v[158:161], v[166:169], v[50:53]
	v_mfma_f32_16x16x32_bf16 v[42:45], v[150:153], v[174:177], v[42:45]
	v_mfma_f32_16x16x32_bf16 v[34:37], v[158:161], v[174:177], v[34:37]
	v_mfma_f32_16x16x32_bf16 v[26:29], v[150:153], v[182:185], v[26:29]
	v_mfma_f32_16x16x32_bf16 v[18:21], v[158:161], v[182:185], v[18:21]
	v_mfma_f32_16x16x32_bf16 v[10:13], v[150:153], v[190:193], v[10:13]
	v_mfma_f32_16x16x32_bf16 v[2:5], v[158:161], v[190:193], v[2:5]
	s_barrier
	s_branch .Lpeel3_join
; #define PG8_STAGE(bufoff, gbase, voff) do { _Pragma("unroll") for (int _i = 0; _i < 2; ++_i) \
;         __builtin_amdgcn_global_load_lds((const unsigned*)((const char*)(gbase) + (voff)[_i]), (LAS unsigned*)(lds + (bufoff) + ldsw + _i * 8192), 16, 0, 0); } while (0)
; #define PG8_LDA(dst, b, h) do { _Pragma("unroll") for (int m = 0; m < 4; ++m) _Pragma("unroll") for (int k = 0; k < 2; ++k) dst[m][k] = *(const LAS bf16x8*)(lds + PG8_SA(b, h) + aoff + m * 2048 + k * 1024); } while (0)
; #define PG8_LDB(dst, b, h) do { _Pragma("unroll") for (int n = 0; n < 2; ++n) _Pragma("unroll") for (int k = 0; k < 2; ++k) dst[n][k] = *(const LAS bf16x8*)(lds + PG8_SB(b, h) + boff + n * 2048 + k * 1024); } while (0)
; #define PG8_MMA(ai, bj, At, Bt) do { __builtin_amdgcn_s_setprio(1); _Pragma("unroll") for (int m = 0; m < 4; ++m) _Pragma("unroll") for (int n = 0; n < 2; ++n) _Pragma("unroll") for (int k = 0; k < 2; ++k) \
;         acc[ai][bj][m][n] = __builtin_amdgcn_mfma_f32_16x16x32_bf16(Bt[n][k], At[m][k], acc[ai][bj][m][n], 0, 0, 0); __builtin_amdgcn_s_setprio(0); } while (0)
; template <class Epi, class Sched>
; __device__ __forceinline__ void gemm_phase(LAS unsigned char* lds, const int lda, const int ldb, const int K, const Sched& S, const Epi& E) {
;     ...
;             PG8_LDB(B0, 0, 0); PG8_LDB(B1, 0, 1); PG8_SCHED; PG8_LDA(At, 0, 0); PG8_STAGE(PG8_SA(1, 1), a1 + hstepA, voffA);
;             PG8_WAIT_V(8); PG8_WAIT_L(0); PG8_BAR; PG8_MMA(0, 0, At, B0); PG8_MMA(0, 1, At, B1); PG8_BAR; PG8_SCHED;
;             PG8_LDA(At, 0, 1); PG8_STAGE(PG8_SB(0, 0), b2, voffB); PG8_STAGE(PG8_SB(0, 1), b2 + hstepB, voffB); PG8_STAGE(PG8_SA(0, 0), a2, voffA);
;             PG8_WAIT_V(8); PG8_WAIT_L(0); PG8_BAR; PG8_MMA(1, 0, At, B0); PG8_MMA(1, 1, At, B1); PG8_BAR; PG8_SCHED;
;             PG8_LDB(B0, 1, 0); PG8_LDB(B1, 1, 1); PG8_SCHED; PG8_LDA(At, 1, 0); PG8_STAGE(PG8_SA(0, 1), a2 + hstepA, voffA);
;             PG8_WAIT_V(8); PG8_WAIT_L(0); PG8_BAR; PG8_MMA(0, 0, At, B0); PG8_MMA(0, 1, At, B1); PG8_BAR; PG8_SCHED;
;             PG8_LDA(At, 1, 1); PG8_STAGE(PG8_SB(1, 0), b3, voffB); PG8_STAGE(PG8_SB(1, 1), b3 + hstepB, voffB); PG8_STAGE(PG8_SA(1, 0), a3, voffA);
;             PG8_WAIT_V(8); PG8_WAIT_L(0); PG8_BAR;
;             if (last) E.pre(cur, wr, fr, rsv);
;             PG8_MMA(1, 0, At, B0); PG8_MMA(1, 1, At, B1); PG8_BAR; PG8_SCHED;
.LBB0_425:
	s_waitcnt lgkmcnt(0)
	v_mfma_f32_16x16x32_bf16 v[62:65], v[146:149], v[186:189], v[62:65]
	v_mfma_f32_16x16x32_bf16 v[54:57], v[154:157], v[186:189], v[54:57]
	v_mfma_f32_16x16x32_bf16 v[46:49], v[146:149], v[178:181], v[46:49]
	v_mfma_f32_16x16x32_bf16 v[38:41], v[154:157], v[178:181], v[38:41]
	v_mfma_f32_16x16x32_bf16 v[30:33], v[146:149], v[170:173], v[30:33]
	v_mfma_f32_16x16x32_bf16 v[22:25], v[154:157], v[170:173], v[22:25]
	v_mfma_f32_16x16x32_bf16 v[14:17], v[146:149], v[162:165], v[14:17]
	v_mfma_f32_16x16x32_bf16 v[6:9], v[154:157], v[162:165], v[6:9]
	v_mfma_f32_16x16x32_bf16 v[62:65], v[150:153], v[190:193], v[62:65]
	v_mfma_f32_16x16x32_bf16 v[54:57], v[158:161], v[190:193], v[54:57]
	v_mfma_f32_16x16x32_bf16 v[46:49], v[150:153], v[182:185], v[46:49]
	v_mfma_f32_16x16x32_bf16 v[38:41], v[158:161], v[182:185], v[38:41]
	v_mfma_f32_16x16x32_bf16 v[30:33], v[150:153], v[174:177], v[30:33]
	v_mfma_f32_16x16x32_bf16 v[22:25], v[158:161], v[174:177], v[22:25]
	v_mfma_f32_16x16x32_bf16 v[14:17], v[150:153], v[166:169], v[14:17]
	v_mfma_f32_16x16x32_bf16 v[6:9], v[158:161], v[166:169], v[6:9]
	v_mfma_f32_16x16x32_bf16 v[58:61], v[130:133], v[186:189], v[58:61]
	v_mfma_f32_16x16x32_bf16 v[50:53], v[138:141], v[186:189], v[50:53]
	v_mfma_f32_16x16x32_bf16 v[42:45], v[130:133], v[178:181], v[42:45]
	v_mfma_f32_16x16x32_bf16 v[34:37], v[138:141], v[178:181], v[34:37]
	v_mfma_f32_16x16x32_bf16 v[26:29], v[130:133], v[170:173], v[26:29]
	v_mfma_f32_16x16x32_bf16 v[18:21], v[138:141], v[170:173], v[18:21]
	v_mfma_f32_16x16x32_bf16 v[10:13], v[130:133], v[162:165], v[10:13]
	v_mfma_f32_16x16x32_bf16 v[2:5], v[138:141], v[162:165], v[2:5]
	v_mfma_f32_16x16x32_bf16 v[58:61], v[134:137], v[190:193], v[58:61]
	v_mfma_f32_16x16x32_bf16 v[50:53], v[142:145], v[190:193], v[50:53]
	v_mfma_f32_16x16x32_bf16 v[42:45], v[134:137], v[182:185], v[42:45]
	v_mfma_f32_16x16x32_bf16 v[34:37], v[142:145], v[182:185], v[34:37]
	v_mfma_f32_16x16x32_bf16 v[26:29], v[134:137], v[174:177], v[26:29]
	v_mfma_f32_16x16x32_bf16 v[18:21], v[142:145], v[174:177], v[18:21]
	v_mfma_f32_16x16x32_bf16 v[10:13], v[134:137], v[166:169], v[10:13]
	v_mfma_f32_16x16x32_bf16 v[2:5], v[142:145], v[166:169], v[2:5]
	s_barrier
	s_add_i32 s69, s69, 2
	s_add_u32 s6, s6, 0x100
	s_addc_u32 s7, s7, 0
	s_add_u32 s5, s5, 0x100
	s_addc_u32 s51, s51, 0
	s_cmp_gt_u32 s69, 13
	s_cbranch_scc1 .LBB0_428
.LBB0_426:
	s_add_u32 s8, s6, 0xfffc0080
	s_addc_u32 s9, s7, -1
	s_cmp_eq_u32 s69, 12
	s_cselect_b32 s13, s71, s9
	s_cselect_b32 s12, s70, s8
	s_cselect_b32 s15, s73, s51
	s_cselect_b32 s14, s72, s5
	s_add_i32 s81, s63, s36
	ds_read_b128 v[130:133], v222
	ds_read_b128 v[134:137], v222 offset:1024
	ds_read_b128 v[138:141], v222 offset:2048
	ds_read_b128 v[142:145], v222 offset:3072
	ds_read_b128 v[146:149], v223
	ds_read_b128 v[150:153], v223 offset:1024
	ds_read_b128 v[154:157], v223 offset:2048
	ds_read_b128 v[158:161], v223 offset:3072
	s_add_i32 m0, s39, 0xc000
	s_add_i32 s80, s39, 0xe000
	s_add_i32 s82, s81, 0x2000
	s_add_u32 s16, s14, 0x40000
	s_addc_u32 s17, s15, 0
	s_add_i32 s83, s64, s36
	s_add_i32 s84, s83, 0x2000
	s_add_i32 s85, 0, 0x18000
	s_add_i32 s86, 0, 0x1c000
	s_add_u32 s10, s12, 0x40000
	s_addc_u32 s11, s13, 0
	s_add_i32 s75, s85, s36
	s_add_i32 s74, s75, 0x2000
	s_add_u32 s8, s14, 0x40080
	s_addc_u32 s9, s15, 0
	s_add_i32 s79, s86, s36
	s_add_i32 s78, s79, 0x2000
	s_cmp_lg_u32 s69, 12
	ds_read_b128 v[162:165], v224
	ds_read_b128 v[166:169], v224 offset:1024
	ds_read_b128 v[170:173], v224 offset:2048
	ds_read_b128 v[174:177], v224 offset:3072
	ds_read_b128 v[178:181], v224 offset:4096
	ds_read_b128 v[182:185], v224 offset:5120
	ds_read_b128 v[186:189], v224 offset:6144
	ds_read_b128 v[190:193], v224 offset:7168
	global_load_lds_dwordx4 v212, s[6:7]
	s_mov_b32 m0, s80
	s_nop 0
	global_load_lds_dwordx4 v214, s[6:7]
	s_waitcnt vmcnt(8)
	s_waitcnt lgkmcnt(0)
	s_barrier
	s_waitcnt lgkmcnt(0)
	v_mfma_f32_16x16x32_bf16 v[126:129], v[130:133], v[162:165], v[126:129]
	v_mfma_f32_16x16x32_bf16 v[118:121], v[138:141], v[162:165], v[118:121]
	v_mfma_f32_16x16x32_bf16 v[110:113], v[130:133], v[170:173], v[110:113]
	v_mfma_f32_16x16x32_bf16 v[102:105], v[138:141], v[170:173], v[102:105]
	v_mfma_f32_16x16x32_bf16 v[94:97], v[130:133], v[178:181], v[94:97]
	v_mfma_f32_16x16x32_bf16 v[86:89], v[138:141], v[178:181], v[86:89]
	v_mfma_f32_16x16x32_bf16 v[78:81], v[130:133], v[186:189], v[78:81]
	v_mfma_f32_16x16x32_bf16 v[70:73], v[138:141], v[186:189], v[70:73]
	v_mfma_f32_16x16x32_bf16 v[126:129], v[134:137], v[166:169], v[126:129]
	v_mfma_f32_16x16x32_bf16 v[118:121], v[142:145], v[166:169], v[118:121]
	v_mfma_f32_16x16x32_bf16 v[110:113], v[134:137], v[174:177], v[110:113]
	v_mfma_f32_16x16x32_bf16 v[102:105], v[142:145], v[174:177], v[102:105]
	v_mfma_f32_16x16x32_bf16 v[94:97], v[134:137], v[182:185], v[94:97]
	v_mfma_f32_16x16x32_bf16 v[86:89], v[142:145], v[182:185], v[86:89]
	v_mfma_f32_16x16x32_bf16 v[78:81], v[134:137], v[190:193], v[78:81]
	v_mfma_f32_16x16x32_bf16 v[70:73], v[142:145], v[190:193], v[70:73]
	v_mfma_f32_16x16x32_bf16 v[122:125], v[146:149], v[162:165], v[122:125]
	v_mfma_f32_16x16x32_bf16 v[114:117], v[154:157], v[162:165], v[114:117]
	v_mfma_f32_16x16x32_bf16 v[106:109], v[146:149], v[170:173], v[106:109]
	v_mfma_f32_16x16x32_bf16 v[98:101], v[154:157], v[170:173], v[98:101]
	v_mfma_f32_16x16x32_bf16 v[90:93], v[146:149], v[178:181], v[90:93]
	v_mfma_f32_16x16x32_bf16 v[82:85], v[154:157], v[178:181], v[82:85]
	v_mfma_f32_16x16x32_bf16 v[74:77], v[146:149], v[186:189], v[74:77]
	v_mfma_f32_16x16x32_bf16 v[66:69], v[154:157], v[186:189], v[66:69]
	v_mfma_f32_16x16x32_bf16 v[122:125], v[150:153], v[166:169], v[122:125]
	v_mfma_f32_16x16x32_bf16 v[114:117], v[158:161], v[166:169], v[114:117]
	v_mfma_f32_16x16x32_bf16 v[106:109], v[150:153], v[174:177], v[106:109]
	v_mfma_f32_16x16x32_bf16 v[98:101], v[158:161], v[174:177], v[98:101]
	v_mfma_f32_16x16x32_bf16 v[90:93], v[150:153], v[182:185], v[90:93]
	v_mfma_f32_16x16x32_bf16 v[82:85], v[158:161], v[182:185], v[82:85]
	v_mfma_f32_16x16x32_bf16 v[74:77], v[150:153], v[190:193], v[74:77]
	v_mfma_f32_16x16x32_bf16 v[66:69], v[158:161], v[190:193], v[66:69]
	s_barrier
; #define PG8_STAGE(bufoff, gbase, voff) do { _Pragma("unroll") for (int _i = 0; _i < 2; ++_i) \
;         __builtin_amdgcn_global_load_lds((const unsigned*)((const char*)(gbase) + (voff)[_i]), (LAS unsigned*)(lds + (bufoff) + ldsw + _i * 8192), 16, 0, 0); } while (0)
; #define PG8_LDA(dst, b, h) do { _Pragma("unroll") for (int m = 0; m < 4; ++m) _Pragma("unroll") for (int k = 0; k < 2; ++k) dst[m][k] = *(const LAS bf16x8*)(lds + PG8_SA(b, h) + aoff + m * 2048 + k * 1024); } while (0)
; #define PG8_MMA(ai, bj, At, Bt) do { __builtin_amdgcn_s_setprio(1); _Pragma("unroll") for (int m = 0; m < 4; ++m) _Pragma("unroll") for (int n = 0; n < 2; ++n) _Pragma("unroll") for (int k = 0; k < 2; ++k) \
;         acc[ai][bj][m][n] = __builtin_amdgcn_mfma_f32_16x16x32_bf16(Bt[n][k], At[m][k], acc[ai][bj][m][n], 0, 0, 0); __builtin_amdgcn_s_setprio(0); } while (0)
; #define PG8_WAIT_V(n) asm volatile("s_waitcnt vmcnt(" #n ")" ::: "memory")
; #define PG8_WAIT_L(n) asm volatile("s_waitcnt lgkmcnt(" #n ")" ::: "memory")
; #define PG8_BAR __builtin_amdgcn_s_barrier()
; #define PG8_SCHED __builtin_amdgcn_sched_barrier(0)
; template <class Epi, class Sched>
; __device__ __forceinline__ void gemm_phase(LAS unsigned char* lds, const int lda, const int ldb, const int K, const Sched& S, const Epi& E) {
;     ...
;             PG8_LDA(At, 0, 1); PG8_STAGE(PG8_SB(0, 0), b2, voffB); PG8_STAGE(PG8_SB(0, 1), b2 + hstepB, voffB); PG8_STAGE(PG8_SA(0, 0), a2, voffA);
;             PG8_WAIT_V(8); PG8_WAIT_L(0); PG8_BAR; PG8_MMA(1, 0, At, B0); PG8_MMA(1, 1, At, B1); PG8_BAR; PG8_SCHED;
	s_mov_b32 m0, s81
	ds_read_b128 v[162:165], v224 offset:16384
	ds_read_b128 v[166:169], v224 offset:17408
	ds_read_b128 v[170:173], v224 offset:18432
	ds_read_b128 v[174:177], v224 offset:19456
	ds_read_b128 v[178:181], v224 offset:20480
	ds_read_b128 v[182:185], v224 offset:21504
	ds_read_b128 v[186:189], v224 offset:22528
	ds_read_b128 v[190:193], v224 offset:23552
	global_load_lds_dwordx4 v202, s[14:15]
	s_mov_b32 m0, s82
	s_nop 0
	global_load_lds_dwordx4 v198, s[14:15]
	s_mov_b32 m0, s83
	s_nop 0
	global_load_lds_dwordx4 v202, s[16:17]
	s_mov_b32 m0, s84
	s_nop 0
	global_load_lds_dwordx4 v198, s[16:17]
	s_mov_b32 m0, s39
	s_nop 0
	global_load_lds_dwordx4 v204, s[12:13]
	s_mov_b32 m0, s40
	s_nop 0
	global_load_lds_dwordx4 v200, s[12:13]
	s_waitcnt vmcnt(8)
	s_waitcnt lgkmcnt(0)
	s_barrier
	s_waitcnt lgkmcnt(0)
	v_mfma_f32_16x16x32_bf16 v[62:65], v[130:133], v[162:165], v[62:65]
	v_mfma_f32_16x16x32_bf16 v[54:57], v[138:141], v[162:165], v[54:57]
	v_mfma_f32_16x16x32_bf16 v[46:49], v[130:133], v[170:173], v[46:49]
	v_mfma_f32_16x16x32_bf16 v[38:41], v[138:141], v[170:173], v[38:41]
	v_mfma_f32_16x16x32_bf16 v[30:33], v[130:133], v[178:181], v[30:33]
	v_mfma_f32_16x16x32_bf16 v[22:25], v[138:141], v[178:181], v[22:25]
	v_mfma_f32_16x16x32_bf16 v[14:17], v[130:133], v[186:189], v[14:17]
	v_mfma_f32_16x16x32_bf16 v[6:9], v[138:141], v[186:189], v[6:9]
	v_mfma_f32_16x16x32_bf16 v[62:65], v[134:137], v[166:169], v[62:65]
	v_mfma_f32_16x16x32_bf16 v[54:57], v[142:145], v[166:169], v[54:57]
	v_mfma_f32_16x16x32_bf16 v[46:49], v[134:137], v[174:177], v[46:49]
	v_mfma_f32_16x16x32_bf16 v[38:41], v[142:145], v[174:177], v[38:41]
	v_mfma_f32_16x16x32_bf16 v[30:33], v[134:137], v[182:185], v[30:33]
	v_mfma_f32_16x16x32_bf16 v[22:25], v[142:145], v[182:185], v[22:25]
	v_mfma_f32_16x16x32_bf16 v[14:17], v[134:137], v[190:193], v[14:17]
	v_mfma_f32_16x16x32_bf16 v[6:9], v[142:145], v[190:193], v[6:9]
	v_mfma_f32_16x16x32_bf16 v[58:61], v[146:149], v[162:165], v[58:61]
	v_mfma_f32_16x16x32_bf16 v[50:53], v[154:157], v[162:165], v[50:53]
	v_mfma_f32_16x16x32_bf16 v[42:45], v[146:149], v[170:173], v[42:45]
	v_mfma_f32_16x16x32_bf16 v[34:37], v[154:157], v[170:173], v[34:37]
	v_mfma_f32_16x16x32_bf16 v[26:29], v[146:149], v[178:181], v[26:29]
	v_mfma_f32_16x16x32_bf16 v[18:21], v[154:157], v[178:181], v[18:21]
	v_mfma_f32_16x16x32_bf16 v[10:13], v[146:149], v[186:189], v[10:13]
	v_mfma_f32_16x16x32_bf16 v[2:5], v[154:157], v[186:189], v[2:5]
	v_mfma_f32_16x16x32_bf16 v[58:61], v[150:153], v[166:169], v[58:61]
	v_mfma_f32_16x16x32_bf16 v[50:53], v[158:161], v[166:169], v[50:53]
	v_mfma_f32_16x16x32_bf16 v[42:45], v[150:153], v[174:177], v[42:45]
	v_mfma_f32_16x16x32_bf16 v[34:37], v[158:161], v[174:177], v[34:37]
	v_mfma_f32_16x16x32_bf16 v[26:29], v[150:153], v[182:185], v[26:29]
	v_mfma_f32_16x16x32_bf16 v[18:21], v[158:161], v[182:185], v[18:21]
	v_mfma_f32_16x16x32_bf16 v[10:13], v[150:153], v[190:193], v[10:13]
	v_mfma_f32_16x16x32_bf16 v[2:5], v[158:161], v[190:193], v[2:5]
	s_barrier
; #define PG8_STAGE(bufoff, gbase, voff) do { _Pragma("unroll") for (int _i = 0; _i < 2; ++_i) \
;         __builtin_amdgcn_global_load_lds((const unsigned*)((const char*)(gbase) + (voff)[_i]), (LAS unsigned*)(lds + (bufoff) + ldsw + _i * 8192), 16, 0, 0); } while (0)
; #define PG8_LDA(dst, b, h) do { _Pragma("unroll") for (int m = 0; m < 4; ++m) _Pragma("unroll") for (int k = 0; k < 2; ++k) dst[m][k] = *(const LAS bf16x8*)(lds + PG8_SA(b, h) + aoff + m * 2048 + k * 1024); } while (0)
; #define PG8_LDB(dst, b, h) do { _Pragma("unroll") for (int n = 0; n < 2; ++n) _Pragma("unroll") for (int k = 0; k < 2; ++k) dst[n][k] = *(const LAS bf16x8*)(lds + PG8_SB(b, h) + boff + n * 2048 + k * 1024); } while (0)
; #define PG8_MMA(ai, bj, At, Bt) do { __builtin_amdgcn_s_setprio(1); _Pragma("unroll") for (int m = 0; m < 4; ++m) _Pragma("unroll") for (int n = 0; n < 2; ++n) _Pragma("unroll") for (int k = 0; k < 2; ++k) \
;         acc[ai][bj][m][n] = __builtin_amdgcn_mfma_f32_16x16x32_bf16(Bt[n][k], At[m][k], acc[ai][bj][m][n], 0, 0, 0); __builtin_amdgcn_s_setprio(0); } while (0)
; #define PG8_WAIT_V(n) asm volatile("s_waitcnt vmcnt(" #n ")" ::: "memory")
; #define PG8_WAIT_L(n) asm volatile("s_waitcnt lgkmcnt(" #n ")" ::: "memory")
; #define PG8_BAR __builtin_amdgcn_s_barrier()
; #define PG8_SCHED __builtin_amdgcn_sched_barrier(0)
; template <class Epi, class Sched>
; __device__ __forceinline__ void gemm_phase(LAS unsigned char* lds, const int lda, const int ldb, const int K, const Sched& S, const Epi& E) {
;     ...
;             PG8_LDB(B0, 1, 0); PG8_LDB(B1, 1, 1); PG8_SCHED; PG8_LDA(At, 1, 0); PG8_STAGE(PG8_SA(0, 1), a2 + hstepA, voffA);
;             PG8_WAIT_V(8); PG8_WAIT_L(0); PG8_BAR; PG8_MMA(0, 0, At, B0); PG8_MMA(0, 1, At, B1); PG8_BAR; PG8_SCHED;
;             PG8_LDA(At, 1, 1); PG8_STAGE(PG8_SB(1, 0), b3, voffB); PG8_STAGE(PG8_SB(1, 1), b3 + hstepB, voffB); PG8_STAGE(PG8_SA(1, 0), a3, voffA);
;             PG8_WAIT_V(8); PG8_WAIT_L(0); PG8_BAR;
;             if (last) E.pre(cur, wr, fr, rsv);
;     __device__ __forceinline__ void pre(const pg8::Unit& u, int wr, int fr, float (&rsv)[8]) const {
;         const float* p = ss + u.pm * 256 + wr * 64 + fr;
; #pragma unroll
;         for (int ai = 0; ai < 2; ++ai)
; #pragma unroll
;             for (int m = 0; m < 4; ++m) rsv[ai * 4 + m] = p[ai * 128 + m * 16];
;     }
.Lpeel3_join:
	v_add_u32_e32 v130, s85, v195
	v_add_u32_e32 v142, s86, v195
	ds_read_b128 v[146:149], v130
	ds_read_b128 v[150:153], v130 offset:1024
	ds_read_b128 v[154:157], v130 offset:2048
	ds_read_b128 v[158:161], v130 offset:3072
	ds_read_b128 v[130:133], v142
	ds_read_b128 v[134:137], v142 offset:1024
	ds_read_b128 v[138:141], v142 offset:2048
	ds_read_b128 v[142:145], v142 offset:3072
	s_mov_b32 m0, s41
	ds_read_b128 v[162:165], v224 offset:32768
	ds_read_b128 v[166:169], v224 offset:33792
	ds_read_b128 v[170:173], v224 offset:34816
	ds_read_b128 v[174:177], v224 offset:35840
	ds_read_b128 v[178:181], v224 offset:36864
	ds_read_b128 v[182:185], v224 offset:37888
	ds_read_b128 v[186:189], v224 offset:38912
	ds_read_b128 v[190:193], v224 offset:39936
	global_load_lds_dwordx4 v204, s[10:11]
	s_mov_b32 m0, s42
	s_nop 0
	global_load_lds_dwordx4 v200, s[10:11]
	s_waitcnt vmcnt(8)
	s_waitcnt lgkmcnt(0)
	s_barrier
	s_waitcnt lgkmcnt(0)
	v_mfma_f32_16x16x32_bf16 v[126:129], v[146:149], v[162:165], v[126:129]
	v_mfma_f32_16x16x32_bf16 v[118:121], v[154:157], v[162:165], v[118:121]
	v_mfma_f32_16x16x32_bf16 v[110:113], v[146:149], v[170:173], v[110:113]
	v_mfma_f32_16x16x32_bf16 v[102:105], v[154:157], v[170:173], v[102:105]
	v_mfma_f32_16x16x32_bf16 v[94:97], v[146:149], v[178:181], v[94:97]
	v_mfma_f32_16x16x32_bf16 v[86:89], v[154:157], v[178:181], v[86:89]
	v_mfma_f32_16x16x32_bf16 v[78:81], v[146:149], v[186:189], v[78:81]
	v_mfma_f32_16x16x32_bf16 v[70:73], v[154:157], v[186:189], v[70:73]
	v_mfma_f32_16x16x32_bf16 v[126:129], v[150:153], v[166:169], v[126:129]
	v_mfma_f32_16x16x32_bf16 v[118:121], v[158:161], v[166:169], v[118:121]
	v_mfma_f32_16x16x32_bf16 v[110:113], v[150:153], v[174:177], v[110:113]
	v_mfma_f32_16x16x32_bf16 v[102:105], v[158:161], v[174:177], v[102:105]
	v_mfma_f32_16x16x32_bf16 v[94:97], v[150:153], v[182:185], v[94:97]
	v_mfma_f32_16x16x32_bf16 v[86:89], v[158:161], v[182:185], v[86:89]
	v_mfma_f32_16x16x32_bf16 v[78:81], v[150:153], v[190:193], v[78:81]
	v_mfma_f32_16x16x32_bf16 v[70:73], v[158:161], v[190:193], v[70:73]
	v_mfma_f32_16x16x32_bf16 v[122:125], v[130:133], v[162:165], v[122:125]
	v_mfma_f32_16x16x32_bf16 v[114:117], v[138:141], v[162:165], v[114:117]
	v_mfma_f32_16x16x32_bf16 v[106:109], v[130:133], v[170:173], v[106:109]
	v_mfma_f32_16x16x32_bf16 v[98:101], v[138:141], v[170:173], v[98:101]
	v_mfma_f32_16x16x32_bf16 v[90:93], v[130:133], v[178:181], v[90:93]
	v_mfma_f32_16x16x32_bf16 v[82:85], v[138:141], v[178:181], v[82:85]
	v_mfma_f32_16x16x32_bf16 v[74:77], v[130:133], v[186:189], v[74:77]
	v_mfma_f32_16x16x32_bf16 v[66:69], v[138:141], v[186:189], v[66:69]
	v_mfma_f32_16x16x32_bf16 v[122:125], v[134:137], v[166:169], v[122:125]
	v_mfma_f32_16x16x32_bf16 v[114:117], v[142:145], v[166:169], v[114:117]
	v_mfma_f32_16x16x32_bf16 v[106:109], v[134:137], v[174:177], v[106:109]
	v_mfma_f32_16x16x32_bf16 v[98:101], v[142:145], v[174:177], v[98:101]
	v_mfma_f32_16x16x32_bf16 v[90:93], v[134:137], v[182:185], v[90:93]
	v_mfma_f32_16x16x32_bf16 v[82:85], v[142:145], v[182:185], v[82:85]
	v_mfma_f32_16x16x32_bf16 v[74:77], v[134:137], v[190:193], v[74:77]
	v_mfma_f32_16x16x32_bf16 v[66:69], v[142:145], v[190:193], v[66:69]
	s_barrier
	s_mov_b32 m0, s75
	ds_read_b128 v[186:189], v224 offset:49152
	ds_read_b128 v[190:193], v224 offset:50176
	ds_read_b128 v[178:181], v224 offset:51200
	ds_read_b128 v[182:185], v224 offset:52224
	ds_read_b128 v[170:173], v224 offset:53248
	ds_read_b128 v[174:177], v224 offset:54272
	ds_read_b128 v[162:165], v224 offset:55296
	ds_read_b128 v[166:169], v224 offset:56320
	global_load_lds_dwordx4 v234, s[14:15]
	s_mov_b32 m0, s74
	s_nop 0
	global_load_lds_dwordx4 v235, s[14:15]
	s_mov_b32 m0, s79
	s_nop 0
	global_load_lds_dwordx4 v202, s[8:9]
	s_mov_b32 m0, s78
	s_nop 0
	global_load_lds_dwordx4 v198, s[8:9]
	s_mov_b32 m0, s43
	s_nop 0
	global_load_lds_dwordx4 v236, s[12:13]
	s_mov_b32 m0, s44
	s_nop 0
	global_load_lds_dwordx4 v237, s[12:13]
	s_waitcnt vmcnt(8)
	s_waitcnt lgkmcnt(0)
	s_barrier
	s_cbranch_scc1 .LBB0_425
	global_load_dword v233, v[220:221], off
	global_load_dword v232, v[220:221], off offset:64
	global_load_dword v231, v[220:221], off offset:128
	global_load_dword v230, v[220:221], off offset:192
	global_load_dword v229, v[220:221], off offset:512
	global_load_dword v228, v[220:221], off offset:576
	global_load_dword v227, v[220:221], off offset:640
	global_load_dword v226, v[220:221], off offset:704
	s_branch .LBB0_425

; #define PG8_STAGE(bufoff, gbase, voff) do { _Pragma("unroll") for (int _i = 0; _i < 2; ++_i) \
;         __builtin_amdgcn_global_load_lds((const unsigned*)((const char*)(gbase) + (voff)[_i]), (LAS unsigned*)(lds + (bufoff) + ldsw + _i * 8192), 16, 0, 0); } while (0)
; #define PG8_BAR __builtin_amdgcn_s_barrier()
; template <class Epi, class Sched>
; __device__ __forceinline__ void gemm_phase(LAS unsigned char* lds, const int lda, const int ldb, const int K, const Sched& S, const Epi& E) {
;     const int tid = threadIdx.x, wid = __builtin_amdgcn_readfirstlane(tid >> 6), lane = tid & 63, wr = wid >> 2, wc = wid & 3, fr = lane & 15, fq = lane >> 4;
;     const int nt = K / BK;
;     unsigned voffA[2], voffB[2];
; #pragma unroll
;     for (int i = 0; i < 2; ++i) { int R, C; stage_rc(tid * 16 + i * 8192, R, C); const int Rb = (R & ~31) + perm32(R & 31);
;         voffA[i] = (unsigned)(R * lda + C) * 2u; voffB[i] = (unsigned)(Rb * ldb + C) * 2u; }
;     const size_t kstep = (size_t)(BK * 2);
;     const size_t hstepA = (size_t)HALF * lda * 2, hstepB = (size_t)HALF * ldb * 2;
;     const unsigned ldsw = (unsigned)wid * 1024u;
;     const int aoff = lds_byte(wr * 64 + fr, fq * 8), boff = lds_byte(wc * 32 + fr, fq * 8);
;     ...
;     Unit cur, nxt; int ui = 0;
;     if (!S.next(0, cur)) return;
;     f32x4 acc[2][2][4][2];
; #pragma unroll
;     for (int a = 0; a < 2; ++a)
; #pragma unroll
;         for (int b = 0; b < 2; ++b)
; #pragma unroll
;             for (int m = 0; m < 4; ++m)
; #pragma unroll
;                 for (int n = 0; n < 2; ++n) acc[a][b][m][n] = (f32x4){0.f, 0.f, 0.f, 0.f};
;     bf16x8 At[4][2], B0[2][2], B1[2][2];
;     float rsv[8];
; #pragma unroll
;     for (int i = 0; i < 8; ++i) rsv[i] = 0.f;
;     const char* cA = cur.A; const char* cB = cur.B;
;     PG8_STAGE(PG8_SB(0, 0), cB, voffB); PG8_STAGE(PG8_SB(0, 1), cB + hstepB, voffB); PG8_STAGE(PG8_SA(0, 0), cA, voffA); PG8_STAGE(PG8_SA(0, 1), cA + hstepA, voffA);
;     if (wr == 1) PG8_BAR;
.LBB0_831:
	v_lshrrev_b32_e32 v5, 1, v194
	v_and_b32_e32 v13, 24, v5
	v_lshrrev_b32_e32 v5, 5, v194
	v_and_b32_e32 v5, 4, v5
	v_bfe_u32 v6, v194, 2, 2
	v_lshlrev_b32_e32 v1, 4, v194
	v_and_b32_e32 v2, 32, v194
	v_bfe_u32 v4, v194, 2, 4
	v_or3_b32 v5, v5, v6, v13
	v_lshrrev_b32_e32 v6, 3, v194
	s_movk_i32 s1, 0x70
	s_waitcnt lgkmcnt(0)
	v_bitop3_b32 v3, v1, v2, 48 bitop3:0x6c
	v_and_or_b32 v7, v6, s1, v4
	s_movk_i32 s1, 0x60
	v_add_u32_e32 v1, 0x2000, v1
	v_and_or_b32 v6, v6, s1, v5
	v_lshrrev_b32_e32 v1, 7, v1
	s_movk_i32 s1, 0xf0
	v_and_or_b32 v4, v1, s1, v4
	s_movk_i32 s1, 0xe0
	v_and_or_b32 v1, v1, s1, v5
	s_lshr_b32 s1, s12, 6
	v_and_b32_e32 v12, 64, v194
	s_lshl_b32 s27, s1, 10
	v_or_b32_e32 v2, v3, v12
	s_add_i32 s28, s27, 0
	v_lshl_or_b32 v172, v6, 10, v2
	s_add_i32 m0, s28, 0x10000
	s_lshr_b32 s0, s12, 8
	global_load_lds_dwordx4 v172, s[20:21]
	s_add_i32 m0, s28, 0x12000
	v_lshl_or_b32 v176, v1, 10, v2
	s_add_u32 s8, s20, 0x20000
	global_load_lds_dwordx4 v176, s[20:21]
	s_addc_u32 s9, s21, 0
	s_add_i32 m0, s28, 0x14000
	v_mul_u32_u24_e32 v14, 0x1600, v7
	global_load_lds_dwordx4 v172, s[8:9]
	s_add_i32 m0, s28, 0x16000
	s_add_i32 s29, s28, 0x2000
	v_or_b32_e32 v170, v2, v14
	v_mul_u32_u24_e32 v15, 0x1600, v4
	global_load_lds_dwordx4 v176, s[8:9]
	s_mov_b32 m0, s28
	s_add_u32 s8, s4, 0xb0000
	v_or_b32_e32 v174, v15, v2
	global_load_lds_dwordx4 v170, s[4:5]
	s_mov_b32 m0, s29
	s_addc_u32 s9, s5, 0
	s_add_i32 s30, s28, 0x4000
	global_load_lds_dwordx4 v174, s[4:5]
	s_mov_b32 m0, s30
	s_add_i32 s31, s28, 0x6000
	global_load_lds_dwordx4 v170, s[8:9]
	s_mov_b32 m0, s31
	v_mov_b32_e32 v2, 0
	global_load_lds_dwordx4 v174, s[8:9]
	v_mov_b32_e32 v173, v2
	v_mov_b32_e32 v177, v2
	v_mov_b32_e32 v171, v2
	v_mov_b32_e32 v175, v2
	s_cmp_eq_u32 s0, 1
	v_lshl_add_u64 v[10:11], s[20:21], 0, v[172:173]
	v_lshl_add_u64 v[8:9], s[20:21], 0, v[176:177]
	v_lshl_add_u64 v[4:5], s[4:5], 0, v[170:171]
	s_cselect_b64 s[8:9], -1, 0
	s_cmp_lg_u32 s0, 1
	v_lshl_add_u64 v[6:7], s[4:5], 0, v[174:175]
	s_cbranch_scc1 .LBB0_833
	s_setprio 1
	s_barrier

; #define PG8_STAGE(bufoff, gbase, voff) do { _Pragma("unroll") for (int _i = 0; _i < 2; ++_i) \
;         __builtin_amdgcn_global_load_lds((const unsigned*)((const char*)(gbase) + (voff)[_i]), (LAS unsigned*)(lds + (bufoff) + ldsw + _i * 8192), 16, 0, 0); } while (0)
; #define PG8_LDA(dst, b, h) do { _Pragma("unroll") for (int m = 0; m < 4; ++m) _Pragma("unroll") for (int k = 0; k < 2; ++k) dst[m][k] = *(const LAS bf16x8*)(lds + PG8_SA(b, h) + aoff + m * 2048 + k * 1024); } while (0)
; #define PG8_LDB(dst, b, h) do { _Pragma("unroll") for (int n = 0; n < 2; ++n) _Pragma("unroll") for (int k = 0; k < 2; ++k) dst[n][k] = *(const LAS bf16x8*)(lds + PG8_SB(b, h) + boff + n * 2048 + k * 1024); } while (0)
; #define PG8_MMA(ai, bj, At, Bt) do { __builtin_amdgcn_s_setprio(1); _Pragma("unroll") for (int m = 0; m < 4; ++m) _Pragma("unroll") for (int n = 0; n < 2; ++n) _Pragma("unroll") for (int k = 0; k < 2; ++k) \
;         acc[ai][bj][m][n] = __builtin_amdgcn_mfma_f32_16x16x32_bf16(Bt[n][k], At[m][k], acc[ai][bj][m][n], 0, 0, 0); __builtin_amdgcn_s_setprio(0); } while (0)
; #define PG8_WAIT_V(n) asm volatile("s_waitcnt vmcnt(" #n ")" ::: "memory")
; #define PG8_WAIT_L(n) asm volatile("s_waitcnt lgkmcnt(" #n ")" ::: "memory")
; #define PG8_BAR __builtin_amdgcn_s_barrier()
; #define PG8_SCHED __builtin_amdgcn_sched_barrier(0)
; template <class Epi, class Sched>
; __device__ __forceinline__ void gemm_phase(LAS unsigned char* lds, const int lda, const int ldb, const int K, const Sched& S, const Epi& E) {
;     ...
;             PG8_LDB(B0, 0, 0); PG8_LDB(B1, 0, 1); PG8_SCHED; PG8_LDA(At, 0, 0); PG8_STAGE(PG8_SA(1, 1), a1 + hstepA, voffA);
;             PG8_WAIT_V(8); PG8_WAIT_L(0); PG8_BAR; PG8_MMA(0, 0, At, B0); PG8_MMA(0, 1, At, B1); PG8_BAR; PG8_SCHED;
;             PG8_LDA(At, 0, 1); PG8_STAGE(PG8_SB(0, 0), b2, voffB); PG8_STAGE(PG8_SB(0, 1), b2 + hstepB, voffB); PG8_STAGE(PG8_SA(0, 0), a2, voffA);
;             PG8_WAIT_V(8); PG8_WAIT_L(0); PG8_BAR; PG8_MMA(1, 0, At, B0); PG8_MMA(1, 1, At, B1); PG8_BAR; PG8_SCHED;
.LBB0_839:
	v_add_u32_e32 v3, s43, v195
	ds_read_b128 v[62:65], v3
	ds_read_b128 v[66:69], v3 offset:1024
	ds_read_b128 v[86:89], v3 offset:2048
	ds_read_b128 v[90:93], v3 offset:3072
	v_add_u32_e32 v3, s44, v195
	ds_read_b128 v[110:113], v3
	ds_read_b128 v[114:117], v3 offset:1024
	ds_read_b128 v[142:145], v3 offset:2048
	ds_read_b128 v[146:149], v3 offset:3072
	s_add_u32 s20, s4, 0xfff50080
	s_addc_u32 s21, s5, -1
	s_cmp_eq_u32 s64, 4
	s_cselect_b32 s23, s17, s21
	s_cselect_b32 s22, s16, s20
	s_cselect_b32 s21, s19, s63
	s_cselect_b32 s20, s18, s15
	s_add_i32 m0, s28, 0xc000
	ds_read_b128 v[166:169], v201
	ds_read_b128 v[186:189], v201 offset:1024
	ds_read_b128 v[190:193], v201 offset:2048
	ds_read_b128 v[196:199], v201 offset:3072
	ds_read_b128 v[202:205], v201 offset:4096
	ds_read_b128 v[206:209], v201 offset:5120
	ds_read_b128 v[210:213], v201 offset:6144
	ds_read_b128 v[214:217], v201 offset:7168
	global_load_lds_dwordx4 v178, s[4:5]
	s_add_i32 m0, s28, 0xe000
	s_nop 0
	global_load_lds_dwordx4 v180, s[4:5]
	s_waitcnt vmcnt(8)
	s_waitcnt lgkmcnt(0)
	s_barrier
	s_waitcnt lgkmcnt(0)
	v_mfma_f32_16x16x32_bf16 v[74:77], v[62:65], v[166:169], v[74:77]
	v_mfma_f32_16x16x32_bf16 v[70:73], v[86:89], v[166:169], v[70:73]
	v_mfma_f32_16x16x32_bf16 v[106:109], v[62:65], v[190:193], v[106:109]
	v_mfma_f32_16x16x32_bf16 v[102:105], v[86:89], v[190:193], v[102:105]
	v_mfma_f32_16x16x32_bf16 v[138:141], v[62:65], v[202:205], v[138:141]
	v_mfma_f32_16x16x32_bf16 v[126:129], v[86:89], v[202:205], v[126:129]
	v_mfma_f32_16x16x32_bf16 v[122:125], v[62:65], v[210:213], v[122:125]
	v_mfma_f32_16x16x32_bf16 v[118:121], v[86:89], v[210:213], v[118:121]
	v_mfma_f32_16x16x32_bf16 v[74:77], v[66:69], v[186:189], v[74:77]
	v_mfma_f32_16x16x32_bf16 v[70:73], v[90:93], v[186:189], v[70:73]
	v_mfma_f32_16x16x32_bf16 v[106:109], v[66:69], v[196:199], v[106:109]
	v_mfma_f32_16x16x32_bf16 v[102:105], v[90:93], v[196:199], v[102:105]
	v_mfma_f32_16x16x32_bf16 v[138:141], v[66:69], v[206:209], v[138:141]
	v_mfma_f32_16x16x32_bf16 v[126:129], v[90:93], v[206:209], v[126:129]
	v_mfma_f32_16x16x32_bf16 v[122:125], v[66:69], v[214:217], v[122:125]
	v_mfma_f32_16x16x32_bf16 v[118:121], v[90:93], v[214:217], v[118:121]
	v_mfma_f32_16x16x32_bf16 v[162:165], v[110:113], v[166:169], v[162:165]
	v_mfma_f32_16x16x32_bf16 v[158:161], v[142:145], v[166:169], v[158:161]
	v_mfma_f32_16x16x32_bf16 v[154:157], v[110:113], v[190:193], v[154:157]
	v_mfma_f32_16x16x32_bf16 v[150:153], v[142:145], v[190:193], v[150:153]
	v_mfma_f32_16x16x32_bf16 v[134:137], v[110:113], v[202:205], v[134:137]
	v_mfma_f32_16x16x32_bf16 v[130:133], v[142:145], v[202:205], v[130:133]
	v_mfma_f32_16x16x32_bf16 v[98:101], v[110:113], v[210:213], v[98:101]
	v_mfma_f32_16x16x32_bf16 v[94:97], v[142:145], v[210:213], v[94:97]
	v_mfma_f32_16x16x32_bf16 v[162:165], v[114:117], v[186:189], v[162:165]
	v_mfma_f32_16x16x32_bf16 v[158:161], v[146:149], v[186:189], v[158:161]
	v_mfma_f32_16x16x32_bf16 v[154:157], v[114:117], v[196:199], v[154:157]
	v_mfma_f32_16x16x32_bf16 v[150:153], v[146:149], v[196:199], v[150:153]
	v_mfma_f32_16x16x32_bf16 v[134:137], v[114:117], v[206:209], v[134:137]
	v_mfma_f32_16x16x32_bf16 v[130:133], v[146:149], v[206:209], v[130:133]
	v_mfma_f32_16x16x32_bf16 v[98:101], v[114:117], v[214:217], v[98:101]
	v_mfma_f32_16x16x32_bf16 v[94:97], v[146:149], v[214:217], v[94:97]
	s_barrier
	s_add_i32 s65, s43, s27
	s_mov_b32 m0, s65
	ds_read_b128 v[166:169], v201 offset:16384
	ds_read_b128 v[186:189], v201 offset:17408
	ds_read_b128 v[190:193], v201 offset:18432
	ds_read_b128 v[196:199], v201 offset:19456
	ds_read_b128 v[202:205], v201 offset:20480
	ds_read_b128 v[206:209], v201 offset:21504
	ds_read_b128 v[210:213], v201 offset:22528
	ds_read_b128 v[214:217], v201 offset:23552
	global_load_lds_dwordx4 v172, s[20:21]
	s_add_i32 m0, s65, 0x2000
	s_add_u32 s68, s20, 0x20000
	s_mov_b64 s[98:99], s[20:21]
	s_addc_u32 s69, s21, 0
	s_add_i32 s65, s44, s27
	global_load_lds_dwordx4 v176, s[20:21]
	s_mov_b32 m0, s65
	s_mov_b64 s[100:101], s[22:23]
	global_load_lds_dwordx4 v172, s[68:69]
	s_add_i32 m0, s65, 0x2000
	s_nop 0
	global_load_lds_dwordx4 v176, s[68:69]
	s_mov_b32 m0, s28
	s_nop 0
	global_load_lds_dwordx4 v170, s[22:23]
	s_mov_b32 m0, s29
	s_nop 0
	global_load_lds_dwordx4 v174, s[22:23]
	s_waitcnt vmcnt(8)
	s_waitcnt lgkmcnt(0)
	s_barrier
	s_waitcnt lgkmcnt(0)
	v_mfma_f32_16x16x32_bf16 v[82:85], v[62:65], v[166:169], v[82:85]
	v_mfma_f32_16x16x32_bf16 v[78:81], v[86:89], v[166:169], v[78:81]
	v_mfma_f32_16x16x32_bf16 v[50:53], v[62:65], v[190:193], v[50:53]
	v_mfma_f32_16x16x32_bf16 v[46:49], v[86:89], v[190:193], v[46:49]
	v_mfma_f32_16x16x32_bf16 v[34:37], v[62:65], v[202:205], v[34:37]
	v_mfma_f32_16x16x32_bf16 v[30:33], v[86:89], v[202:205], v[30:33]
	v_mfma_f32_16x16x32_bf16 v[18:21], v[62:65], v[210:213], v[18:21]
	v_mfma_f32_16x16x32_bf16 v[14:17], v[86:89], v[210:213], v[14:17]
	v_mfma_f32_16x16x32_bf16 v[82:85], v[66:69], v[186:189], v[82:85]
	v_mfma_f32_16x16x32_bf16 v[78:81], v[90:93], v[186:189], v[78:81]
	v_mfma_f32_16x16x32_bf16 v[50:53], v[66:69], v[196:199], v[50:53]
	v_mfma_f32_16x16x32_bf16 v[46:49], v[90:93], v[196:199], v[46:49]
	v_mfma_f32_16x16x32_bf16 v[34:37], v[66:69], v[206:209], v[34:37]
	v_mfma_f32_16x16x32_bf16 v[30:33], v[90:93], v[206:209], v[30:33]
	v_mfma_f32_16x16x32_bf16 v[18:21], v[66:69], v[214:217], v[18:21]
	v_mfma_f32_16x16x32_bf16 v[14:17], v[90:93], v[214:217], v[14:17]
	v_mfma_f32_16x16x32_bf16 v[58:61], v[110:113], v[166:169], v[58:61]
	v_mfma_f32_16x16x32_bf16 v[54:57], v[142:145], v[166:169], v[54:57]
	v_mfma_f32_16x16x32_bf16 v[42:45], v[110:113], v[190:193], v[42:45]
	v_mfma_f32_16x16x32_bf16 v[38:41], v[142:145], v[190:193], v[38:41]
	v_mfma_f32_16x16x32_bf16 v[26:29], v[110:113], v[202:205], v[26:29]
	v_mfma_f32_16x16x32_bf16 v[22:25], v[142:145], v[202:205], v[22:25]
	v_mfma_f32_16x16x32_bf16 v[10:13], v[110:113], v[210:213], v[10:13]
	v_mfma_f32_16x16x32_bf16 v[4:7], v[142:145], v[210:213], v[6:9]
	v_mfma_f32_16x16x32_bf16 v[58:61], v[114:117], v[186:189], v[58:61]
	v_mfma_f32_16x16x32_bf16 v[54:57], v[146:149], v[186:189], v[54:57]
	v_mfma_f32_16x16x32_bf16 v[42:45], v[114:117], v[196:199], v[42:45]
	v_mfma_f32_16x16x32_bf16 v[38:41], v[146:149], v[196:199], v[38:41]
	v_mfma_f32_16x16x32_bf16 v[26:29], v[114:117], v[206:209], v[26:29]
	v_mfma_f32_16x16x32_bf16 v[22:25], v[146:149], v[206:209], v[22:25]
	v_mfma_f32_16x16x32_bf16 v[10:13], v[114:117], v[214:217], v[10:13]
	v_mfma_f32_16x16x32_bf16 v[4:7], v[146:149], v[214:217], v[4:7]
	s_barrier
; #define PG8_STAGE(bufoff, gbase, voff) do { _Pragma("unroll") for (int _i = 0; _i < 2; ++_i) \
;         __builtin_amdgcn_global_load_lds((const unsigned*)((const char*)(gbase) + (voff)[_i]), (LAS unsigned*)(lds + (bufoff) + ldsw + _i * 8192), 16, 0, 0); } while (0)
; #define PG8_LDA(dst, b, h) do { _Pragma("unroll") for (int m = 0; m < 4; ++m) _Pragma("unroll") for (int k = 0; k < 2; ++k) dst[m][k] = *(const LAS bf16x8*)(lds + PG8_SA(b, h) + aoff + m * 2048 + k * 1024); } while (0)
; #define PG8_LDB(dst, b, h) do { _Pragma("unroll") for (int n = 0; n < 2; ++n) _Pragma("unroll") for (int k = 0; k < 2; ++k) dst[n][k] = *(const LAS bf16x8*)(lds + PG8_SB(b, h) + boff + n * 2048 + k * 1024); } while (0)
; #define PG8_MMA(ai, bj, At, Bt) do { __builtin_amdgcn_s_setprio(1); _Pragma("unroll") for (int m = 0; m < 4; ++m) _Pragma("unroll") for (int n = 0; n < 2; ++n) _Pragma("unroll") for (int k = 0; k < 2; ++k) \
;         acc[ai][bj][m][n] = __builtin_amdgcn_mfma_f32_16x16x32_bf16(Bt[n][k], At[m][k], acc[ai][bj][m][n], 0, 0, 0); __builtin_amdgcn_s_setprio(0); } while (0)
; #define PG8_WAIT_V(n) asm volatile("s_waitcnt vmcnt(" #n ")" ::: "memory")
; #define PG8_WAIT_L(n) asm volatile("s_waitcnt lgkmcnt(" #n ")" ::: "memory")
; #define PG8_BAR __builtin_amdgcn_s_barrier()
; #define PG8_SCHED __builtin_amdgcn_sched_barrier(0)
; template <class Epi, class Sched>
; __device__ __forceinline__ void gemm_phase(LAS unsigned char* lds, const int lda, const int ldb, const int K, const Sched& S, const Epi& E) {
;     ...
;             PG8_LDB(B0, 1, 0); PG8_LDB(B1, 1, 1); PG8_SCHED; PG8_LDA(At, 1, 0); PG8_STAGE(PG8_SA(0, 1), a2 + hstepA, voffA);
;             PG8_WAIT_V(8); PG8_WAIT_L(0); PG8_BAR; PG8_MMA(0, 0, At, B0); PG8_MMA(0, 1, At, B1); PG8_BAR; PG8_SCHED;
;             PG8_LDA(At, 1, 1); PG8_STAGE(PG8_SB(1, 0), b3, voffB); PG8_STAGE(PG8_SB(1, 1), b3 + hstepB, voffB); PG8_STAGE(PG8_SA(1, 0), a3, voffA);
;             PG8_WAIT_V(8); PG8_WAIT_L(0); PG8_BAR;
;             if (last) E.pre(cur, wr, fr, rsv);
;             PG8_MMA(1, 0, At, B0); PG8_MMA(1, 1, At, B1); PG8_BAR; PG8_SCHED;
;         }
	s_add_i32 s65, 0, 0x18000
	v_add_u32_e32 v3, s65, v195
	s_add_i32 s68, 0, 0x1c000
	ds_read_b128 v[62:65], v3
	ds_read_b128 v[66:69], v3 offset:1024
	ds_read_b128 v[86:89], v3 offset:2048
	ds_read_b128 v[90:93], v3 offset:3072
	v_add_u32_e32 v3, s68, v195
	ds_read_b128 v[110:113], v3
	ds_read_b128 v[114:117], v3 offset:1024
	ds_read_b128 v[142:145], v3 offset:2048
	ds_read_b128 v[146:149], v3 offset:3072
	s_add_u32 s22, s22, 0xb0000
	s_addc_u32 s23, s23, 0
	s_mov_b32 m0, s30
	ds_read_b128 v[166:169], v201 offset:32768
	ds_read_b128 v[186:189], v201 offset:33792
	ds_read_b128 v[190:193], v201 offset:34816
	ds_read_b128 v[196:199], v201 offset:35840
	ds_read_b128 v[202:205], v201 offset:36864
	ds_read_b128 v[206:209], v201 offset:37888
	ds_read_b128 v[210:213], v201 offset:38912
	ds_read_b128 v[214:217], v201 offset:39936
	global_load_lds_dwordx4 v170, s[22:23]
	s_mov_b32 m0, s31
	s_nop 0
	global_load_lds_dwordx4 v174, s[22:23]
	s_waitcnt vmcnt(8)
	s_waitcnt lgkmcnt(0)
	s_barrier
	s_waitcnt lgkmcnt(0)
	v_mfma_f32_16x16x32_bf16 v[74:77], v[62:65], v[166:169], v[74:77]
	v_mfma_f32_16x16x32_bf16 v[70:73], v[86:89], v[166:169], v[70:73]
	v_mfma_f32_16x16x32_bf16 v[106:109], v[62:65], v[190:193], v[106:109]
	v_mfma_f32_16x16x32_bf16 v[102:105], v[86:89], v[190:193], v[102:105]
	v_mfma_f32_16x16x32_bf16 v[138:141], v[62:65], v[202:205], v[138:141]
	v_mfma_f32_16x16x32_bf16 v[126:129], v[86:89], v[202:205], v[126:129]
	v_mfma_f32_16x16x32_bf16 v[122:125], v[62:65], v[210:213], v[122:125]
	v_mfma_f32_16x16x32_bf16 v[118:121], v[86:89], v[210:213], v[118:121]
	v_mfma_f32_16x16x32_bf16 v[74:77], v[66:69], v[186:189], v[74:77]
	v_mfma_f32_16x16x32_bf16 v[70:73], v[90:93], v[186:189], v[70:73]
	v_mfma_f32_16x16x32_bf16 v[106:109], v[66:69], v[196:199], v[106:109]
	v_mfma_f32_16x16x32_bf16 v[102:105], v[90:93], v[196:199], v[102:105]
	v_mfma_f32_16x16x32_bf16 v[138:141], v[66:69], v[206:209], v[138:141]
	v_mfma_f32_16x16x32_bf16 v[126:129], v[90:93], v[206:209], v[126:129]
	v_mfma_f32_16x16x32_bf16 v[122:125], v[66:69], v[214:217], v[122:125]
	v_mfma_f32_16x16x32_bf16 v[118:121], v[90:93], v[214:217], v[118:121]
	v_mfma_f32_16x16x32_bf16 v[162:165], v[110:113], v[166:169], v[162:165]
	v_mfma_f32_16x16x32_bf16 v[158:161], v[142:145], v[166:169], v[158:161]
	v_mfma_f32_16x16x32_bf16 v[154:157], v[110:113], v[190:193], v[154:157]
	v_mfma_f32_16x16x32_bf16 v[150:153], v[142:145], v[190:193], v[150:153]
	v_mfma_f32_16x16x32_bf16 v[134:137], v[110:113], v[202:205], v[134:137]
	v_mfma_f32_16x16x32_bf16 v[130:133], v[142:145], v[202:205], v[130:133]
	v_mfma_f32_16x16x32_bf16 v[98:101], v[110:113], v[210:213], v[98:101]
	v_mfma_f32_16x16x32_bf16 v[94:97], v[142:145], v[210:213], v[94:97]
	v_mfma_f32_16x16x32_bf16 v[162:165], v[114:117], v[186:189], v[162:165]
	v_mfma_f32_16x16x32_bf16 v[158:161], v[146:149], v[186:189], v[158:161]
	v_mfma_f32_16x16x32_bf16 v[154:157], v[114:117], v[196:199], v[154:157]
	v_mfma_f32_16x16x32_bf16 v[150:153], v[146:149], v[196:199], v[150:153]
	v_mfma_f32_16x16x32_bf16 v[134:137], v[114:117], v[206:209], v[134:137]
	v_mfma_f32_16x16x32_bf16 v[130:133], v[146:149], v[206:209], v[130:133]
	v_mfma_f32_16x16x32_bf16 v[98:101], v[114:117], v[214:217], v[98:101]
	v_mfma_f32_16x16x32_bf16 v[94:97], v[146:149], v[214:217], v[94:97]
	s_barrier
	s_add_i32 s22, s65, s27
	s_mov_b32 m0, s22
	ds_read_b128 v[166:169], v201 offset:49152
	ds_read_b128 v[186:189], v201 offset:50176
	ds_read_b128 v[190:193], v201 offset:51200
	ds_read_b128 v[196:199], v201 offset:52224
	ds_read_b128 v[202:205], v201 offset:53248
	ds_read_b128 v[206:209], v201 offset:54272
	ds_read_b128 v[210:213], v201 offset:55296
	ds_read_b128 v[214:217], v201 offset:56320
	global_load_lds_dwordx4 v218, s[20:21]
	s_add_i32 m0, s22, 0x2000
	s_add_u32 s20, s20, 0x20080
	s_addc_u32 s21, s21, 0
	s_add_i32 s22, s68, s27
	global_load_lds_dwordx4 v219, s[98:99]
	s_mov_b32 m0, s22
	s_nop 0
	global_load_lds_dwordx4 v172, s[20:21]
	s_add_i32 m0, s22, 0x2000
	s_nop 0
	global_load_lds_dwordx4 v176, s[20:21]
	s_mov_b32 m0, s40
	s_nop 0
	global_load_lds_dwordx4 v220, s[100:101]
	s_mov_b32 m0, s41
	s_nop 0
	global_load_lds_dwordx4 v221, s[100:101]
	s_waitcnt vmcnt(8)
	s_waitcnt lgkmcnt(0)
	s_barrier
	s_waitcnt lgkmcnt(0)
	v_mfma_f32_16x16x32_bf16 v[82:85], v[62:65], v[166:169], v[82:85]
	v_mfma_f32_16x16x32_bf16 v[78:81], v[86:89], v[166:169], v[78:81]
	v_mfma_f32_16x16x32_bf16 v[50:53], v[62:65], v[190:193], v[50:53]
	v_mfma_f32_16x16x32_bf16 v[46:49], v[86:89], v[190:193], v[46:49]
	v_mfma_f32_16x16x32_bf16 v[34:37], v[62:65], v[202:205], v[34:37]
	v_mfma_f32_16x16x32_bf16 v[30:33], v[86:89], v[202:205], v[30:33]
	v_mfma_f32_16x16x32_bf16 v[18:21], v[62:65], v[210:213], v[18:21]
	v_mfma_f32_16x16x32_bf16 v[14:17], v[86:89], v[210:213], v[14:17]
	v_mfma_f32_16x16x32_bf16 v[82:85], v[66:69], v[186:189], v[82:85]
	v_mfma_f32_16x16x32_bf16 v[78:81], v[90:93], v[186:189], v[78:81]
	v_mfma_f32_16x16x32_bf16 v[50:53], v[66:69], v[196:199], v[50:53]
	v_mfma_f32_16x16x32_bf16 v[46:49], v[90:93], v[196:199], v[46:49]
	v_mfma_f32_16x16x32_bf16 v[34:37], v[66:69], v[206:209], v[34:37]
	v_mfma_f32_16x16x32_bf16 v[30:33], v[90:93], v[206:209], v[30:33]
	v_mfma_f32_16x16x32_bf16 v[18:21], v[66:69], v[214:217], v[18:21]
	v_mfma_f32_16x16x32_bf16 v[14:17], v[90:93], v[214:217], v[14:17]
	v_mfma_f32_16x16x32_bf16 v[58:61], v[110:113], v[166:169], v[58:61]
	v_mfma_f32_16x16x32_bf16 v[54:57], v[142:145], v[166:169], v[54:57]
	v_mfma_f32_16x16x32_bf16 v[42:45], v[110:113], v[190:193], v[42:45]
	v_mfma_f32_16x16x32_bf16 v[38:41], v[142:145], v[190:193], v[38:41]
	v_mfma_f32_16x16x32_bf16 v[26:29], v[110:113], v[202:205], v[26:29]
	v_mfma_f32_16x16x32_bf16 v[22:25], v[142:145], v[202:205], v[22:25]
	v_mfma_f32_16x16x32_bf16 v[8:11], v[110:113], v[210:213], v[10:13]
	v_mfma_f32_16x16x32_bf16 v[4:7], v[142:145], v[210:213], v[4:7]
	v_mfma_f32_16x16x32_bf16 v[58:61], v[114:117], v[186:189], v[58:61]
	v_mfma_f32_16x16x32_bf16 v[54:57], v[146:149], v[186:189], v[54:57]
	v_mfma_f32_16x16x32_bf16 v[42:45], v[114:117], v[196:199], v[42:45]
	v_mfma_f32_16x16x32_bf16 v[38:41], v[146:149], v[196:199], v[38:41]
	v_mfma_f32_16x16x32_bf16 v[26:29], v[114:117], v[206:209], v[26:29]
	v_mfma_f32_16x16x32_bf16 v[22:25], v[146:149], v[206:209], v[22:25]
	v_mfma_f32_16x16x32_bf16 v[10:13], v[114:117], v[214:217], v[8:11]
	v_mfma_f32_16x16x32_bf16 v[6:9], v[146:149], v[214:217], v[4:7]
	s_barrier
	s_add_i32 s64, s64, 2
	s_add_u32 s4, s4, 0x100
	s_addc_u32 s5, s5, 0
	s_add_u32 s15, s15, 0x100
	s_addc_u32 s63, s63, 0
	s_cmp_gt_u32 s64, 5
	s_cbranch_scc0 .LBB0_839
	s_and_b64 vcc, exec, s[12:13]
	s_cbranch_vccz .LBB0_842
	s_barrier

; #define PG8_STAGE(bufoff, gbase, voff) do { _Pragma("unroll") for (int _i = 0; _i < 2; ++_i) \
;         __builtin_amdgcn_global_load_lds((const unsigned*)((const char*)(gbase) + (voff)[_i]), (LAS unsigned*)(lds + (bufoff) + ldsw + _i * 8192), 16, 0, 0); } while (0)
; #define PG8_BAR __builtin_amdgcn_s_barrier()
; template <class Epi, class Sched>
; __device__ __forceinline__ void gemm_phase(LAS unsigned char* lds, const int lda, const int ldb, const int K, const Sched& S, const Epi& E) {
;     const int tid = threadIdx.x, wid = __builtin_amdgcn_readfirstlane(tid >> 6), lane = tid & 63, wr = wid >> 2, wc = wid & 3, fr = lane & 15, fq = lane >> 4;
;     const int nt = K / BK;
;     unsigned voffA[2], voffB[2];
; #pragma unroll
;     for (int i = 0; i < 2; ++i) { int R, C; stage_rc(tid * 16 + i * 8192, R, C); const int Rb = (R & ~31) + perm32(R & 31);
;         voffA[i] = (unsigned)(R * lda + C) * 2u; voffB[i] = (unsigned)(Rb * ldb + C) * 2u; }
;     const size_t kstep = (size_t)(BK * 2);
;     const size_t hstepA = (size_t)HALF * lda * 2, hstepB = (size_t)HALF * ldb * 2;
;     const unsigned ldsw = (unsigned)wid * 1024u;
;     const int aoff = lds_byte(wr * 64 + fr, fq * 8), boff = lds_byte(wc * 32 + fr, fq * 8);
;     ...
;     Unit cur, nxt; int ui = 0;
;     if (!S.next(0, cur)) return;
;     f32x4 acc[2][2][4][2];
; #pragma unroll
;     for (int a = 0; a < 2; ++a)
; #pragma unroll
;         for (int b = 0; b < 2; ++b)
; #pragma unroll
;             for (int m = 0; m < 4; ++m)
; #pragma unroll
;                 for (int n = 0; n < 2; ++n) acc[a][b][m][n] = (f32x4){0.f, 0.f, 0.f, 0.f};
;     bf16x8 At[4][2], B0[2][2], B1[2][2];
;     float rsv[8];
; #pragma unroll
;     for (int i = 0; i < 8; ++i) rsv[i] = 0.f;
;     const char* cA = cur.A; const char* cB = cur.B;
;     PG8_STAGE(PG8_SB(0, 0), cB, voffB); PG8_STAGE(PG8_SB(0, 1), cB + hstepB, voffB); PG8_STAGE(PG8_SA(0, 0), cA, voffA); PG8_STAGE(PG8_SA(0, 1), cA + hstepA, voffA);
;     if (wr == 1) PG8_BAR;
.LBB0_948:
	s_waitcnt lgkmcnt(0)
	v_lshrrev_b32_e32 v3, 1, v194
	v_lshrrev_b32_e32 v4, 5, v194
	v_and_b32_e32 v3, 24, v3
	v_and_b32_e32 v4, 4, v4
	v_bfe_u32 v5, v194, 2, 2
	v_lshlrev_b32_e32 v1, 4, v194
	v_and_b32_e32 v2, 32, v194
	v_bfe_u32 v12, v194, 2, 4
	v_or3_b32 v3, v4, v5, v3
	v_lshrrev_b32_e32 v4, 3, v194
	s_movk_i32 s1, 0x70
	v_bitop3_b32 v10, v1, v2, 48 bitop3:0x6c
	v_and_b32_e32 v11, 64, v194
	v_and_or_b32 v5, v4, s1, v12
	s_movk_i32 s1, 0x60
	v_add_u32_e32 v13, 0x2000, v1
	v_or_b32_e32 v2, v10, v11
	v_and_or_b32 v4, v4, s1, v3
	v_lshrrev_b32_e32 v1, 7, v13
	s_movk_i32 s1, 0xf0
	v_lshl_or_b32 v156, v4, 11, v2
	v_and_or_b32 v4, v1, s1, v12
	s_movk_i32 s1, 0xe0
	v_and_or_b32 v1, v1, s1, v3
	s_lshr_b32 s1, s4, 6
	s_lshl_b32 s31, s1, 10
	s_add_i32 s33, s31, 0
	s_add_i32 m0, s33, 0x10000
	s_lshr_b32 s0, s4, 8
	global_load_lds_dwordx4 v156, s[26:27]
	s_add_i32 m0, s33, 0x12000
	v_lshl_or_b32 v160, v1, 11, v2
	s_add_u32 s8, s26, 0x40000
	global_load_lds_dwordx4 v160, s[26:27]
	s_addc_u32 s9, s27, 0
	s_add_i32 m0, s33, 0x14000
	s_add_i32 s34, s33, 0x2000
	global_load_lds_dwordx4 v156, s[8:9]
	s_add_i32 m0, s33, 0x16000
	v_lshl_or_b32 v154, v5, 11, v2
	global_load_lds_dwordx4 v160, s[8:9]
	s_mov_b32 m0, s33
	s_add_u32 s8, s24, 0x40000
	v_lshl_or_b32 v158, v4, 11, v2
	global_load_lds_dwordx4 v154, s[24:25]
	s_mov_b32 m0, s34
	s_addc_u32 s9, s25, 0
	s_add_i32 s35, s33, 0x4000
	global_load_lds_dwordx4 v158, s[24:25]
	s_mov_b32 m0, s35
	s_add_i32 s38, s33, 0x6000
	global_load_lds_dwordx4 v154, s[8:9]
	s_mov_b32 m0, s38
	v_mov_b32_e32 v157, 0
	global_load_lds_dwordx4 v158, s[8:9]
	v_mov_b32_e32 v161, v157
	v_mov_b32_e32 v155, v157
	v_mov_b32_e32 v159, v157
	s_cmp_eq_u32 s0, 1
	s_mov_b32 s39, 0
	v_lshl_add_u64 v[8:9], s[26:27], 0, v[156:157]
	v_lshl_add_u64 v[6:7], s[26:27], 0, v[160:161]
	v_lshl_add_u64 v[2:3], s[24:25], 0, v[154:155]
	s_cselect_b64 s[8:9], -1, 0
	s_cmp_lg_u32 s0, 1
	v_lshl_add_u64 v[4:5], s[24:25], 0, v[158:159]
	s_cbranch_scc1 .LBB0_950
	s_setprio 1
	s_barrier

; #define PG8_STAGE(bufoff, gbase, voff) do { _Pragma("unroll") for (int _i = 0; _i < 2; ++_i) \
;         __builtin_amdgcn_global_load_lds((const unsigned*)((const char*)(gbase) + (voff)[_i]), (LAS unsigned*)(lds + (bufoff) + ldsw + _i * 8192), 16, 0, 0); } while (0)
; #define PG8_LDA(dst, b, h) do { _Pragma("unroll") for (int m = 0; m < 4; ++m) _Pragma("unroll") for (int k = 0; k < 2; ++k) dst[m][k] = *(const LAS bf16x8*)(lds + PG8_SA(b, h) + aoff + m * 2048 + k * 1024); } while (0)
; #define PG8_LDB(dst, b, h) do { _Pragma("unroll") for (int n = 0; n < 2; ++n) _Pragma("unroll") for (int k = 0; k < 2; ++k) dst[n][k] = *(const LAS bf16x8*)(lds + PG8_SB(b, h) + boff + n * 2048 + k * 1024); } while (0)
; #define PG8_MMA(ai, bj, At, Bt) do { __builtin_amdgcn_s_setprio(1); _Pragma("unroll") for (int m = 0; m < 4; ++m) _Pragma("unroll") for (int n = 0; n < 2; ++n) _Pragma("unroll") for (int k = 0; k < 2; ++k) \
;         acc[ai][bj][m][n] = __builtin_amdgcn_mfma_f32_16x16x32_bf16(Bt[n][k], At[m][k], acc[ai][bj][m][n], 0, 0, 0); __builtin_amdgcn_s_setprio(0); } while (0)
; #define PG8_WAIT_V(n) asm volatile("s_waitcnt vmcnt(" #n ")" ::: "memory")
; #define PG8_WAIT_L(n) asm volatile("s_waitcnt lgkmcnt(" #n ")" ::: "memory")
; #define PG8_BAR __builtin_amdgcn_s_barrier()
; #define PG8_SCHED __builtin_amdgcn_sched_barrier(0)
; template <class Epi, class Sched>
; __device__ __forceinline__ void gemm_phase(LAS unsigned char* lds, const int lda, const int ldb, const int K, const Sched& S, const Epi& E) {
;     ...
;         for (int t = 0; t < nt; t += 2) {
;             const bool last = (t == nt - 2);
;             const char* a1 = cA + (size_t)(t + 1) * kstep;
;             const char* a2 = last ? nA : cA + (size_t)(t + 2) * kstep; const char* b2 = last ? nB : cB + (size_t)(t + 2) * kstep;
;             const char* a3 = a2 + kstep; const char* b3 = b2 + kstep;
;             PG8_LDB(B0, 0, 0); PG8_LDB(B1, 0, 1); PG8_SCHED; PG8_LDA(At, 0, 0); PG8_STAGE(PG8_SA(1, 1), a1 + hstepA, voffA);
;             PG8_WAIT_V(8); PG8_WAIT_L(0); PG8_BAR; PG8_MMA(0, 0, At, B0); PG8_MMA(0, 1, At, B1); PG8_BAR; PG8_SCHED;
;             PG8_LDA(At, 0, 1); PG8_STAGE(PG8_SB(0, 0), b2, voffB); PG8_STAGE(PG8_SB(0, 1), b2 + hstepB, voffB); PG8_STAGE(PG8_SA(0, 0), a2, voffA);
;             PG8_WAIT_V(8); PG8_WAIT_L(0); PG8_BAR; PG8_MMA(1, 0, At, B0); PG8_MMA(1, 1, At, B1); PG8_BAR; PG8_SCHED;
.LBB0_955:
	s_add_u32 s24, s24, 0x40080
	s_addc_u32 s25, s25, 0
	s_add_u32 s15, s26, 0x100
	s_addc_u32 s17, s27, 0
	s_mov_b32 s23, -2
	s_waitcnt lgkmcnt(0)
	v_add_u32_e32 v192, 0x80, v156
	v_add_u32_e32 v193, 0x80, v160
	v_add_u32_e32 v220, 0x80, v154
	v_add_u32_e32 v221, 0x80, v158
	ds_read_b128 v[130:133], v188
	ds_read_b128 v[134:137], v188 offset:1024
	ds_read_b128 v[138:141], v188 offset:2048
	ds_read_b128 v[142:145], v188 offset:3072
	ds_read_b128 v[146:149], v189
	ds_read_b128 v[150:153], v189 offset:1024
	ds_read_b128 v[170:173], v189 offset:2048
	ds_read_b128 v[174:177], v189 offset:3072
	s_add_u32 s26, s24, 0xfffc0080
	s_addc_u32 s27, s25, -1
	s_cmp_eq_u32 s23, 12
	s_cselect_b32 s29, s19, s27
	s_cselect_b32 s28, s18, s26
	s_cselect_b32 s27, s21, s17
	s_cselect_b32 s26, s20, s15
	s_add_i32 m0, s33, 0xc000
	ds_read_b128 v[178:181], v190
	ds_read_b128 v[182:185], v190 offset:1024
	ds_read_b128 v[196:199], v190 offset:2048
	ds_read_b128 v[200:203], v190 offset:3072
	ds_read_b128 v[204:207], v190 offset:4096
	ds_read_b128 v[208:211], v190 offset:5120
	ds_read_b128 v[212:215], v190 offset:6144
	ds_read_b128 v[216:219], v190 offset:7168
	global_load_lds_dwordx4 v162, s[24:25]
	s_add_i32 m0, s33, 0xe000
	s_nop 0
	global_load_lds_dwordx4 v164, s[24:25]
	s_waitcnt vmcnt(8)
	s_waitcnt lgkmcnt(0)
	s_barrier
	s_waitcnt lgkmcnt(0)
	v_mfma_f32_16x16x32_bf16 v[126:129], v[130:133], v[178:181], 0
	v_mfma_f32_16x16x32_bf16 v[122:125], v[138:141], v[178:181], 0
	v_mfma_f32_16x16x32_bf16 v[110:113], v[130:133], v[196:199], 0
	v_mfma_f32_16x16x32_bf16 v[106:109], v[138:141], v[196:199], 0
	v_mfma_f32_16x16x32_bf16 v[94:97], v[130:133], v[204:207], 0
	v_mfma_f32_16x16x32_bf16 v[90:93], v[138:141], v[204:207], 0
	v_mfma_f32_16x16x32_bf16 v[78:81], v[130:133], v[212:215], 0
	v_mfma_f32_16x16x32_bf16 v[74:77], v[138:141], v[212:215], 0
	v_mfma_f32_16x16x32_bf16 v[126:129], v[134:137], v[182:185], v[126:129]
	v_mfma_f32_16x16x32_bf16 v[122:125], v[142:145], v[182:185], v[122:125]
	v_mfma_f32_16x16x32_bf16 v[110:113], v[134:137], v[200:203], v[110:113]
	v_mfma_f32_16x16x32_bf16 v[106:109], v[142:145], v[200:203], v[106:109]
	v_mfma_f32_16x16x32_bf16 v[94:97], v[134:137], v[208:211], v[94:97]
	v_mfma_f32_16x16x32_bf16 v[90:93], v[142:145], v[208:211], v[90:93]
	v_mfma_f32_16x16x32_bf16 v[78:81], v[134:137], v[216:219], v[78:81]
	v_mfma_f32_16x16x32_bf16 v[74:77], v[142:145], v[216:219], v[74:77]
	v_mfma_f32_16x16x32_bf16 v[118:121], v[146:149], v[178:181], 0
	v_mfma_f32_16x16x32_bf16 v[114:117], v[170:173], v[178:181], 0
	v_mfma_f32_16x16x32_bf16 v[102:105], v[146:149], v[196:199], 0
	v_mfma_f32_16x16x32_bf16 v[98:101], v[170:173], v[196:199], 0
	v_mfma_f32_16x16x32_bf16 v[86:89], v[146:149], v[204:207], 0
	v_mfma_f32_16x16x32_bf16 v[82:85], v[170:173], v[204:207], 0
	v_mfma_f32_16x16x32_bf16 v[70:73], v[146:149], v[212:215], 0
	v_mfma_f32_16x16x32_bf16 v[66:69], v[170:173], v[212:215], 0
	v_mfma_f32_16x16x32_bf16 v[118:121], v[150:153], v[182:185], v[118:121]
	v_mfma_f32_16x16x32_bf16 v[114:117], v[174:177], v[182:185], v[114:117]
	v_mfma_f32_16x16x32_bf16 v[102:105], v[150:153], v[200:203], v[102:105]
	v_mfma_f32_16x16x32_bf16 v[98:101], v[174:177], v[200:203], v[98:101]
	v_mfma_f32_16x16x32_bf16 v[86:89], v[150:153], v[208:211], v[86:89]
	v_mfma_f32_16x16x32_bf16 v[82:85], v[174:177], v[208:211], v[82:85]
	v_mfma_f32_16x16x32_bf16 v[70:73], v[150:153], v[216:219], v[70:73]
	v_mfma_f32_16x16x32_bf16 v[66:69], v[174:177], v[216:219], v[66:69]
	s_barrier
	s_add_i32 s51, s48, s31
	s_mov_b32 m0, s51
	ds_read_b128 v[178:181], v190 offset:16384
	ds_read_b128 v[182:185], v190 offset:17408
	ds_read_b128 v[196:199], v190 offset:18432
	ds_read_b128 v[200:203], v190 offset:19456
	ds_read_b128 v[204:207], v190 offset:20480
	ds_read_b128 v[208:211], v190 offset:21504
	ds_read_b128 v[212:215], v190 offset:22528
	ds_read_b128 v[216:219], v190 offset:23552
	global_load_lds_dwordx4 v156, s[26:27]
	s_add_i32 m0, s51, 0x2000
	s_add_u32 s62, s26, 0x40000
	s_mov_b64 s[98:99], s[26:27]
	s_addc_u32 s63, s27, 0
	s_add_i32 s51, s49, s31
	global_load_lds_dwordx4 v160, s[26:27]
	s_mov_b32 m0, s51
	s_mov_b64 s[100:101], s[28:29]
	global_load_lds_dwordx4 v156, s[62:63]
	s_add_i32 m0, s51, 0x2000
	s_nop 0
	global_load_lds_dwordx4 v160, s[62:63]
	s_mov_b32 m0, s33
	s_nop 0
	global_load_lds_dwordx4 v154, s[28:29]
	s_mov_b32 m0, s34
	s_nop 0
	global_load_lds_dwordx4 v158, s[28:29]
	s_waitcnt vmcnt(8)
	s_waitcnt lgkmcnt(0)
	s_barrier
	s_waitcnt lgkmcnt(0)
	v_mfma_f32_16x16x32_bf16 v[62:65], v[130:133], v[178:181], 0
	v_mfma_f32_16x16x32_bf16 v[58:61], v[138:141], v[178:181], 0
	v_mfma_f32_16x16x32_bf16 v[46:49], v[130:133], v[196:199], 0
	v_mfma_f32_16x16x32_bf16 v[42:45], v[138:141], v[196:199], 0
	v_mfma_f32_16x16x32_bf16 v[30:33], v[130:133], v[204:207], 0
	v_mfma_f32_16x16x32_bf16 v[26:29], v[138:141], v[204:207], 0
	v_mfma_f32_16x16x32_bf16 v[14:17], v[130:133], v[212:215], 0
	v_mfma_f32_16x16x32_bf16 v[10:13], v[138:141], v[212:215], 0
	v_mfma_f32_16x16x32_bf16 v[62:65], v[134:137], v[182:185], v[62:65]
	v_mfma_f32_16x16x32_bf16 v[58:61], v[142:145], v[182:185], v[58:61]
	v_mfma_f32_16x16x32_bf16 v[46:49], v[134:137], v[200:203], v[46:49]
	v_mfma_f32_16x16x32_bf16 v[42:45], v[142:145], v[200:203], v[42:45]
	v_mfma_f32_16x16x32_bf16 v[30:33], v[134:137], v[208:211], v[30:33]
	v_mfma_f32_16x16x32_bf16 v[26:29], v[142:145], v[208:211], v[26:29]
	v_mfma_f32_16x16x32_bf16 v[14:17], v[134:137], v[216:219], v[14:17]
	v_mfma_f32_16x16x32_bf16 v[10:13], v[142:145], v[216:219], v[10:13]
	v_mfma_f32_16x16x32_bf16 v[54:57], v[146:149], v[178:181], 0
	v_mfma_f32_16x16x32_bf16 v[50:53], v[170:173], v[178:181], 0
	v_mfma_f32_16x16x32_bf16 v[38:41], v[146:149], v[196:199], 0
	v_mfma_f32_16x16x32_bf16 v[34:37], v[170:173], v[196:199], 0
	v_mfma_f32_16x16x32_bf16 v[22:25], v[146:149], v[204:207], 0
	v_mfma_f32_16x16x32_bf16 v[18:21], v[170:173], v[204:207], 0
	v_mfma_f32_16x16x32_bf16 v[6:9], v[146:149], v[212:215], 0
	v_mfma_f32_16x16x32_bf16 v[2:5], v[170:173], v[212:215], 0
	v_mfma_f32_16x16x32_bf16 v[54:57], v[150:153], v[182:185], v[54:57]
	v_mfma_f32_16x16x32_bf16 v[50:53], v[174:177], v[182:185], v[50:53]
	v_mfma_f32_16x16x32_bf16 v[38:41], v[150:153], v[200:203], v[38:41]
	v_mfma_f32_16x16x32_bf16 v[34:37], v[174:177], v[200:203], v[34:37]
	v_mfma_f32_16x16x32_bf16 v[22:25], v[150:153], v[208:211], v[22:25]
	v_mfma_f32_16x16x32_bf16 v[18:21], v[174:177], v[208:211], v[18:21]
	v_mfma_f32_16x16x32_bf16 v[6:9], v[150:153], v[216:219], v[6:9]
	v_mfma_f32_16x16x32_bf16 v[2:5], v[174:177], v[216:219], v[2:5]
	s_barrier
	s_branch .Lpeel5_join
; #define PG8_STAGE(bufoff, gbase, voff) do { _Pragma("unroll") for (int _i = 0; _i < 2; ++_i) \
;         __builtin_amdgcn_global_load_lds((const unsigned*)((const char*)(gbase) + (voff)[_i]), (LAS unsigned*)(lds + (bufoff) + ldsw + _i * 8192), 16, 0, 0); } while (0)
; #define PG8_LDA(dst, b, h) do { _Pragma("unroll") for (int m = 0; m < 4; ++m) _Pragma("unroll") for (int k = 0; k < 2; ++k) dst[m][k] = *(const LAS bf16x8*)(lds + PG8_SA(b, h) + aoff + m * 2048 + k * 1024); } while (0)
; #define PG8_LDB(dst, b, h) do { _Pragma("unroll") for (int n = 0; n < 2; ++n) _Pragma("unroll") for (int k = 0; k < 2; ++k) dst[n][k] = *(const LAS bf16x8*)(lds + PG8_SB(b, h) + boff + n * 2048 + k * 1024); } while (0)
; #define PG8_MMA(ai, bj, At, Bt) do { __builtin_amdgcn_s_setprio(1); _Pragma("unroll") for (int m = 0; m < 4; ++m) _Pragma("unroll") for (int n = 0; n < 2; ++n) _Pragma("unroll") for (int k = 0; k < 2; ++k) \
;         acc[ai][bj][m][n] = __builtin_amdgcn_mfma_f32_16x16x32_bf16(Bt[n][k], At[m][k], acc[ai][bj][m][n], 0, 0, 0); __builtin_amdgcn_s_setprio(0); } while (0)
; #define PG8_WAIT_V(n) asm volatile("s_waitcnt vmcnt(" #n ")" ::: "memory")
; #define PG8_WAIT_L(n) asm volatile("s_waitcnt lgkmcnt(" #n ")" ::: "memory")
; #define PG8_BAR __builtin_amdgcn_s_barrier()
; #define PG8_SCHED __builtin_amdgcn_sched_barrier(0)
; template <class Epi, class Sched>
; __device__ __forceinline__ void gemm_phase(LAS unsigned char* lds, const int lda, const int ldb, const int K, const Sched& S, const Epi& E) {
;     ...
;             PG8_LDB(B0, 0, 0); PG8_LDB(B1, 0, 1); PG8_SCHED; PG8_LDA(At, 0, 0); PG8_STAGE(PG8_SA(1, 1), a1 + hstepA, voffA);
;             PG8_WAIT_V(8); PG8_WAIT_L(0); PG8_BAR; PG8_MMA(0, 0, At, B0); PG8_MMA(0, 1, At, B1); PG8_BAR; PG8_SCHED;
;             PG8_LDA(At, 0, 1); PG8_STAGE(PG8_SB(0, 0), b2, voffB); PG8_STAGE(PG8_SB(0, 1), b2 + hstepB, voffB); PG8_STAGE(PG8_SA(0, 0), a2, voffA);
;             PG8_WAIT_V(8); PG8_WAIT_L(0); PG8_BAR; PG8_MMA(1, 0, At, B0); PG8_MMA(1, 1, At, B1); PG8_BAR; PG8_SCHED;
.LBB0_956:
	ds_read_b128 v[130:133], v188
	ds_read_b128 v[134:137], v188 offset:1024
	ds_read_b128 v[138:141], v188 offset:2048
	ds_read_b128 v[142:145], v188 offset:3072
	ds_read_b128 v[146:149], v189
	ds_read_b128 v[150:153], v189 offset:1024
	ds_read_b128 v[170:173], v189 offset:2048
	ds_read_b128 v[174:177], v189 offset:3072
	s_add_u32 s26, s24, 0xfffc0080
	s_addc_u32 s27, s25, -1
	s_cmp_eq_u32 s23, 12
	s_cselect_b32 s29, s19, s27
	s_cselect_b32 s28, s18, s26
	s_cselect_b32 s27, s21, s17
	s_cselect_b32 s26, s20, s15
	s_add_i32 m0, s33, 0xc000
	ds_read_b128 v[178:181], v190
	ds_read_b128 v[182:185], v190 offset:1024
	ds_read_b128 v[196:199], v190 offset:2048
	ds_read_b128 v[200:203], v190 offset:3072
	ds_read_b128 v[204:207], v190 offset:4096
	ds_read_b128 v[208:211], v190 offset:5120
	ds_read_b128 v[212:215], v190 offset:6144
	ds_read_b128 v[216:219], v190 offset:7168
	global_load_lds_dwordx4 v162, s[24:25]
	s_add_i32 m0, s33, 0xe000
	s_nop 0
	global_load_lds_dwordx4 v164, s[24:25]
	s_waitcnt vmcnt(8)
	s_waitcnt lgkmcnt(0)
	s_barrier
	s_waitcnt lgkmcnt(0)
	v_mfma_f32_16x16x32_bf16 v[126:129], v[130:133], v[178:181], v[126:129]
	v_mfma_f32_16x16x32_bf16 v[122:125], v[138:141], v[178:181], v[122:125]
	v_mfma_f32_16x16x32_bf16 v[110:113], v[130:133], v[196:199], v[110:113]
	v_mfma_f32_16x16x32_bf16 v[106:109], v[138:141], v[196:199], v[106:109]
	v_mfma_f32_16x16x32_bf16 v[94:97], v[130:133], v[204:207], v[94:97]
	v_mfma_f32_16x16x32_bf16 v[90:93], v[138:141], v[204:207], v[90:93]
	v_mfma_f32_16x16x32_bf16 v[78:81], v[130:133], v[212:215], v[78:81]
	v_mfma_f32_16x16x32_bf16 v[74:77], v[138:141], v[212:215], v[74:77]
	v_mfma_f32_16x16x32_bf16 v[126:129], v[134:137], v[182:185], v[126:129]
	v_mfma_f32_16x16x32_bf16 v[122:125], v[142:145], v[182:185], v[122:125]
	v_mfma_f32_16x16x32_bf16 v[110:113], v[134:137], v[200:203], v[110:113]
	v_mfma_f32_16x16x32_bf16 v[106:109], v[142:145], v[200:203], v[106:109]
	v_mfma_f32_16x16x32_bf16 v[94:97], v[134:137], v[208:211], v[94:97]
	v_mfma_f32_16x16x32_bf16 v[90:93], v[142:145], v[208:211], v[90:93]
	v_mfma_f32_16x16x32_bf16 v[78:81], v[134:137], v[216:219], v[78:81]
	v_mfma_f32_16x16x32_bf16 v[74:77], v[142:145], v[216:219], v[74:77]
	v_mfma_f32_16x16x32_bf16 v[118:121], v[146:149], v[178:181], v[118:121]
	v_mfma_f32_16x16x32_bf16 v[114:117], v[170:173], v[178:181], v[114:117]
	v_mfma_f32_16x16x32_bf16 v[102:105], v[146:149], v[196:199], v[102:105]
	v_mfma_f32_16x16x32_bf16 v[98:101], v[170:173], v[196:199], v[98:101]
	v_mfma_f32_16x16x32_bf16 v[86:89], v[146:149], v[204:207], v[86:89]
	v_mfma_f32_16x16x32_bf16 v[82:85], v[170:173], v[204:207], v[82:85]
	v_mfma_f32_16x16x32_bf16 v[70:73], v[146:149], v[212:215], v[70:73]
	v_mfma_f32_16x16x32_bf16 v[66:69], v[170:173], v[212:215], v[66:69]
	v_mfma_f32_16x16x32_bf16 v[118:121], v[150:153], v[182:185], v[118:121]
	v_mfma_f32_16x16x32_bf16 v[114:117], v[174:177], v[182:185], v[114:117]
	v_mfma_f32_16x16x32_bf16 v[102:105], v[150:153], v[200:203], v[102:105]
	v_mfma_f32_16x16x32_bf16 v[98:101], v[174:177], v[200:203], v[98:101]
	v_mfma_f32_16x16x32_bf16 v[86:89], v[150:153], v[208:211], v[86:89]
	v_mfma_f32_16x16x32_bf16 v[82:85], v[174:177], v[208:211], v[82:85]
	v_mfma_f32_16x16x32_bf16 v[70:73], v[150:153], v[216:219], v[70:73]
	v_mfma_f32_16x16x32_bf16 v[66:69], v[174:177], v[216:219], v[66:69]
	s_barrier
	s_add_i32 s51, s48, s31
	s_mov_b32 m0, s51
	ds_read_b128 v[178:181], v190 offset:16384
	ds_read_b128 v[182:185], v190 offset:17408
	ds_read_b128 v[196:199], v190 offset:18432
	ds_read_b128 v[200:203], v190 offset:19456
	ds_read_b128 v[204:207], v190 offset:20480
	ds_read_b128 v[208:211], v190 offset:21504
	ds_read_b128 v[212:215], v190 offset:22528
	ds_read_b128 v[216:219], v190 offset:23552
	global_load_lds_dwordx4 v156, s[26:27]
	s_add_i32 m0, s51, 0x2000
	s_add_u32 s62, s26, 0x40000
	s_mov_b64 s[98:99], s[26:27]
	s_addc_u32 s63, s27, 0
	s_add_i32 s51, s49, s31
	global_load_lds_dwordx4 v160, s[26:27]
	s_mov_b32 m0, s51
	s_mov_b64 s[100:101], s[28:29]
	global_load_lds_dwordx4 v156, s[62:63]
	s_add_i32 m0, s51, 0x2000
	s_nop 0
	global_load_lds_dwordx4 v160, s[62:63]
	s_mov_b32 m0, s33
	s_nop 0
	global_load_lds_dwordx4 v154, s[28:29]
	s_mov_b32 m0, s34
	s_nop 0
	global_load_lds_dwordx4 v158, s[28:29]
	s_waitcnt vmcnt(8)
	s_waitcnt lgkmcnt(0)
	s_barrier
	s_waitcnt lgkmcnt(0)
	v_mfma_f32_16x16x32_bf16 v[62:65], v[130:133], v[178:181], v[62:65]
	v_mfma_f32_16x16x32_bf16 v[58:61], v[138:141], v[178:181], v[58:61]
	v_mfma_f32_16x16x32_bf16 v[46:49], v[130:133], v[196:199], v[46:49]
	v_mfma_f32_16x16x32_bf16 v[42:45], v[138:141], v[196:199], v[42:45]
	v_mfma_f32_16x16x32_bf16 v[30:33], v[130:133], v[204:207], v[30:33]
	v_mfma_f32_16x16x32_bf16 v[26:29], v[138:141], v[204:207], v[26:29]
	v_mfma_f32_16x16x32_bf16 v[14:17], v[130:133], v[212:215], v[14:17]
	v_mfma_f32_16x16x32_bf16 v[10:13], v[138:141], v[212:215], v[10:13]
	v_mfma_f32_16x16x32_bf16 v[62:65], v[134:137], v[182:185], v[62:65]
	v_mfma_f32_16x16x32_bf16 v[58:61], v[142:145], v[182:185], v[58:61]
	v_mfma_f32_16x16x32_bf16 v[46:49], v[134:137], v[200:203], v[46:49]
	v_mfma_f32_16x16x32_bf16 v[42:45], v[142:145], v[200:203], v[42:45]
	v_mfma_f32_16x16x32_bf16 v[30:33], v[134:137], v[208:211], v[30:33]
	v_mfma_f32_16x16x32_bf16 v[26:29], v[142:145], v[208:211], v[26:29]
	v_mfma_f32_16x16x32_bf16 v[14:17], v[134:137], v[216:219], v[14:17]
	v_mfma_f32_16x16x32_bf16 v[10:13], v[142:145], v[216:219], v[10:13]
	v_mfma_f32_16x16x32_bf16 v[54:57], v[146:149], v[178:181], v[54:57]
	v_mfma_f32_16x16x32_bf16 v[50:53], v[170:173], v[178:181], v[50:53]
	v_mfma_f32_16x16x32_bf16 v[38:41], v[146:149], v[196:199], v[38:41]
	v_mfma_f32_16x16x32_bf16 v[34:37], v[170:173], v[196:199], v[34:37]
	v_mfma_f32_16x16x32_bf16 v[22:25], v[146:149], v[204:207], v[22:25]
	v_mfma_f32_16x16x32_bf16 v[18:21], v[170:173], v[204:207], v[18:21]
	v_mfma_f32_16x16x32_bf16 v[6:9], v[146:149], v[212:215], v[6:9]
	v_mfma_f32_16x16x32_bf16 v[2:5], v[170:173], v[212:215], v[2:5]
	v_mfma_f32_16x16x32_bf16 v[54:57], v[150:153], v[182:185], v[54:57]
	v_mfma_f32_16x16x32_bf16 v[50:53], v[174:177], v[182:185], v[50:53]
	v_mfma_f32_16x16x32_bf16 v[38:41], v[150:153], v[200:203], v[38:41]
	v_mfma_f32_16x16x32_bf16 v[34:37], v[174:177], v[200:203], v[34:37]
	v_mfma_f32_16x16x32_bf16 v[22:25], v[150:153], v[208:211], v[22:25]
	v_mfma_f32_16x16x32_bf16 v[18:21], v[174:177], v[208:211], v[18:21]
	v_mfma_f32_16x16x32_bf16 v[6:9], v[150:153], v[216:219], v[6:9]
	v_mfma_f32_16x16x32_bf16 v[2:5], v[174:177], v[216:219], v[2:5]
	s_barrier
; #define PG8_STAGE(bufoff, gbase, voff) do { _Pragma("unroll") for (int _i = 0; _i < 2; ++_i) \
;         __builtin_amdgcn_global_load_lds((const unsigned*)((const char*)(gbase) + (voff)[_i]), (LAS unsigned*)(lds + (bufoff) + ldsw + _i * 8192), 16, 0, 0); } while (0)
; #define PG8_LDA(dst, b, h) do { _Pragma("unroll") for (int m = 0; m < 4; ++m) _Pragma("unroll") for (int k = 0; k < 2; ++k) dst[m][k] = *(const LAS bf16x8*)(lds + PG8_SA(b, h) + aoff + m * 2048 + k * 1024); } while (0)
; #define PG8_LDB(dst, b, h) do { _Pragma("unroll") for (int n = 0; n < 2; ++n) _Pragma("unroll") for (int k = 0; k < 2; ++k) dst[n][k] = *(const LAS bf16x8*)(lds + PG8_SB(b, h) + boff + n * 2048 + k * 1024); } while (0)
; #define PG8_MMA(ai, bj, At, Bt) do { __builtin_amdgcn_s_setprio(1); _Pragma("unroll") for (int m = 0; m < 4; ++m) _Pragma("unroll") for (int n = 0; n < 2; ++n) _Pragma("unroll") for (int k = 0; k < 2; ++k) \
;         acc[ai][bj][m][n] = __builtin_amdgcn_mfma_f32_16x16x32_bf16(Bt[n][k], At[m][k], acc[ai][bj][m][n], 0, 0, 0); __builtin_amdgcn_s_setprio(0); } while (0)
; #define PG8_WAIT_V(n) asm volatile("s_waitcnt vmcnt(" #n ")" ::: "memory")
; #define PG8_WAIT_L(n) asm volatile("s_waitcnt lgkmcnt(" #n ")" ::: "memory")
; #define PG8_BAR __builtin_amdgcn_s_barrier()
; #define PG8_SCHED __builtin_amdgcn_sched_barrier(0)
; template <class Epi, class Sched>
; __device__ __forceinline__ void gemm_phase(LAS unsigned char* lds, const int lda, const int ldb, const int K, const Sched& S, const Epi& E) {
;     ...
;             PG8_LDB(B0, 1, 0); PG8_LDB(B1, 1, 1); PG8_SCHED; PG8_LDA(At, 1, 0); PG8_STAGE(PG8_SA(0, 1), a2 + hstepA, voffA);
;             PG8_WAIT_V(8); PG8_WAIT_L(0); PG8_BAR; PG8_MMA(0, 0, At, B0); PG8_MMA(0, 1, At, B1); PG8_BAR; PG8_SCHED;
;             PG8_LDA(At, 1, 1); PG8_STAGE(PG8_SB(1, 0), b3, voffB); PG8_STAGE(PG8_SB(1, 1), b3 + hstepB, voffB); PG8_STAGE(PG8_SA(1, 0), a3, voffA);
;             PG8_WAIT_V(8); PG8_WAIT_L(0); PG8_BAR;
;             if (last) E.pre(cur, wr, fr, rsv);
;             PG8_MMA(1, 0, At, B0); PG8_MMA(1, 1, At, B1); PG8_BAR; PG8_SCHED;
;         }
.Lpeel5_join:
	s_add_i32 s51, 0, 0x18000
	s_add_i32 s62, 0, 0x1c000
	v_add_u32_e32 v142, s51, v186
	v_add_u32_e32 v174, s62, v186
	ds_read_b128 v[130:133], v142
	ds_read_b128 v[134:137], v142 offset:1024
	ds_read_b128 v[138:141], v142 offset:2048
	ds_read_b128 v[142:145], v142 offset:3072
	ds_read_b128 v[146:149], v174
	ds_read_b128 v[150:153], v174 offset:1024
	ds_read_b128 v[170:173], v174 offset:2048
	ds_read_b128 v[174:177], v174 offset:3072
	s_add_u32 s28, s28, 0x40000
	s_addc_u32 s29, s29, 0
	s_mov_b32 m0, s35
	ds_read_b128 v[178:181], v190 offset:32768
	ds_read_b128 v[182:185], v190 offset:33792
	ds_read_b128 v[196:199], v190 offset:34816
	ds_read_b128 v[200:203], v190 offset:35840
	ds_read_b128 v[204:207], v190 offset:36864
	ds_read_b128 v[208:211], v190 offset:37888
	ds_read_b128 v[212:215], v190 offset:38912
	ds_read_b128 v[216:219], v190 offset:39936
	global_load_lds_dwordx4 v154, s[28:29]
	s_mov_b32 m0, s38
	s_nop 0
	global_load_lds_dwordx4 v158, s[28:29]
	s_waitcnt vmcnt(8)
	s_waitcnt lgkmcnt(0)
	s_barrier
	s_waitcnt lgkmcnt(0)
	v_mfma_f32_16x16x32_bf16 v[126:129], v[130:133], v[178:181], v[126:129]
	v_mfma_f32_16x16x32_bf16 v[122:125], v[138:141], v[178:181], v[122:125]
	v_mfma_f32_16x16x32_bf16 v[110:113], v[130:133], v[196:199], v[110:113]
	v_mfma_f32_16x16x32_bf16 v[106:109], v[138:141], v[196:199], v[106:109]
	v_mfma_f32_16x16x32_bf16 v[94:97], v[130:133], v[204:207], v[94:97]
	v_mfma_f32_16x16x32_bf16 v[90:93], v[138:141], v[204:207], v[90:93]
	v_mfma_f32_16x16x32_bf16 v[78:81], v[130:133], v[212:215], v[78:81]
	v_mfma_f32_16x16x32_bf16 v[74:77], v[138:141], v[212:215], v[74:77]
	v_mfma_f32_16x16x32_bf16 v[126:129], v[134:137], v[182:185], v[126:129]
	v_mfma_f32_16x16x32_bf16 v[122:125], v[142:145], v[182:185], v[122:125]
	v_mfma_f32_16x16x32_bf16 v[110:113], v[134:137], v[200:203], v[110:113]
	v_mfma_f32_16x16x32_bf16 v[106:109], v[142:145], v[200:203], v[106:109]
	v_mfma_f32_16x16x32_bf16 v[94:97], v[134:137], v[208:211], v[94:97]
	v_mfma_f32_16x16x32_bf16 v[90:93], v[142:145], v[208:211], v[90:93]
	v_mfma_f32_16x16x32_bf16 v[78:81], v[134:137], v[216:219], v[78:81]
	v_mfma_f32_16x16x32_bf16 v[74:77], v[142:145], v[216:219], v[74:77]
	v_mfma_f32_16x16x32_bf16 v[118:121], v[146:149], v[178:181], v[118:121]
	v_mfma_f32_16x16x32_bf16 v[114:117], v[170:173], v[178:181], v[114:117]
	v_mfma_f32_16x16x32_bf16 v[102:105], v[146:149], v[196:199], v[102:105]
	v_mfma_f32_16x16x32_bf16 v[98:101], v[170:173], v[196:199], v[98:101]
	v_mfma_f32_16x16x32_bf16 v[86:89], v[146:149], v[204:207], v[86:89]
	v_mfma_f32_16x16x32_bf16 v[82:85], v[170:173], v[204:207], v[82:85]
	v_mfma_f32_16x16x32_bf16 v[70:73], v[146:149], v[212:215], v[70:73]
	v_mfma_f32_16x16x32_bf16 v[66:69], v[170:173], v[212:215], v[66:69]
	v_mfma_f32_16x16x32_bf16 v[118:121], v[150:153], v[182:185], v[118:121]
	v_mfma_f32_16x16x32_bf16 v[114:117], v[174:177], v[182:185], v[114:117]
	v_mfma_f32_16x16x32_bf16 v[102:105], v[150:153], v[200:203], v[102:105]
	v_mfma_f32_16x16x32_bf16 v[98:101], v[174:177], v[200:203], v[98:101]
	v_mfma_f32_16x16x32_bf16 v[86:89], v[150:153], v[208:211], v[86:89]
	v_mfma_f32_16x16x32_bf16 v[82:85], v[174:177], v[208:211], v[82:85]
	v_mfma_f32_16x16x32_bf16 v[70:73], v[150:153], v[216:219], v[70:73]
	v_mfma_f32_16x16x32_bf16 v[66:69], v[174:177], v[216:219], v[66:69]
	s_barrier
	s_add_i32 s28, s51, s31
	s_mov_b32 m0, s28
	ds_read_b128 v[178:181], v190 offset:49152
	ds_read_b128 v[182:185], v190 offset:50176
	ds_read_b128 v[196:199], v190 offset:51200
	ds_read_b128 v[200:203], v190 offset:52224
	ds_read_b128 v[204:207], v190 offset:53248
	ds_read_b128 v[208:211], v190 offset:54272
	ds_read_b128 v[212:215], v190 offset:55296
	ds_read_b128 v[216:219], v190 offset:56320
	global_load_lds_dwordx4 v192, s[26:27]
	s_add_i32 m0, s28, 0x2000
	s_add_u32 s26, s26, 0x40080
	s_addc_u32 s27, s27, 0
	s_add_i32 s28, s62, s31
	global_load_lds_dwordx4 v193, s[98:99]
	s_mov_b32 m0, s28
	s_nop 0
	global_load_lds_dwordx4 v156, s[26:27]
	s_add_i32 m0, s28, 0x2000
	s_nop 0
	global_load_lds_dwordx4 v160, s[26:27]
	s_mov_b32 m0, s41
	s_nop 0
	global_load_lds_dwordx4 v220, s[100:101]
	s_mov_b32 m0, s42
	s_nop 0
	global_load_lds_dwordx4 v221, s[100:101]
	s_waitcnt vmcnt(8)
	s_waitcnt lgkmcnt(0)
	s_barrier
	s_waitcnt lgkmcnt(0)
	v_mfma_f32_16x16x32_bf16 v[62:65], v[130:133], v[178:181], v[62:65]
	v_mfma_f32_16x16x32_bf16 v[58:61], v[138:141], v[178:181], v[58:61]
	v_mfma_f32_16x16x32_bf16 v[46:49], v[130:133], v[196:199], v[46:49]
	v_mfma_f32_16x16x32_bf16 v[42:45], v[138:141], v[196:199], v[42:45]
	v_mfma_f32_16x16x32_bf16 v[30:33], v[130:133], v[204:207], v[30:33]
	v_mfma_f32_16x16x32_bf16 v[26:29], v[138:141], v[204:207], v[26:29]
	v_mfma_f32_16x16x32_bf16 v[14:17], v[130:133], v[212:215], v[14:17]
	v_mfma_f32_16x16x32_bf16 v[10:13], v[138:141], v[212:215], v[10:13]
	v_mfma_f32_16x16x32_bf16 v[62:65], v[134:137], v[182:185], v[62:65]
	v_mfma_f32_16x16x32_bf16 v[58:61], v[142:145], v[182:185], v[58:61]
	v_mfma_f32_16x16x32_bf16 v[46:49], v[134:137], v[200:203], v[46:49]
	v_mfma_f32_16x16x32_bf16 v[42:45], v[142:145], v[200:203], v[42:45]
	v_mfma_f32_16x16x32_bf16 v[30:33], v[134:137], v[208:211], v[30:33]
	v_mfma_f32_16x16x32_bf16 v[26:29], v[142:145], v[208:211], v[26:29]
	v_mfma_f32_16x16x32_bf16 v[14:17], v[134:137], v[216:219], v[14:17]
	v_mfma_f32_16x16x32_bf16 v[10:13], v[142:145], v[216:219], v[10:13]
	v_mfma_f32_16x16x32_bf16 v[54:57], v[146:149], v[178:181], v[54:57]
	v_mfma_f32_16x16x32_bf16 v[50:53], v[170:173], v[178:181], v[50:53]
	v_mfma_f32_16x16x32_bf16 v[38:41], v[146:149], v[196:199], v[38:41]
	v_mfma_f32_16x16x32_bf16 v[34:37], v[170:173], v[196:199], v[34:37]
	v_mfma_f32_16x16x32_bf16 v[22:25], v[146:149], v[204:207], v[22:25]
	v_mfma_f32_16x16x32_bf16 v[18:21], v[170:173], v[204:207], v[18:21]
	v_mfma_f32_16x16x32_bf16 v[6:9], v[146:149], v[212:215], v[6:9]
	v_mfma_f32_16x16x32_bf16 v[2:5], v[170:173], v[212:215], v[2:5]
	v_mfma_f32_16x16x32_bf16 v[54:57], v[150:153], v[182:185], v[54:57]
	v_mfma_f32_16x16x32_bf16 v[50:53], v[174:177], v[182:185], v[50:53]
	v_mfma_f32_16x16x32_bf16 v[38:41], v[150:153], v[200:203], v[38:41]
	v_mfma_f32_16x16x32_bf16 v[34:37], v[174:177], v[200:203], v[34:37]
	v_mfma_f32_16x16x32_bf16 v[22:25], v[150:153], v[208:211], v[22:25]
	v_mfma_f32_16x16x32_bf16 v[18:21], v[174:177], v[208:211], v[18:21]
	v_mfma_f32_16x16x32_bf16 v[6:9], v[150:153], v[216:219], v[6:9]
	v_mfma_f32_16x16x32_bf16 v[2:5], v[174:177], v[216:219], v[2:5]
	s_barrier
	s_add_i32 s23, s23, 2
	s_add_u32 s24, s24, 0x100
	s_addc_u32 s25, s25, 0
	s_add_u32 s15, s15, 0x100
	s_addc_u32 s17, s17, 0
	s_cmp_gt_u32 s23, 13
	s_cbranch_scc0 .LBB0_956
	s_and_b64 vcc, exec, s[12:13]
	s_cbranch_vccz .LBB0_959
	s_barrier

; #define PG8_STAGE(bufoff, gbase, voff) do { _Pragma("unroll") for (int _i = 0; _i < 2; ++_i) \
;         __builtin_amdgcn_global_load_lds((const unsigned*)((const char*)(gbase) + (voff)[_i]), (LAS unsigned*)(lds + (bufoff) + ldsw + _i * 8192), 16, 0, 0); } while (0)
; #define PG8_BAR __builtin_amdgcn_s_barrier()
; template <class Epi, class Sched>
; __device__ __forceinline__ void gemm_phase(LAS unsigned char* lds, const int lda, const int ldb, const int K, const Sched& S, const Epi& E) {
;     const int tid = threadIdx.x, wid = __builtin_amdgcn_readfirstlane(tid >> 6), lane = tid & 63, wr = wid >> 2, wc = wid & 3, fr = lane & 15, fq = lane >> 4;
;     const int nt = K / BK;
;     unsigned voffA[2], voffB[2];
; #pragma unroll
;     for (int i = 0; i < 2; ++i) { int R, C; stage_rc(tid * 16 + i * 8192, R, C); const int Rb = (R & ~31) + perm32(R & 31);
;         voffA[i] = (unsigned)(R * lda + C) * 2u; voffB[i] = (unsigned)(Rb * ldb + C) * 2u; }
;     const size_t kstep = (size_t)(BK * 2);
;     const size_t hstepA = (size_t)HALF * lda * 2, hstepB = (size_t)HALF * ldb * 2;
;     const unsigned ldsw = (unsigned)wid * 1024u;
;     const int aoff = lds_byte(wr * 64 + fr, fq * 8), boff = lds_byte(wc * 32 + fr, fq * 8);
;     ...
;     Unit cur, nxt; int ui = 0;
;     if (!S.next(0, cur)) return;
;     f32x4 acc[2][2][4][2];
; #pragma unroll
;     for (int a = 0; a < 2; ++a)
; #pragma unroll
;         for (int b = 0; b < 2; ++b)
; #pragma unroll
;             for (int m = 0; m < 4; ++m)
; #pragma unroll
;                 for (int n = 0; n < 2; ++n) acc[a][b][m][n] = (f32x4){0.f, 0.f, 0.f, 0.f};
;     bf16x8 At[4][2], B0[2][2], B1[2][2];
;     float rsv[8];
; #pragma unroll
;     for (int i = 0; i < 8; ++i) rsv[i] = 0.f;
;     const char* cA = cur.A; const char* cB = cur.B;
;     PG8_STAGE(PG8_SB(0, 0), cB, voffB); PG8_STAGE(PG8_SB(0, 1), cB + hstepB, voffB); PG8_STAGE(PG8_SA(0, 0), cA, voffA); PG8_STAGE(PG8_SA(0, 1), cA + hstepA, voffA);
;     if (wr == 1) PG8_BAR;
.LBB0_1043:
	s_cmp_lt_i32 s56, 9
	s_cselect_b64 s[4:5], -1, 0
	s_and_b64 s[4:5], s[4:5], s[0:1]
	s_andn2_b64 vcc, exec, s[4:5]
	s_cbranch_vccnz .LBB0_1062
	s_cmpk_gt_i32 s2, 0x20ff
	v_readfirstlane_b32 s1, v194
	s_cbranch_scc1 .LBB0_1062
	v_lshrrev_b32_e32 v1, 5, v194
	s_waitcnt lgkmcnt(0)
	v_lshrrev_b32_e32 v3, 1, v194
	v_and_b32_e32 v1, 4, v1
	v_bfe_u32 v2, v194, 2, 2
	v_and_b32_e32 v13, 24, v3
	v_or3_b32 v1, v1, v2, v13
	v_lshlrev_b32_e32 v2, 4, v194
	v_add_u32_e32 v10, 0x2000, v2
	v_lshrrev_b32_e32 v3, 7, v10
	s_movk_i32 s0, 0xe0
	v_and_b32_e32 v5, 32, v194
	v_and_or_b32 v4, v3, s0, v1
	v_bitop3_b32 v11, v2, v5, 48 bitop3:0x6c
	v_and_b32_e32 v12, 64, v194
	v_bfe_u32 v14, v194, 2, 4
	s_movk_i32 s0, 0xf0
	v_or_b32_e32 v2, v11, v12
	v_and_or_b32 v3, v3, s0, v14
	s_add_u32 s3, s54, 0x1e08000
	v_lshl_or_b32 v198, v3, 11, v2
	v_lshrrev_b32_e32 v3, 3, v194
	s_movk_i32 s0, 0x60
	s_addc_u32 s33, s55, 0
	v_and_or_b32 v1, v3, s0, v1
	s_movk_i32 s0, 0x70
	s_ashr_i32 s37, s2, 31
	v_lshl_or_b32 v200, v1, 11, v2
	v_and_or_b32 v1, v3, s0, v14
	s_lshr_b32 s0, s37, 29
	s_add_i32 s0, s2, s0
	s_lshr_b32 s8, s1, 6
	s_and_b32 s6, s0, -8
	s_lshr_b32 s10, s1, 8
	s_lshl_b32 s36, s8, 10
	s_sub_i32 s6, s2, s6
	s_cmp_lt_i32 s6, 0
	s_movk_i32 s38, 0x421
	s_cselect_b32 s7, s38, 0x420
	s_mul_i32 s6, s6, s7
	s_ashr_i32 s0, s0, 3
	s_add_i32 s6, s6, s0
	s_mul_hi_i32 s0, s6, 0x2e8ba2e9
	s_lshr_b32 s7, s0, 31
	s_ashr_i32 s0, s0, 5
	s_add_i32 s0, s0, s7
	s_lshl_b32 s7, s0, 3
	s_mulk_i32 s0, 0xb0
	s_sub_i32 s0, s6, s0
	s_bfe_u32 s6, s0, 0x3001c
	s_add_i32 s6, s0, s6
	s_and_b32 s9, s6, 0xfff8
	s_sub_i32 s0, s0, s9
	s_sext_i32_i16 s0, s0
	s_add_i32 s20, s7, s0
	s_sext_i32_i16 s0, s6
	s_ashr_i32 s21, s20, 31
	s_lshr_b32 s0, s0, 3
	s_lshl_b64 s[6:7], s[20:21], 19
	s_add_u32 s22, s60, s6
	s_addc_u32 s23, s61, s7
	s_bfe_i64 s[6:7], s[0:1], 0x100000
	s_lshl_b64 s[6:7], s[6:7], 19
	s_add_u32 s24, s3, s6
	s_addc_u32 s25, s33, s7
	s_add_i32 s39, s36, 0
	s_add_i32 m0, s39, 0x10000
	v_lshl_or_b32 v196, v4, 11, v2
	global_load_lds_dwordx4 v200, s[24:25]
	s_add_i32 m0, s39, 0x12000
	s_add_u32 s6, s24, 0x40000
	global_load_lds_dwordx4 v196, s[24:25]
	s_addc_u32 s7, s25, 0
	s_add_i32 m0, s39, 0x14000
	s_add_i32 s40, s39, 0x2000
	global_load_lds_dwordx4 v200, s[6:7]
	s_add_i32 m0, s39, 0x16000
	v_lshl_or_b32 v202, v1, 11, v2
	global_load_lds_dwordx4 v196, s[6:7]
	s_mov_b32 m0, s39
	s_add_u32 s6, s22, 0x40000
	global_load_lds_dwordx4 v202, s[22:23]
	s_mov_b32 m0, s40
	s_addc_u32 s7, s23, 0
	s_add_i32 s41, s39, 0x4000
	global_load_lds_dwordx4 v198, s[22:23]
	s_mov_b32 m0, s41
	s_add_i32 s42, s39, 0x6000
	global_load_lds_dwordx4 v202, s[6:7]
	s_mov_b32 m0, s42
	v_mov_b32_e32 v201, 0
	global_load_lds_dwordx4 v198, s[6:7]
	v_mov_b32_e32 v197, v201
	v_mov_b32_e32 v203, v201
	v_mov_b32_e32 v199, v201
	s_cmp_eq_u32 s10, 1
	s_mov_b32 s43, 0
	v_lshl_add_u64 v[8:9], s[24:25], 0, v[200:201]
	v_lshl_add_u64 v[6:7], s[24:25], 0, v[196:197]
	v_lshl_add_u64 v[2:3], s[22:23], 0, v[202:203]
	s_cselect_b64 s[6:7], -1, 0
	s_cmp_lg_u32 s10, 1
	v_lshl_add_u64 v[4:5], s[22:23], 0, v[198:199]
	s_cbranch_scc1 .LBB0_1047
	s_setprio 1
	s_barrier

; #define PG8_STAGE(bufoff, gbase, voff) do { _Pragma("unroll") for (int _i = 0; _i < 2; ++_i) \
;         __builtin_amdgcn_global_load_lds((const unsigned*)((const char*)(gbase) + (voff)[_i]), (LAS unsigned*)(lds + (bufoff) + ldsw + _i * 8192), 16, 0, 0); } while (0)
; #define PG8_LDA(dst, b, h) do { _Pragma("unroll") for (int m = 0; m < 4; ++m) _Pragma("unroll") for (int k = 0; k < 2; ++k) dst[m][k] = *(const LAS bf16x8*)(lds + PG8_SA(b, h) + aoff + m * 2048 + k * 1024); } while (0)
; #define PG8_LDB(dst, b, h) do { _Pragma("unroll") for (int n = 0; n < 2; ++n) _Pragma("unroll") for (int k = 0; k < 2; ++k) dst[n][k] = *(const LAS bf16x8*)(lds + PG8_SB(b, h) + boff + n * 2048 + k * 1024); } while (0)
; #define PG8_MMA(ai, bj, At, Bt) do { __builtin_amdgcn_s_setprio(1); _Pragma("unroll") for (int m = 0; m < 4; ++m) _Pragma("unroll") for (int n = 0; n < 2; ++n) _Pragma("unroll") for (int k = 0; k < 2; ++k) \
;         acc[ai][bj][m][n] = __builtin_amdgcn_mfma_f32_16x16x32_bf16(Bt[n][k], At[m][k], acc[ai][bj][m][n], 0, 0, 0); __builtin_amdgcn_s_setprio(0); } while (0)
; #define PG8_WAIT_V(n) asm volatile("s_waitcnt vmcnt(" #n ")" ::: "memory")
; template <class Epi, class Sched>
; __device__ __forceinline__ void gemm_phase(LAS unsigned char* lds, const int lda, const int ldb, const int K, const Sched& S, const Epi& E) {
;     ...
;         const bool has_next = S.next(ui + 1, nxt);
;         const char* nA = has_next ? nxt.A : cA; const char* nB = has_next ? nxt.B : cB;
;         for (int t = 0; t < nt; t += 2) {
;             const bool last = (t == nt - 2);
;             const char* a1 = cA + (size_t)(t + 1) * kstep;
;             const char* a2 = last ? nA : cA + (size_t)(t + 2) * kstep; const char* b2 = last ? nB : cB + (size_t)(t + 2) * kstep;
;             const char* a3 = a2 + kstep; const char* b3 = b2 + kstep;
;             PG8_LDB(B0, 0, 0); PG8_LDB(B1, 0, 1); PG8_SCHED; PG8_LDA(At, 0, 0); PG8_STAGE(PG8_SA(1, 1), a1 + hstepA, voffA);
;             PG8_WAIT_V(8); PG8_WAIT_L(0); PG8_BAR; PG8_MMA(0, 0, At, B0); PG8_MMA(0, 1, At, B1); PG8_BAR; PG8_SCHED;
;             PG8_LDA(At, 0, 1); PG8_STAGE(PG8_SB(0, 0), b2, voffB); PG8_STAGE(PG8_SB(0, 1), b2 + hstepB, voffB); PG8_STAGE(PG8_SA(0, 0), a2, voffA);
;             PG8_WAIT_V(8); PG8_WAIT_L(0); PG8_BAR; PG8_MMA(1, 0, At, B0); PG8_MMA(1, 1, At, B1); PG8_BAR; PG8_SCHED;
.LBB0_1052:
	s_lshl_b32 s20, s20, 8
	s_ashr_i32 s21, s20, 31
	s_add_u32 s22, s22, 0x40080
	s_addc_u32 s23, s23, 0
	s_add_u32 s13, s24, 0x100
	v_lshl_add_u64 v[214:215], s[20:21], 2, v[204:205]
	s_addc_u32 s15, s25, 0
	s_mov_b32 s21, -2
	v_add_u32_e32 v230, 0x80, v200
	v_add_u32_e32 v231, 0x80, v196
	v_add_u32_e32 v232, 0x80, v202
	v_add_u32_e32 v233, 0x80, v198
	s_add_u32 s24, s22, 0xfffc0080
	s_addc_u32 s25, s23, -1
	s_cmp_eq_u32 s21, 12
	s_cselect_b32 s29, s17, s25
	s_cselect_b32 s28, s16, s24
	s_cselect_b32 s31, s19, s15
	s_cselect_b32 s30, s18, s13
	s_add_i32 s70, s50, s36
	s_add_i32 m0, s39, 0xc000
	s_add_i32 s69, s39, 0xe000
	s_add_i32 s71, s70, 0x2000
	s_add_u32 s34, s30, 0x40000
	s_addc_u32 s35, s31, 0
	s_add_i32 s72, s51, s36
	s_add_i32 s73, s72, 0x2000
	s_add_i32 s74, 0, 0x18000
	s_add_i32 s75, 0, 0x1c000
	s_add_u32 s26, s28, 0x40000
	s_addc_u32 s27, s29, 0
	s_add_i32 s66, s74, s36
	s_add_i32 s65, s66, 0x2000
	s_add_u32 s24, s30, 0x40080
	s_addc_u32 s25, s31, 0
	s_add_i32 s68, s75, s36
	s_add_i32 s67, s68, 0x2000
	s_cmp_lg_u32 s21, 12
	global_load_lds_dwordx4 v206, s[22:23]
	s_mov_b32 m0, s69
	s_nop 0
	global_load_lds_dwordx4 v208, s[22:23]
	s_waitcnt vmcnt(8)
	s_waitcnt lgkmcnt(0)
	s_barrier
	s_waitcnt lgkmcnt(0)
	v_mfma_f32_16x16x32_bf16 v[126:129], v[130:133], v[162:165], 0
	v_mfma_f32_16x16x32_bf16 v[118:121], v[138:141], v[162:165], 0
	v_mfma_f32_16x16x32_bf16 v[110:113], v[130:133], v[170:173], 0
	v_mfma_f32_16x16x32_bf16 v[102:105], v[138:141], v[170:173], 0
	v_mfma_f32_16x16x32_bf16 v[94:97], v[130:133], v[178:181], 0
	v_mfma_f32_16x16x32_bf16 v[86:89], v[138:141], v[178:181], 0
	v_mfma_f32_16x16x32_bf16 v[78:81], v[130:133], v[186:189], 0
	v_mfma_f32_16x16x32_bf16 v[70:73], v[138:141], v[186:189], 0
	v_mfma_f32_16x16x32_bf16 v[126:129], v[134:137], v[166:169], v[126:129]
	v_mfma_f32_16x16x32_bf16 v[118:121], v[142:145], v[166:169], v[118:121]
	v_mfma_f32_16x16x32_bf16 v[110:113], v[134:137], v[174:177], v[110:113]
	v_mfma_f32_16x16x32_bf16 v[102:105], v[142:145], v[174:177], v[102:105]
	v_mfma_f32_16x16x32_bf16 v[94:97], v[134:137], v[182:185], v[94:97]
	v_mfma_f32_16x16x32_bf16 v[86:89], v[142:145], v[182:185], v[86:89]
	v_mfma_f32_16x16x32_bf16 v[78:81], v[134:137], v[190:193], v[78:81]
	v_mfma_f32_16x16x32_bf16 v[70:73], v[142:145], v[190:193], v[70:73]
	v_mfma_f32_16x16x32_bf16 v[122:125], v[146:149], v[162:165], 0
	v_mfma_f32_16x16x32_bf16 v[114:117], v[154:157], v[162:165], 0
	v_mfma_f32_16x16x32_bf16 v[106:109], v[146:149], v[170:173], 0
	v_mfma_f32_16x16x32_bf16 v[98:101], v[154:157], v[170:173], 0
	v_mfma_f32_16x16x32_bf16 v[90:93], v[146:149], v[178:181], 0
	v_mfma_f32_16x16x32_bf16 v[82:85], v[154:157], v[178:181], 0
	v_mfma_f32_16x16x32_bf16 v[74:77], v[146:149], v[186:189], 0
	v_mfma_f32_16x16x32_bf16 v[66:69], v[154:157], v[186:189], 0
	v_mfma_f32_16x16x32_bf16 v[122:125], v[150:153], v[166:169], v[122:125]
	v_mfma_f32_16x16x32_bf16 v[114:117], v[158:161], v[166:169], v[114:117]
	v_mfma_f32_16x16x32_bf16 v[106:109], v[150:153], v[174:177], v[106:109]
	v_mfma_f32_16x16x32_bf16 v[98:101], v[158:161], v[174:177], v[98:101]
	v_mfma_f32_16x16x32_bf16 v[90:93], v[150:153], v[182:185], v[90:93]
	v_mfma_f32_16x16x32_bf16 v[82:85], v[158:161], v[182:185], v[82:85]
	v_mfma_f32_16x16x32_bf16 v[74:77], v[150:153], v[190:193], v[74:77]
	v_mfma_f32_16x16x32_bf16 v[66:69], v[158:161], v[190:193], v[66:69]
	s_barrier
	s_mov_b32 m0, s70
	ds_read_b128 v[162:165], v219 offset:16384
	ds_read_b128 v[166:169], v219 offset:17408
	ds_read_b128 v[170:173], v219 offset:18432
	ds_read_b128 v[174:177], v219 offset:19456
	ds_read_b128 v[178:181], v219 offset:20480
	ds_read_b128 v[182:185], v219 offset:21504
	ds_read_b128 v[186:189], v219 offset:22528
	ds_read_b128 v[190:193], v219 offset:23552
	global_load_lds_dwordx4 v200, s[30:31]
	s_mov_b32 m0, s71
	s_nop 0
	global_load_lds_dwordx4 v196, s[30:31]
	s_mov_b32 m0, s72
	s_nop 0
	global_load_lds_dwordx4 v200, s[34:35]
	s_mov_b32 m0, s73
	s_nop 0
	global_load_lds_dwordx4 v196, s[34:35]
	s_mov_b32 m0, s39
	s_nop 0
	global_load_lds_dwordx4 v202, s[28:29]
	s_mov_b32 m0, s40
	s_nop 0
	global_load_lds_dwordx4 v198, s[28:29]
	s_waitcnt vmcnt(8)
	s_waitcnt lgkmcnt(0)
	s_barrier
	s_waitcnt lgkmcnt(0)
	v_mfma_f32_16x16x32_bf16 v[62:65], v[130:133], v[162:165], 0
	v_mfma_f32_16x16x32_bf16 v[54:57], v[138:141], v[162:165], 0
	v_mfma_f32_16x16x32_bf16 v[46:49], v[130:133], v[170:173], 0
	v_mfma_f32_16x16x32_bf16 v[38:41], v[138:141], v[170:173], 0
	v_mfma_f32_16x16x32_bf16 v[30:33], v[130:133], v[178:181], 0
	v_mfma_f32_16x16x32_bf16 v[22:25], v[138:141], v[178:181], 0
	v_mfma_f32_16x16x32_bf16 v[14:17], v[130:133], v[186:189], 0
	v_mfma_f32_16x16x32_bf16 v[6:9], v[138:141], v[186:189], 0
	v_mfma_f32_16x16x32_bf16 v[62:65], v[134:137], v[166:169], v[62:65]
	v_mfma_f32_16x16x32_bf16 v[54:57], v[142:145], v[166:169], v[54:57]
	v_mfma_f32_16x16x32_bf16 v[46:49], v[134:137], v[174:177], v[46:49]
	v_mfma_f32_16x16x32_bf16 v[38:41], v[142:145], v[174:177], v[38:41]
	v_mfma_f32_16x16x32_bf16 v[30:33], v[134:137], v[182:185], v[30:33]
	v_mfma_f32_16x16x32_bf16 v[22:25], v[142:145], v[182:185], v[22:25]
	v_mfma_f32_16x16x32_bf16 v[14:17], v[134:137], v[190:193], v[14:17]
	v_mfma_f32_16x16x32_bf16 v[6:9], v[142:145], v[190:193], v[6:9]
	v_mfma_f32_16x16x32_bf16 v[58:61], v[146:149], v[162:165], 0
	v_mfma_f32_16x16x32_bf16 v[50:53], v[154:157], v[162:165], 0
	v_mfma_f32_16x16x32_bf16 v[42:45], v[146:149], v[170:173], 0
	v_mfma_f32_16x16x32_bf16 v[34:37], v[154:157], v[170:173], 0
	v_mfma_f32_16x16x32_bf16 v[26:29], v[146:149], v[178:181], 0
	v_mfma_f32_16x16x32_bf16 v[18:21], v[154:157], v[178:181], 0
	v_mfma_f32_16x16x32_bf16 v[10:13], v[146:149], v[186:189], 0
	v_mfma_f32_16x16x32_bf16 v[2:5], v[154:157], v[186:189], 0
	v_mfma_f32_16x16x32_bf16 v[58:61], v[150:153], v[166:169], v[58:61]
	v_mfma_f32_16x16x32_bf16 v[50:53], v[158:161], v[166:169], v[50:53]
	v_mfma_f32_16x16x32_bf16 v[42:45], v[150:153], v[174:177], v[42:45]
	v_mfma_f32_16x16x32_bf16 v[34:37], v[158:161], v[174:177], v[34:37]
	v_mfma_f32_16x16x32_bf16 v[26:29], v[150:153], v[182:185], v[26:29]
	v_mfma_f32_16x16x32_bf16 v[18:21], v[158:161], v[182:185], v[18:21]
	v_mfma_f32_16x16x32_bf16 v[10:13], v[150:153], v[190:193], v[10:13]
	v_mfma_f32_16x16x32_bf16 v[2:5], v[158:161], v[190:193], v[2:5]
	s_barrier
	s_branch .Lpeel6_join
; #define PG8_STAGE(bufoff, gbase, voff) do { _Pragma("unroll") for (int _i = 0; _i < 2; ++_i) \
;         __builtin_amdgcn_global_load_lds((const unsigned*)((const char*)(gbase) + (voff)[_i]), (LAS unsigned*)(lds + (bufoff) + ldsw + _i * 8192), 16, 0, 0); } while (0)
; #define PG8_LDA(dst, b, h) do { _Pragma("unroll") for (int m = 0; m < 4; ++m) _Pragma("unroll") for (int k = 0; k < 2; ++k) dst[m][k] = *(const LAS bf16x8*)(lds + PG8_SA(b, h) + aoff + m * 2048 + k * 1024); } while (0)
; #define PG8_LDB(dst, b, h) do { _Pragma("unroll") for (int n = 0; n < 2; ++n) _Pragma("unroll") for (int k = 0; k < 2; ++k) dst[n][k] = *(const LAS bf16x8*)(lds + PG8_SB(b, h) + boff + n * 2048 + k * 1024); } while (0)
; #define PG8_MMA(ai, bj, At, Bt) do { __builtin_amdgcn_s_setprio(1); _Pragma("unroll") for (int m = 0; m < 4; ++m) _Pragma("unroll") for (int n = 0; n < 2; ++n) _Pragma("unroll") for (int k = 0; k < 2; ++k) \
;         acc[ai][bj][m][n] = __builtin_amdgcn_mfma_f32_16x16x32_bf16(Bt[n][k], At[m][k], acc[ai][bj][m][n], 0, 0, 0); __builtin_amdgcn_s_setprio(0); } while (0)
; template <class Epi, class Sched>
; __device__ __forceinline__ void gemm_phase(LAS unsigned char* lds, const int lda, const int ldb, const int K, const Sched& S, const Epi& E) {
;     ...
;             PG8_LDB(B0, 0, 0); PG8_LDB(B1, 0, 1); PG8_SCHED; PG8_LDA(At, 0, 0); PG8_STAGE(PG8_SA(1, 1), a1 + hstepA, voffA);
;             PG8_WAIT_V(8); PG8_WAIT_L(0); PG8_BAR; PG8_MMA(0, 0, At, B0); PG8_MMA(0, 1, At, B1); PG8_BAR; PG8_SCHED;
;             PG8_LDA(At, 0, 1); PG8_STAGE(PG8_SB(0, 0), b2, voffB); PG8_STAGE(PG8_SB(0, 1), b2 + hstepB, voffB); PG8_STAGE(PG8_SA(0, 0), a2, voffA);
;             PG8_WAIT_V(8); PG8_WAIT_L(0); PG8_BAR; PG8_MMA(1, 0, At, B0); PG8_MMA(1, 1, At, B1); PG8_BAR; PG8_SCHED;
;             PG8_LDB(B0, 1, 0); PG8_LDB(B1, 1, 1); PG8_SCHED; PG8_LDA(At, 1, 0); PG8_STAGE(PG8_SA(0, 1), a2 + hstepA, voffA);
;             PG8_WAIT_V(8); PG8_WAIT_L(0); PG8_BAR; PG8_MMA(0, 0, At, B0); PG8_MMA(0, 1, At, B1); PG8_BAR; PG8_SCHED;
;             PG8_LDA(At, 1, 1); PG8_STAGE(PG8_SB(1, 0), b3, voffB); PG8_STAGE(PG8_SB(1, 1), b3 + hstepB, voffB); PG8_STAGE(PG8_SA(1, 0), a3, voffA);
;             PG8_WAIT_V(8); PG8_WAIT_L(0); PG8_BAR;
;             if (last) E.pre(cur, wr, fr, rsv);
;             PG8_MMA(1, 0, At, B0); PG8_MMA(1, 1, At, B1); PG8_BAR; PG8_SCHED;
.LBB0_1053:
	s_waitcnt lgkmcnt(0)
	v_mfma_f32_16x16x32_bf16 v[62:65], v[146:149], v[186:189], v[62:65]
	v_mfma_f32_16x16x32_bf16 v[54:57], v[154:157], v[186:189], v[54:57]
	v_mfma_f32_16x16x32_bf16 v[46:49], v[146:149], v[178:181], v[46:49]
	v_mfma_f32_16x16x32_bf16 v[38:41], v[154:157], v[178:181], v[38:41]
	v_mfma_f32_16x16x32_bf16 v[30:33], v[146:149], v[170:173], v[30:33]
	v_mfma_f32_16x16x32_bf16 v[22:25], v[154:157], v[170:173], v[22:25]
	v_mfma_f32_16x16x32_bf16 v[14:17], v[146:149], v[162:165], v[14:17]
	v_mfma_f32_16x16x32_bf16 v[6:9], v[154:157], v[162:165], v[6:9]
	v_mfma_f32_16x16x32_bf16 v[62:65], v[150:153], v[190:193], v[62:65]
	v_mfma_f32_16x16x32_bf16 v[54:57], v[158:161], v[190:193], v[54:57]
	v_mfma_f32_16x16x32_bf16 v[46:49], v[150:153], v[182:185], v[46:49]
	v_mfma_f32_16x16x32_bf16 v[38:41], v[158:161], v[182:185], v[38:41]
	v_mfma_f32_16x16x32_bf16 v[30:33], v[150:153], v[174:177], v[30:33]
	v_mfma_f32_16x16x32_bf16 v[22:25], v[158:161], v[174:177], v[22:25]
	v_mfma_f32_16x16x32_bf16 v[14:17], v[150:153], v[166:169], v[14:17]
	v_mfma_f32_16x16x32_bf16 v[6:9], v[158:161], v[166:169], v[6:9]
	v_mfma_f32_16x16x32_bf16 v[58:61], v[130:133], v[186:189], v[58:61]
	v_mfma_f32_16x16x32_bf16 v[50:53], v[138:141], v[186:189], v[50:53]
	v_mfma_f32_16x16x32_bf16 v[42:45], v[130:133], v[178:181], v[42:45]
	v_mfma_f32_16x16x32_bf16 v[34:37], v[138:141], v[178:181], v[34:37]
	v_mfma_f32_16x16x32_bf16 v[26:29], v[130:133], v[170:173], v[26:29]
	v_mfma_f32_16x16x32_bf16 v[18:21], v[138:141], v[170:173], v[18:21]
	v_mfma_f32_16x16x32_bf16 v[10:13], v[130:133], v[162:165], v[10:13]
	v_mfma_f32_16x16x32_bf16 v[2:5], v[138:141], v[162:165], v[2:5]
	v_mfma_f32_16x16x32_bf16 v[58:61], v[134:137], v[190:193], v[58:61]
	v_mfma_f32_16x16x32_bf16 v[50:53], v[142:145], v[190:193], v[50:53]
	v_mfma_f32_16x16x32_bf16 v[42:45], v[134:137], v[182:185], v[42:45]
	v_mfma_f32_16x16x32_bf16 v[34:37], v[142:145], v[182:185], v[34:37]
	v_mfma_f32_16x16x32_bf16 v[26:29], v[134:137], v[174:177], v[26:29]
	v_mfma_f32_16x16x32_bf16 v[18:21], v[142:145], v[174:177], v[18:21]
	v_mfma_f32_16x16x32_bf16 v[10:13], v[134:137], v[166:169], v[10:13]
	v_mfma_f32_16x16x32_bf16 v[2:5], v[142:145], v[166:169], v[2:5]
	s_barrier
	s_add_i32 s21, s21, 2
	s_add_u32 s22, s22, 0x100
	s_addc_u32 s23, s23, 0
	s_add_u32 s13, s13, 0x100
	s_addc_u32 s15, s15, 0
	s_cmp_gt_u32 s21, 13
	s_cbranch_scc1 .LBB0_1056
.LBB0_1054:
	s_add_u32 s24, s22, 0xfffc0080
	s_addc_u32 s25, s23, -1
	s_cmp_eq_u32 s21, 12
	s_cselect_b32 s29, s17, s25
	s_cselect_b32 s28, s16, s24
	s_cselect_b32 s31, s19, s15
	s_cselect_b32 s30, s18, s13
	s_add_i32 s70, s50, s36
	ds_read_b128 v[130:133], v217
	ds_read_b128 v[134:137], v217 offset:1024
	ds_read_b128 v[138:141], v217 offset:2048
	ds_read_b128 v[142:145], v217 offset:3072
	ds_read_b128 v[146:149], v218
	ds_read_b128 v[150:153], v218 offset:1024
	ds_read_b128 v[154:157], v218 offset:2048
	ds_read_b128 v[158:161], v218 offset:3072
	s_add_i32 m0, s39, 0xc000
	s_add_i32 s69, s39, 0xe000
	s_add_i32 s71, s70, 0x2000
	s_add_u32 s34, s30, 0x40000
	s_addc_u32 s35, s31, 0
	s_add_i32 s72, s51, s36
	s_add_i32 s73, s72, 0x2000
	s_add_i32 s74, 0, 0x18000
	s_add_i32 s75, 0, 0x1c000
	s_add_u32 s26, s28, 0x40000
	s_addc_u32 s27, s29, 0
	s_add_i32 s66, s74, s36
	s_add_i32 s65, s66, 0x2000
	s_add_u32 s24, s30, 0x40080
	s_addc_u32 s25, s31, 0
	s_add_i32 s68, s75, s36
	s_add_i32 s67, s68, 0x2000
	s_cmp_lg_u32 s21, 12
	ds_read_b128 v[162:165], v219
	ds_read_b128 v[166:169], v219 offset:1024
	ds_read_b128 v[170:173], v219 offset:2048
	ds_read_b128 v[174:177], v219 offset:3072
	ds_read_b128 v[178:181], v219 offset:4096
	ds_read_b128 v[182:185], v219 offset:5120
	ds_read_b128 v[186:189], v219 offset:6144
	ds_read_b128 v[190:193], v219 offset:7168
	global_load_lds_dwordx4 v206, s[22:23]
	s_mov_b32 m0, s69
	s_nop 0
	global_load_lds_dwordx4 v208, s[22:23]
	s_waitcnt vmcnt(8)
	s_waitcnt lgkmcnt(0)
	s_barrier
	s_waitcnt lgkmcnt(0)
	v_mfma_f32_16x16x32_bf16 v[126:129], v[130:133], v[162:165], v[126:129]
	v_mfma_f32_16x16x32_bf16 v[118:121], v[138:141], v[162:165], v[118:121]
	v_mfma_f32_16x16x32_bf16 v[110:113], v[130:133], v[170:173], v[110:113]
	v_mfma_f32_16x16x32_bf16 v[102:105], v[138:141], v[170:173], v[102:105]
	v_mfma_f32_16x16x32_bf16 v[94:97], v[130:133], v[178:181], v[94:97]
	v_mfma_f32_16x16x32_bf16 v[86:89], v[138:141], v[178:181], v[86:89]
	v_mfma_f32_16x16x32_bf16 v[78:81], v[130:133], v[186:189], v[78:81]
	v_mfma_f32_16x16x32_bf16 v[70:73], v[138:141], v[186:189], v[70:73]
	v_mfma_f32_16x16x32_bf16 v[126:129], v[134:137], v[166:169], v[126:129]
	v_mfma_f32_16x16x32_bf16 v[118:121], v[142:145], v[166:169], v[118:121]
	v_mfma_f32_16x16x32_bf16 v[110:113], v[134:137], v[174:177], v[110:113]
	v_mfma_f32_16x16x32_bf16 v[102:105], v[142:145], v[174:177], v[102:105]
	v_mfma_f32_16x16x32_bf16 v[94:97], v[134:137], v[182:185], v[94:97]
	v_mfma_f32_16x16x32_bf16 v[86:89], v[142:145], v[182:185], v[86:89]
	v_mfma_f32_16x16x32_bf16 v[78:81], v[134:137], v[190:193], v[78:81]
	v_mfma_f32_16x16x32_bf16 v[70:73], v[142:145], v[190:193], v[70:73]
	v_mfma_f32_16x16x32_bf16 v[122:125], v[146:149], v[162:165], v[122:125]
	v_mfma_f32_16x16x32_bf16 v[114:117], v[154:157], v[162:165], v[114:117]
	v_mfma_f32_16x16x32_bf16 v[106:109], v[146:149], v[170:173], v[106:109]
	v_mfma_f32_16x16x32_bf16 v[98:101], v[154:157], v[170:173], v[98:101]
	v_mfma_f32_16x16x32_bf16 v[90:93], v[146:149], v[178:181], v[90:93]
	v_mfma_f32_16x16x32_bf16 v[82:85], v[154:157], v[178:181], v[82:85]
	v_mfma_f32_16x16x32_bf16 v[74:77], v[146:149], v[186:189], v[74:77]
	v_mfma_f32_16x16x32_bf16 v[66:69], v[154:157], v[186:189], v[66:69]
	v_mfma_f32_16x16x32_bf16 v[122:125], v[150:153], v[166:169], v[122:125]
	v_mfma_f32_16x16x32_bf16 v[114:117], v[158:161], v[166:169], v[114:117]
	v_mfma_f32_16x16x32_bf16 v[106:109], v[150:153], v[174:177], v[106:109]
	v_mfma_f32_16x16x32_bf16 v[98:101], v[158:161], v[174:177], v[98:101]
	v_mfma_f32_16x16x32_bf16 v[90:93], v[150:153], v[182:185], v[90:93]
	v_mfma_f32_16x16x32_bf16 v[82:85], v[158:161], v[182:185], v[82:85]
	v_mfma_f32_16x16x32_bf16 v[74:77], v[150:153], v[190:193], v[74:77]
	v_mfma_f32_16x16x32_bf16 v[66:69], v[158:161], v[190:193], v[66:69]
	s_barrier
; #define PG8_STAGE(bufoff, gbase, voff) do { _Pragma("unroll") for (int _i = 0; _i < 2; ++_i) \
;         __builtin_amdgcn_global_load_lds((const unsigned*)((const char*)(gbase) + (voff)[_i]), (LAS unsigned*)(lds + (bufoff) + ldsw + _i * 8192), 16, 0, 0); } while (0)
; #define PG8_LDA(dst, b, h) do { _Pragma("unroll") for (int m = 0; m < 4; ++m) _Pragma("unroll") for (int k = 0; k < 2; ++k) dst[m][k] = *(const LAS bf16x8*)(lds + PG8_SA(b, h) + aoff + m * 2048 + k * 1024); } while (0)
; #define PG8_MMA(ai, bj, At, Bt) do { __builtin_amdgcn_s_setprio(1); _Pragma("unroll") for (int m = 0; m < 4; ++m) _Pragma("unroll") for (int n = 0; n < 2; ++n) _Pragma("unroll") for (int k = 0; k < 2; ++k) \
;         acc[ai][bj][m][n] = __builtin_amdgcn_mfma_f32_16x16x32_bf16(Bt[n][k], At[m][k], acc[ai][bj][m][n], 0, 0, 0); __builtin_amdgcn_s_setprio(0); } while (0)
; #define PG8_WAIT_V(n) asm volatile("s_waitcnt vmcnt(" #n ")" ::: "memory")
; #define PG8_WAIT_L(n) asm volatile("s_waitcnt lgkmcnt(" #n ")" ::: "memory")
; #define PG8_BAR __builtin_amdgcn_s_barrier()
; #define PG8_SCHED __builtin_amdgcn_sched_barrier(0)
; template <class Epi, class Sched>
; __device__ __forceinline__ void gemm_phase(LAS unsigned char* lds, const int lda, const int ldb, const int K, const Sched& S, const Epi& E) {
;     ...
;             PG8_LDA(At, 0, 1); PG8_STAGE(PG8_SB(0, 0), b2, voffB); PG8_STAGE(PG8_SB(0, 1), b2 + hstepB, voffB); PG8_STAGE(PG8_SA(0, 0), a2, voffA);
;             PG8_WAIT_V(8); PG8_WAIT_L(0); PG8_BAR; PG8_MMA(1, 0, At, B0); PG8_MMA(1, 1, At, B1); PG8_BAR; PG8_SCHED;
	s_mov_b32 m0, s70
	ds_read_b128 v[162:165], v219 offset:16384
	ds_read_b128 v[166:169], v219 offset:17408
	ds_read_b128 v[170:173], v219 offset:18432
	ds_read_b128 v[174:177], v219 offset:19456
	ds_read_b128 v[178:181], v219 offset:20480
	ds_read_b128 v[182:185], v219 offset:21504
	ds_read_b128 v[186:189], v219 offset:22528
	ds_read_b128 v[190:193], v219 offset:23552
	global_load_lds_dwordx4 v200, s[30:31]
	s_mov_b32 m0, s71
	s_nop 0
	global_load_lds_dwordx4 v196, s[30:31]
	s_mov_b32 m0, s72
	s_nop 0
	global_load_lds_dwordx4 v200, s[34:35]
	s_mov_b32 m0, s73
	s_nop 0
	global_load_lds_dwordx4 v196, s[34:35]
	s_mov_b32 m0, s39
	s_nop 0
	global_load_lds_dwordx4 v202, s[28:29]
	s_mov_b32 m0, s40
	s_nop 0
	global_load_lds_dwordx4 v198, s[28:29]
	s_waitcnt vmcnt(8)
	s_waitcnt lgkmcnt(0)
	s_barrier
	s_waitcnt lgkmcnt(0)
	v_mfma_f32_16x16x32_bf16 v[62:65], v[130:133], v[162:165], v[62:65]
	v_mfma_f32_16x16x32_bf16 v[54:57], v[138:141], v[162:165], v[54:57]
	v_mfma_f32_16x16x32_bf16 v[46:49], v[130:133], v[170:173], v[46:49]
	v_mfma_f32_16x16x32_bf16 v[38:41], v[138:141], v[170:173], v[38:41]
	v_mfma_f32_16x16x32_bf16 v[30:33], v[130:133], v[178:181], v[30:33]
	v_mfma_f32_16x16x32_bf16 v[22:25], v[138:141], v[178:181], v[22:25]
	v_mfma_f32_16x16x32_bf16 v[14:17], v[130:133], v[186:189], v[14:17]
	v_mfma_f32_16x16x32_bf16 v[6:9], v[138:141], v[186:189], v[6:9]
	v_mfma_f32_16x16x32_bf16 v[62:65], v[134:137], v[166:169], v[62:65]
	v_mfma_f32_16x16x32_bf16 v[54:57], v[142:145], v[166:169], v[54:57]
	v_mfma_f32_16x16x32_bf16 v[46:49], v[134:137], v[174:177], v[46:49]
	v_mfma_f32_16x16x32_bf16 v[38:41], v[142:145], v[174:177], v[38:41]
	v_mfma_f32_16x16x32_bf16 v[30:33], v[134:137], v[182:185], v[30:33]
	v_mfma_f32_16x16x32_bf16 v[22:25], v[142:145], v[182:185], v[22:25]
	v_mfma_f32_16x16x32_bf16 v[14:17], v[134:137], v[190:193], v[14:17]
	v_mfma_f32_16x16x32_bf16 v[6:9], v[142:145], v[190:193], v[6:9]
	v_mfma_f32_16x16x32_bf16 v[58:61], v[146:149], v[162:165], v[58:61]
	v_mfma_f32_16x16x32_bf16 v[50:53], v[154:157], v[162:165], v[50:53]
	v_mfma_f32_16x16x32_bf16 v[42:45], v[146:149], v[170:173], v[42:45]
	v_mfma_f32_16x16x32_bf16 v[34:37], v[154:157], v[170:173], v[34:37]
	v_mfma_f32_16x16x32_bf16 v[26:29], v[146:149], v[178:181], v[26:29]
	v_mfma_f32_16x16x32_bf16 v[18:21], v[154:157], v[178:181], v[18:21]
	v_mfma_f32_16x16x32_bf16 v[10:13], v[146:149], v[186:189], v[10:13]
	v_mfma_f32_16x16x32_bf16 v[2:5], v[154:157], v[186:189], v[2:5]
	v_mfma_f32_16x16x32_bf16 v[58:61], v[150:153], v[166:169], v[58:61]
	v_mfma_f32_16x16x32_bf16 v[50:53], v[158:161], v[166:169], v[50:53]
	v_mfma_f32_16x16x32_bf16 v[42:45], v[150:153], v[174:177], v[42:45]
	v_mfma_f32_16x16x32_bf16 v[34:37], v[158:161], v[174:177], v[34:37]
	v_mfma_f32_16x16x32_bf16 v[26:29], v[150:153], v[182:185], v[26:29]
	v_mfma_f32_16x16x32_bf16 v[18:21], v[158:161], v[182:185], v[18:21]
	v_mfma_f32_16x16x32_bf16 v[10:13], v[150:153], v[190:193], v[10:13]
	v_mfma_f32_16x16x32_bf16 v[2:5], v[158:161], v[190:193], v[2:5]
	s_barrier
; #define PG8_STAGE(bufoff, gbase, voff) do { _Pragma("unroll") for (int _i = 0; _i < 2; ++_i) \
;         __builtin_amdgcn_global_load_lds((const unsigned*)((const char*)(gbase) + (voff)[_i]), (LAS unsigned*)(lds + (bufoff) + ldsw + _i * 8192), 16, 0, 0); } while (0)
; #define PG8_LDA(dst, b, h) do { _Pragma("unroll") for (int m = 0; m < 4; ++m) _Pragma("unroll") for (int k = 0; k < 2; ++k) dst[m][k] = *(const LAS bf16x8*)(lds + PG8_SA(b, h) + aoff + m * 2048 + k * 1024); } while (0)
; #define PG8_LDB(dst, b, h) do { _Pragma("unroll") for (int n = 0; n < 2; ++n) _Pragma("unroll") for (int k = 0; k < 2; ++k) dst[n][k] = *(const LAS bf16x8*)(lds + PG8_SB(b, h) + boff + n * 2048 + k * 1024); } while (0)
; #define PG8_MMA(ai, bj, At, Bt) do { __builtin_amdgcn_s_setprio(1); _Pragma("unroll") for (int m = 0; m < 4; ++m) _Pragma("unroll") for (int n = 0; n < 2; ++n) _Pragma("unroll") for (int k = 0; k < 2; ++k) \
;         acc[ai][bj][m][n] = __builtin_amdgcn_mfma_f32_16x16x32_bf16(Bt[n][k], At[m][k], acc[ai][bj][m][n], 0, 0, 0); __builtin_amdgcn_s_setprio(0); } while (0)
; #define PG8_WAIT_V(n) asm volatile("s_waitcnt vmcnt(" #n ")" ::: "memory")
; #define PG8_WAIT_L(n) asm volatile("s_waitcnt lgkmcnt(" #n ")" ::: "memory")
; #define PG8_BAR __builtin_amdgcn_s_barrier()
; template <class Epi, class Sched>
; __device__ __forceinline__ void gemm_phase(LAS unsigned char* lds, const int lda, const int ldb, const int K, const Sched& S, const Epi& E) {
;     ...
;             PG8_LDB(B0, 1, 0); PG8_LDB(B1, 1, 1); PG8_SCHED; PG8_LDA(At, 1, 0); PG8_STAGE(PG8_SA(0, 1), a2 + hstepA, voffA);
;             PG8_WAIT_V(8); PG8_WAIT_L(0); PG8_BAR; PG8_MMA(0, 0, At, B0); PG8_MMA(0, 1, At, B1); PG8_BAR; PG8_SCHED;
;             PG8_LDA(At, 1, 1); PG8_STAGE(PG8_SB(1, 0), b3, voffB); PG8_STAGE(PG8_SB(1, 1), b3 + hstepB, voffB); PG8_STAGE(PG8_SA(1, 0), a3, voffA);
;             PG8_WAIT_V(8); PG8_WAIT_L(0); PG8_BAR;
;             if (last) E.pre(cur, wr, fr, rsv);
;             PG8_MMA(1, 0, At, B0); PG8_MMA(1, 1, At, B1); PG8_BAR; PG8_SCHED;
;     __device__ __forceinline__ void pre(const pg8::Unit& u, int wr, int fr, float (&rsv)[8]) const {
;         const float* p = ss + u.pm * 256 + wr * 64 + fr;
; #pragma unroll
;         for (int ai = 0; ai < 2; ++ai)
; #pragma unroll
;             for (int m = 0; m < 4; ++m) rsv[ai * 4 + m] = p[ai * 128 + m * 16];
;     }
.Lpeel6_join:
	v_add_u32_e32 v130, s74, v195
	v_add_u32_e32 v142, s75, v195
	ds_read_b128 v[146:149], v130
	ds_read_b128 v[150:153], v130 offset:1024
	ds_read_b128 v[154:157], v130 offset:2048
	ds_read_b128 v[158:161], v130 offset:3072
	ds_read_b128 v[130:133], v142
	ds_read_b128 v[134:137], v142 offset:1024
	ds_read_b128 v[138:141], v142 offset:2048
	ds_read_b128 v[142:145], v142 offset:3072
	s_mov_b32 m0, s41
	ds_read_b128 v[162:165], v219 offset:32768
	ds_read_b128 v[166:169], v219 offset:33792
	ds_read_b128 v[170:173], v219 offset:34816
	ds_read_b128 v[174:177], v219 offset:35840
	ds_read_b128 v[178:181], v219 offset:36864
	ds_read_b128 v[182:185], v219 offset:37888
	ds_read_b128 v[186:189], v219 offset:38912
	ds_read_b128 v[190:193], v219 offset:39936
	global_load_lds_dwordx4 v202, s[26:27]
	s_mov_b32 m0, s42
	s_nop 0
	global_load_lds_dwordx4 v198, s[26:27]
	s_waitcnt vmcnt(8)
	s_waitcnt lgkmcnt(0)
	s_barrier
	s_waitcnt lgkmcnt(0)
	v_mfma_f32_16x16x32_bf16 v[126:129], v[146:149], v[162:165], v[126:129]
	v_mfma_f32_16x16x32_bf16 v[118:121], v[154:157], v[162:165], v[118:121]
	v_mfma_f32_16x16x32_bf16 v[110:113], v[146:149], v[170:173], v[110:113]
	v_mfma_f32_16x16x32_bf16 v[102:105], v[154:157], v[170:173], v[102:105]
	v_mfma_f32_16x16x32_bf16 v[94:97], v[146:149], v[178:181], v[94:97]
	v_mfma_f32_16x16x32_bf16 v[86:89], v[154:157], v[178:181], v[86:89]
	v_mfma_f32_16x16x32_bf16 v[78:81], v[146:149], v[186:189], v[78:81]
	v_mfma_f32_16x16x32_bf16 v[70:73], v[154:157], v[186:189], v[70:73]
	v_mfma_f32_16x16x32_bf16 v[126:129], v[150:153], v[166:169], v[126:129]
	v_mfma_f32_16x16x32_bf16 v[118:121], v[158:161], v[166:169], v[118:121]
	v_mfma_f32_16x16x32_bf16 v[110:113], v[150:153], v[174:177], v[110:113]
	v_mfma_f32_16x16x32_bf16 v[102:105], v[158:161], v[174:177], v[102:105]
	v_mfma_f32_16x16x32_bf16 v[94:97], v[150:153], v[182:185], v[94:97]
	v_mfma_f32_16x16x32_bf16 v[86:89], v[158:161], v[182:185], v[86:89]
	v_mfma_f32_16x16x32_bf16 v[78:81], v[150:153], v[190:193], v[78:81]
	v_mfma_f32_16x16x32_bf16 v[70:73], v[158:161], v[190:193], v[70:73]
	v_mfma_f32_16x16x32_bf16 v[122:125], v[130:133], v[162:165], v[122:125]
	v_mfma_f32_16x16x32_bf16 v[114:117], v[138:141], v[162:165], v[114:117]
	v_mfma_f32_16x16x32_bf16 v[106:109], v[130:133], v[170:173], v[106:109]
	v_mfma_f32_16x16x32_bf16 v[98:101], v[138:141], v[170:173], v[98:101]
	v_mfma_f32_16x16x32_bf16 v[90:93], v[130:133], v[178:181], v[90:93]
	v_mfma_f32_16x16x32_bf16 v[82:85], v[138:141], v[178:181], v[82:85]
	v_mfma_f32_16x16x32_bf16 v[74:77], v[130:133], v[186:189], v[74:77]
	v_mfma_f32_16x16x32_bf16 v[66:69], v[138:141], v[186:189], v[66:69]
	v_mfma_f32_16x16x32_bf16 v[122:125], v[134:137], v[166:169], v[122:125]
	v_mfma_f32_16x16x32_bf16 v[114:117], v[142:145], v[166:169], v[114:117]
	v_mfma_f32_16x16x32_bf16 v[106:109], v[134:137], v[174:177], v[106:109]
	v_mfma_f32_16x16x32_bf16 v[98:101], v[142:145], v[174:177], v[98:101]
	v_mfma_f32_16x16x32_bf16 v[90:93], v[134:137], v[182:185], v[90:93]
	v_mfma_f32_16x16x32_bf16 v[82:85], v[142:145], v[182:185], v[82:85]
	v_mfma_f32_16x16x32_bf16 v[74:77], v[134:137], v[190:193], v[74:77]
	v_mfma_f32_16x16x32_bf16 v[66:69], v[142:145], v[190:193], v[66:69]
	s_barrier
	s_mov_b32 m0, s66
	ds_read_b128 v[186:189], v219 offset:49152
	ds_read_b128 v[190:193], v219 offset:50176
	ds_read_b128 v[178:181], v219 offset:51200
	ds_read_b128 v[182:185], v219 offset:52224
	ds_read_b128 v[170:173], v219 offset:53248
	ds_read_b128 v[174:177], v219 offset:54272
	ds_read_b128 v[162:165], v219 offset:55296
	ds_read_b128 v[166:169], v219 offset:56320
	global_load_lds_dwordx4 v230, s[30:31]
	s_mov_b32 m0, s65
	s_nop 0
	global_load_lds_dwordx4 v231, s[30:31]
	s_mov_b32 m0, s68
	s_nop 0
	global_load_lds_dwordx4 v200, s[24:25]
	s_mov_b32 m0, s67
	s_nop 0
	global_load_lds_dwordx4 v196, s[24:25]
	s_mov_b32 m0, s44
	s_nop 0
	global_load_lds_dwordx4 v232, s[28:29]
	s_mov_b32 m0, s45
	s_nop 0
	global_load_lds_dwordx4 v233, s[28:29]
	s_waitcnt vmcnt(8)
	s_waitcnt lgkmcnt(0)
	s_barrier
	s_cbranch_scc1 .LBB0_1053
	global_load_dword v228, v[214:215], off
	global_load_dword v227, v[214:215], off offset:64
	global_load_dword v226, v[214:215], off offset:128
	global_load_dword v225, v[214:215], off offset:192
	global_load_dword v224, v[214:215], off offset:512
	global_load_dword v223, v[214:215], off offset:576
	global_load_dword v222, v[214:215], off offset:640
	global_load_dword v221, v[214:215], off offset:704
	s_branch .LBB0_1053

; #define PG8_STAGE(bufoff, gbase, voff) do { _Pragma("unroll") for (int _i = 0; _i < 2; ++_i) \
;         __builtin_amdgcn_global_load_lds((const unsigned*)((const char*)(gbase) + (voff)[_i]), (LAS unsigned*)(lds + (bufoff) + ldsw + _i * 8192), 16, 0, 0); } while (0)
; #define PG8_BAR __builtin_amdgcn_s_barrier()
;     __device__ __forceinline__ bool next(int i, Unit& u) const {
;         const long L = (long)i * G + c; if (L >= (long)nM * nN) return false;
;         tile_of((int)L, nM, nN, u.pm, u.pn); u.sub = 0;
;         u.A = A + (size_t)u.pm * BM * lda * 2; u.B = B + (size_t)u.pn * BM * ldb * 2; return true;
; template <class Epi, class Sched>
; __device__ __forceinline__ void gemm_phase(LAS unsigned char* lds, const int lda, const int ldb, const int K, const Sched& S, const Epi& E) {
;     const int tid = threadIdx.x, wid = __builtin_amdgcn_readfirstlane(tid >> 6), lane = tid & 63, wr = wid >> 2, wc = wid & 3, fr = lane & 15, fq = lane >> 4;
;     const int nt = K / BK;
;     unsigned voffA[2], voffB[2];
; #pragma unroll
;     for (int i = 0; i < 2; ++i) { int R, C; stage_rc(tid * 16 + i * 8192, R, C); const int Rb = (R & ~31) + perm32(R & 31);
;         voffA[i] = (unsigned)(R * lda + C) * 2u; voffB[i] = (unsigned)(Rb * ldb + C) * 2u; }
;     const size_t kstep = (size_t)(BK * 2);
;     const size_t hstepA = (size_t)HALF * lda * 2, hstepB = (size_t)HALF * ldb * 2;
;     const unsigned ldsw = (unsigned)wid * 1024u;
;     const int aoff = lds_byte(wr * 64 + fr, fq * 8), boff = lds_byte(wc * 32 + fr, fq * 8);
;     ...
;     Unit cur, nxt; int ui = 0;
;     if (!S.next(0, cur)) return;
;     f32x4 acc[2][2][4][2];
; #pragma unroll
;     for (int a = 0; a < 2; ++a)
; #pragma unroll
;         for (int b = 0; b < 2; ++b)
; #pragma unroll
;             for (int m = 0; m < 4; ++m)
; #pragma unroll
;                 for (int n = 0; n < 2; ++n) acc[a][b][m][n] = (f32x4){0.f, 0.f, 0.f, 0.f};
;     bf16x8 At[4][2], B0[2][2], B1[2][2];
;     float rsv[8];
; #pragma unroll
;     for (int i = 0; i < 8; ++i) rsv[i] = 0.f;
;     const char* cA = cur.A; const char* cB = cur.B;
;     PG8_STAGE(PG8_SB(0, 0), cB, voffB); PG8_STAGE(PG8_SB(0, 1), cB + hstepB, voffB); PG8_STAGE(PG8_SA(0, 0), cA, voffA); PG8_STAGE(PG8_SA(0, 1), cA + hstepA, voffA);
;     if (wr == 1) PG8_BAR;
.LBB0_1126:
	s_cmp_lt_i32 s56, 10
	s_cselect_b64 s[4:5], -1, 0
	s_and_b64 s[0:1], s[4:5], s[0:1]
	s_andn2_b64 vcc, exec, s[0:1]
	s_cbranch_vccnz .LBB0_1143
	s_cmpk_gt_i32 s2, 0x5ff
	v_readfirstlane_b32 s0, v194
	s_cbranch_scc1 .LBB0_1143
	v_lshrrev_b32_e32 v0, 5, v194
	v_lshrrev_b32_e32 v2, 1, v194
	v_and_b32_e32 v0, 4, v0
	v_bfe_u32 v1, v194, 2, 2
	v_and_b32_e32 v8, 24, v2
	v_or3_b32 v0, v0, v1, v8
	v_lshlrev_b32_e32 v1, 4, v194
	v_add_u32_e32 v2, 0x2000, v1
	v_and_b32_e32 v4, 32, v194
	v_lshrrev_b32_e32 v2, 7, v2
	s_movk_i32 s4, 0xe0
	v_bitop3_b32 v9, v1, v4, 48 bitop3:0x6c
	v_and_b32_e32 v10, 64, v194
	s_waitcnt lgkmcnt(0)
	v_and_or_b32 v3, v2, s4, v0
	v_or_b32_e32 v1, v9, v10
	v_mul_u32_u24_e32 v3, 0xb00, v3
	v_lshrrev_b32_e32 v1, 1, v1
	v_or_b32_e32 v3, v3, v1
	v_lshlrev_b32_e32 v128, 1, v3
	v_bfe_u32 v3, v194, 2, 4
	s_movk_i32 s4, 0xf0
	v_and_or_b32 v2, v2, s4, v3
	v_mul_u32_u24_e32 v11, 0xb00, v2
	v_or_b32_e32 v2, v11, v1
	v_lshlrev_b32_e32 v130, 1, v2
	v_lshrrev_b32_e32 v2, 3, v194
	s_movk_i32 s4, 0x60
	v_and_or_b32 v0, v2, s4, v0
	s_add_u32 s3, s54, 0x2908000
	v_mul_u32_u24_e32 v0, 0xb00, v0
	s_addc_u32 s20, s55, 0
	v_or_b32_e32 v0, v0, v1
	s_movk_i32 s4, 0x70
	s_ashr_i32 s22, s2, 31
	v_lshlrev_b32_e32 v132, 1, v0
	v_and_or_b32 v0, v2, s4, v3
	s_lshr_b32 s4, s22, 29
	s_add_i32 s4, s2, s4
	s_lshr_b32 s6, s0, 6
	s_ashr_i32 s5, s4, 3
	s_and_b32 s4, s4, -8
	s_lshr_b32 s1, s0, 8
	s_lshl_b32 s21, s6, 10
	s_sub_i32 s4, s2, s4
	s_cmp_lt_i32 s4, 0
	s_movk_i32 s23, 0xc1
	s_cselect_b32 s7, s23, 0xc0
	s_mul_i32 s4, s4, s7
	s_add_i32 s4, s4, s5
	s_ashr_i32 s5, s4, 31
	s_lshr_b32 s5, s5, 27
	s_add_i32 s5, s4, s5
	s_ashr_i32 s7, s5, 5
	s_and_b32 s5, s5, 0xffe0
	s_sub_i32 s4, s4, s5
	s_bfe_i32 s5, s4, 0x80000
	s_bfe_u32 s5, s5, 0x3000c
	s_add_i32 s5, s4, s5
	s_and_b32 s8, s5, 0xf8
	s_sub_i32 s4, s4, s8
	s_lshl_b32 s7, s7, 3
	s_sext_i32_i8 s4, s4
	s_add_i32 s37, s7, s4
	s_bfe_i32 s4, s5, 0x80000
	s_sext_i32_i16 s4, s4
	s_ashr_i32 s38, s4, 3
	s_mul_i32 s5, s37, 0x160000
	s_mul_hi_i32 s4, s37, 0x160000
	s_add_u32 s14, s46, s5
	s_addc_u32 s15, s47, s4
	s_mul_i32 s4, s38, 0x160000
	s_ashr_i32 s5, s4, 31
	s_add_u32 s16, s3, s4
	s_addc_u32 s17, s20, s5
	s_add_i32 s24, s21, 0
	s_add_i32 m0, s24, 0x10000
	v_mul_u32_u24_e32 v12, 0xb00, v0
	global_load_lds_dwordx4 v132, s[16:17]
	s_add_i32 m0, s24, 0x12000
	s_add_u32 s4, s16, 0xb0000
	global_load_lds_dwordx4 v128, s[16:17]
	s_addc_u32 s5, s17, 0
	s_add_i32 m0, s24, 0x14000
	v_or_b32_e32 v0, v1, v12
	global_load_lds_dwordx4 v132, s[4:5]
	s_add_i32 m0, s24, 0x16000
	s_add_i32 s25, s24, 0x2000
	v_lshlrev_b32_e32 v134, 1, v0
	global_load_lds_dwordx4 v128, s[4:5]
	s_mov_b32 m0, s24
	s_add_u32 s4, s14, 0xb0000
	global_load_lds_dwordx4 v134, s[14:15]
	s_mov_b32 m0, s25
	s_addc_u32 s5, s15, 0
	s_add_i32 s26, s24, 0x4000
	global_load_lds_dwordx4 v130, s[14:15]
	s_mov_b32 m0, s26
	s_add_i32 s27, s24, 0x6000
	global_load_lds_dwordx4 v134, s[4:5]
	s_mov_b32 m0, s27
	v_mov_b32_e32 v133, 0
	global_load_lds_dwordx4 v130, s[4:5]
	v_mov_b32_e32 v129, v133
	v_mov_b32_e32 v135, v133
	v_mov_b32_e32 v131, v133
	s_cmp_eq_u32 s1, 1
	s_mov_b32 s28, 0
	v_lshl_add_u64 v[6:7], s[16:17], 0, v[132:133]
	v_lshl_add_u64 v[4:5], s[16:17], 0, v[128:129]
	v_lshl_add_u64 v[0:1], s[14:15], 0, v[134:135]
	s_cselect_b64 s[4:5], -1, 0
	s_cmp_lg_u32 s1, 1
	v_lshl_add_u64 v[2:3], s[14:15], 0, v[130:131]
	s_cbranch_scc1 .LBB0_1130
	s_setprio 1
	s_barrier

; #define PG8_STAGE(bufoff, gbase, voff) do { _Pragma("unroll") for (int _i = 0; _i < 2; ++_i) \
;         __builtin_amdgcn_global_load_lds((const unsigned*)((const char*)(gbase) + (voff)[_i]), (LAS unsigned*)(lds + (bufoff) + ldsw + _i * 8192), 16, 0, 0); } while (0)
; #define PG8_LDA(dst, b, h) do { _Pragma("unroll") for (int m = 0; m < 4; ++m) _Pragma("unroll") for (int k = 0; k < 2; ++k) dst[m][k] = *(const LAS bf16x8*)(lds + PG8_SA(b, h) + aoff + m * 2048 + k * 1024); } while (0)
; #define PG8_LDB(dst, b, h) do { _Pragma("unroll") for (int n = 0; n < 2; ++n) _Pragma("unroll") for (int k = 0; k < 2; ++k) dst[n][k] = *(const LAS bf16x8*)(lds + PG8_SB(b, h) + boff + n * 2048 + k * 1024); } while (0)
; #define PG8_MMA(ai, bj, At, Bt) do { __builtin_amdgcn_s_setprio(1); _Pragma("unroll") for (int m = 0; m < 4; ++m) _Pragma("unroll") for (int n = 0; n < 2; ++n) _Pragma("unroll") for (int k = 0; k < 2; ++k) \
;         acc[ai][bj][m][n] = __builtin_amdgcn_mfma_f32_16x16x32_bf16(Bt[n][k], At[m][k], acc[ai][bj][m][n], 0, 0, 0); __builtin_amdgcn_s_setprio(0); } while (0)
; #define PG8_WAIT_V(n) asm volatile("s_waitcnt vmcnt(" #n ")" ::: "memory")
; #define PG8_WAIT_L(n) asm volatile("s_waitcnt lgkmcnt(" #n ")" ::: "memory")
; #define PG8_BAR __builtin_amdgcn_s_barrier()
; #define PG8_SCHED __builtin_amdgcn_sched_barrier(0)
; template <class Epi, class Sched>
; __device__ __forceinline__ void gemm_phase(LAS unsigned char* lds, const int lda, const int ldb, const int K, const Sched& S, const Epi& E) {
;     ...
;             const bool last = (t == nt - 2);
;             const char* a1 = cA + (size_t)(t + 1) * kstep;
;             const char* a2 = last ? nA : cA + (size_t)(t + 2) * kstep; const char* b2 = last ? nB : cB + (size_t)(t + 2) * kstep;
;             const char* a3 = a2 + kstep; const char* b3 = b2 + kstep;
;             PG8_LDB(B0, 0, 0); PG8_LDB(B1, 0, 1); PG8_SCHED; PG8_LDA(At, 0, 0); PG8_STAGE(PG8_SA(1, 1), a1 + hstepA, voffA);
;             PG8_WAIT_V(8); PG8_WAIT_L(0); PG8_BAR; PG8_MMA(0, 0, At, B0); PG8_MMA(0, 1, At, B1); PG8_BAR; PG8_SCHED;
;             PG8_LDA(At, 0, 1); PG8_STAGE(PG8_SB(0, 0), b2, voffB); PG8_STAGE(PG8_SB(0, 1), b2 + hstepB, voffB); PG8_STAGE(PG8_SA(0, 0), a2, voffA);
;             PG8_WAIT_V(8); PG8_WAIT_L(0); PG8_BAR; PG8_MMA(1, 0, At, B0); PG8_MMA(1, 1, At, B1); PG8_BAR; PG8_SCHED;
.LBB0_1135:
	s_add_u32 s14, s14, 0xb0080
	s_addc_u32 s15, s15, 0
	s_add_u32 s39, s16, 0x100
	s_addc_u32 s40, s17, 0
	s_mov_b32 s41, -2
	v_add_u32_e32 v214, 0x80, v132
	v_add_u32_e32 v215, 0x80, v128
	v_add_u32_e32 v216, 0x80, v134
	v_add_u32_e32 v217, 0x80, v130
	ds_read_b128 v[144:147], v151
	ds_read_b128 v[154:157], v151 offset:1024
	ds_read_b128 v[158:161], v151 offset:2048
	ds_read_b128 v[162:165], v151 offset:3072
	ds_read_b128 v[166:169], v152
	ds_read_b128 v[170:173], v152 offset:1024
	ds_read_b128 v[174:177], v152 offset:2048
	ds_read_b128 v[178:181], v152 offset:3072
	s_add_u32 s16, s14, 0xfff50080
	s_addc_u32 s17, s15, -1
	s_cmp_eq_u32 s41, 40
	s_cselect_b32 s19, s11, s17
	s_cselect_b32 s18, s10, s16
	s_cselect_b32 s17, s13, s40
	s_cselect_b32 s16, s12, s39
	s_add_i32 m0, s24, 0xc000
	ds_read_b128 v[182:185], v153
	ds_read_b128 v[186:189], v153 offset:1024
	ds_read_b128 v[190:193], v153 offset:2048
	ds_read_b128 v[194:197], v153 offset:3072
	ds_read_b128 v[198:201], v153 offset:4096
	ds_read_b128 v[202:205], v153 offset:5120
	ds_read_b128 v[206:209], v153 offset:6144
	ds_read_b128 v[210:213], v153 offset:7168
	global_load_lds_dwordx4 v136, s[14:15]
	s_add_i32 m0, s24, 0xe000
	s_nop 0
	global_load_lds_dwordx4 v138, s[14:15]
	s_waitcnt vmcnt(8)
	s_waitcnt lgkmcnt(0)
	s_barrier
	s_waitcnt lgkmcnt(0)
	v_mfma_f32_16x16x32_bf16 v[124:127], v[144:147], v[182:185], 0
	v_mfma_f32_16x16x32_bf16 v[120:123], v[158:161], v[182:185], 0
	v_mfma_f32_16x16x32_bf16 v[112:115], v[144:147], v[190:193], 0
	v_mfma_f32_16x16x32_bf16 v[104:107], v[158:161], v[190:193], 0
	v_mfma_f32_16x16x32_bf16 v[96:99], v[144:147], v[198:201], 0
	v_mfma_f32_16x16x32_bf16 v[88:91], v[158:161], v[198:201], 0
	v_mfma_f32_16x16x32_bf16 v[80:83], v[144:147], v[206:209], 0
	v_mfma_f32_16x16x32_bf16 v[72:75], v[158:161], v[206:209], 0
	v_mfma_f32_16x16x32_bf16 v[124:127], v[154:157], v[186:189], v[124:127]
	v_mfma_f32_16x16x32_bf16 v[120:123], v[162:165], v[186:189], v[120:123]
	v_mfma_f32_16x16x32_bf16 v[112:115], v[154:157], v[194:197], v[112:115]
	v_mfma_f32_16x16x32_bf16 v[104:107], v[162:165], v[194:197], v[104:107]
	v_mfma_f32_16x16x32_bf16 v[96:99], v[154:157], v[202:205], v[96:99]
	v_mfma_f32_16x16x32_bf16 v[88:91], v[162:165], v[202:205], v[88:91]
	v_mfma_f32_16x16x32_bf16 v[80:83], v[154:157], v[210:213], v[80:83]
	v_mfma_f32_16x16x32_bf16 v[72:75], v[162:165], v[210:213], v[72:75]
	v_mfma_f32_16x16x32_bf16 v[116:119], v[166:169], v[182:185], 0
	v_mfma_f32_16x16x32_bf16 v[108:111], v[174:177], v[182:185], 0
	v_mfma_f32_16x16x32_bf16 v[100:103], v[166:169], v[190:193], 0
	v_mfma_f32_16x16x32_bf16 v[92:95], v[174:177], v[190:193], 0
	v_mfma_f32_16x16x32_bf16 v[84:87], v[166:169], v[198:201], 0
	v_mfma_f32_16x16x32_bf16 v[76:79], v[174:177], v[198:201], 0
	v_mfma_f32_16x16x32_bf16 v[68:71], v[166:169], v[206:209], 0
	v_mfma_f32_16x16x32_bf16 v[64:67], v[174:177], v[206:209], 0
	v_mfma_f32_16x16x32_bf16 v[116:119], v[170:173], v[186:189], v[116:119]
	v_mfma_f32_16x16x32_bf16 v[108:111], v[178:181], v[186:189], v[108:111]
	v_mfma_f32_16x16x32_bf16 v[100:103], v[170:173], v[194:197], v[100:103]
	v_mfma_f32_16x16x32_bf16 v[92:95], v[178:181], v[194:197], v[92:95]
	v_mfma_f32_16x16x32_bf16 v[84:87], v[170:173], v[202:205], v[84:87]
	v_mfma_f32_16x16x32_bf16 v[76:79], v[178:181], v[202:205], v[76:79]
	v_mfma_f32_16x16x32_bf16 v[68:71], v[170:173], v[210:213], v[68:71]
	v_mfma_f32_16x16x32_bf16 v[64:67], v[178:181], v[210:213], v[64:67]
	s_barrier
	s_add_i32 s42, s33, s21
	s_mov_b32 m0, s42
	ds_read_b128 v[182:185], v153 offset:16384
	ds_read_b128 v[186:189], v153 offset:17408
	ds_read_b128 v[190:193], v153 offset:18432
	ds_read_b128 v[194:197], v153 offset:19456
	ds_read_b128 v[198:201], v153 offset:20480
	ds_read_b128 v[202:205], v153 offset:21504
	ds_read_b128 v[206:209], v153 offset:22528
	ds_read_b128 v[210:213], v153 offset:23552
	global_load_lds_dwordx4 v132, s[16:17]
	s_add_i32 m0, s42, 0x2000
	s_add_u32 s42, s16, 0xb0000
	s_mov_b64 s[98:99], s[16:17]
	s_addc_u32 s43, s17, 0
	s_add_i32 s44, s34, s21
	global_load_lds_dwordx4 v128, s[16:17]
	s_mov_b32 m0, s44
	s_mov_b64 s[100:101], s[18:19]
	global_load_lds_dwordx4 v132, s[42:43]
	s_add_i32 m0, s44, 0x2000
	s_nop 0
	global_load_lds_dwordx4 v128, s[42:43]
	s_mov_b32 m0, s24
	s_nop 0
	global_load_lds_dwordx4 v134, s[18:19]
	s_mov_b32 m0, s25
	s_nop 0
	global_load_lds_dwordx4 v130, s[18:19]
	s_waitcnt vmcnt(8)
	s_waitcnt lgkmcnt(0)
	s_barrier
	s_waitcnt lgkmcnt(0)
	v_mfma_f32_16x16x32_bf16 v[60:63], v[144:147], v[182:185], 0
	v_mfma_f32_16x16x32_bf16 v[56:59], v[158:161], v[182:185], 0
	v_mfma_f32_16x16x32_bf16 v[48:51], v[144:147], v[190:193], 0
	v_mfma_f32_16x16x32_bf16 v[40:43], v[158:161], v[190:193], 0
	v_mfma_f32_16x16x32_bf16 v[32:35], v[144:147], v[198:201], 0
	v_mfma_f32_16x16x32_bf16 v[24:27], v[158:161], v[198:201], 0
	v_mfma_f32_16x16x32_bf16 v[16:19], v[144:147], v[206:209], 0
	v_mfma_f32_16x16x32_bf16 v[8:11], v[158:161], v[206:209], 0
	v_mfma_f32_16x16x32_bf16 v[60:63], v[154:157], v[186:189], v[60:63]
	v_mfma_f32_16x16x32_bf16 v[56:59], v[162:165], v[186:189], v[56:59]
	v_mfma_f32_16x16x32_bf16 v[48:51], v[154:157], v[194:197], v[48:51]
	v_mfma_f32_16x16x32_bf16 v[40:43], v[162:165], v[194:197], v[40:43]
	v_mfma_f32_16x16x32_bf16 v[32:35], v[154:157], v[202:205], v[32:35]
	v_mfma_f32_16x16x32_bf16 v[24:27], v[162:165], v[202:205], v[24:27]
	v_mfma_f32_16x16x32_bf16 v[16:19], v[154:157], v[210:213], v[16:19]
	v_mfma_f32_16x16x32_bf16 v[8:11], v[162:165], v[210:213], v[8:11]
	v_mfma_f32_16x16x32_bf16 v[52:55], v[166:169], v[182:185], 0
	v_mfma_f32_16x16x32_bf16 v[44:47], v[174:177], v[182:185], 0
	v_mfma_f32_16x16x32_bf16 v[36:39], v[166:169], v[190:193], 0
	v_mfma_f32_16x16x32_bf16 v[28:31], v[174:177], v[190:193], 0
	v_mfma_f32_16x16x32_bf16 v[20:23], v[166:169], v[198:201], 0
	v_mfma_f32_16x16x32_bf16 v[12:15], v[174:177], v[198:201], 0
	v_mfma_f32_16x16x32_bf16 v[4:7], v[166:169], v[206:209], 0
	v_mfma_f32_16x16x32_bf16 v[0:3], v[174:177], v[206:209], 0
	v_mfma_f32_16x16x32_bf16 v[52:55], v[170:173], v[186:189], v[52:55]
	v_mfma_f32_16x16x32_bf16 v[44:47], v[178:181], v[186:189], v[44:47]
	v_mfma_f32_16x16x32_bf16 v[36:39], v[170:173], v[194:197], v[36:39]
	v_mfma_f32_16x16x32_bf16 v[28:31], v[178:181], v[194:197], v[28:31]
	v_mfma_f32_16x16x32_bf16 v[20:23], v[170:173], v[202:205], v[20:23]
	v_mfma_f32_16x16x32_bf16 v[12:15], v[178:181], v[202:205], v[12:15]
	v_mfma_f32_16x16x32_bf16 v[4:7], v[170:173], v[210:213], v[4:7]
	v_mfma_f32_16x16x32_bf16 v[0:3], v[178:181], v[210:213], v[0:3]
	s_barrier
	s_branch .Lpeel7_join
; #define PG8_STAGE(bufoff, gbase, voff) do { _Pragma("unroll") for (int _i = 0; _i < 2; ++_i) \
;         __builtin_amdgcn_global_load_lds((const unsigned*)((const char*)(gbase) + (voff)[_i]), (LAS unsigned*)(lds + (bufoff) + ldsw + _i * 8192), 16, 0, 0); } while (0)
; #define PG8_LDA(dst, b, h) do { _Pragma("unroll") for (int m = 0; m < 4; ++m) _Pragma("unroll") for (int k = 0; k < 2; ++k) dst[m][k] = *(const LAS bf16x8*)(lds + PG8_SA(b, h) + aoff + m * 2048 + k * 1024); } while (0)
; #define PG8_LDB(dst, b, h) do { _Pragma("unroll") for (int n = 0; n < 2; ++n) _Pragma("unroll") for (int k = 0; k < 2; ++k) dst[n][k] = *(const LAS bf16x8*)(lds + PG8_SB(b, h) + boff + n * 2048 + k * 1024); } while (0)
; #define PG8_MMA(ai, bj, At, Bt) do { __builtin_amdgcn_s_setprio(1); _Pragma("unroll") for (int m = 0; m < 4; ++m) _Pragma("unroll") for (int n = 0; n < 2; ++n) _Pragma("unroll") for (int k = 0; k < 2; ++k) \
;         acc[ai][bj][m][n] = __builtin_amdgcn_mfma_f32_16x16x32_bf16(Bt[n][k], At[m][k], acc[ai][bj][m][n], 0, 0, 0); __builtin_amdgcn_s_setprio(0); } while (0)
; #define PG8_WAIT_V(n) asm volatile("s_waitcnt vmcnt(" #n ")" ::: "memory")
; #define PG8_WAIT_L(n) asm volatile("s_waitcnt lgkmcnt(" #n ")" ::: "memory")
; #define PG8_BAR __builtin_amdgcn_s_barrier()
; #define PG8_SCHED __builtin_amdgcn_sched_barrier(0)
; template <class Epi, class Sched>
; __device__ __forceinline__ void gemm_phase(LAS unsigned char* lds, const int lda, const int ldb, const int K, const Sched& S, const Epi& E) {
;     ...
;             const bool last = (t == nt - 2);
;             const char* a1 = cA + (size_t)(t + 1) * kstep;
;             const char* a2 = last ? nA : cA + (size_t)(t + 2) * kstep; const char* b2 = last ? nB : cB + (size_t)(t + 2) * kstep;
;             const char* a3 = a2 + kstep; const char* b3 = b2 + kstep;
;             PG8_LDB(B0, 0, 0); PG8_LDB(B1, 0, 1); PG8_SCHED; PG8_LDA(At, 0, 0); PG8_STAGE(PG8_SA(1, 1), a1 + hstepA, voffA);
;             PG8_WAIT_V(8); PG8_WAIT_L(0); PG8_BAR; PG8_MMA(0, 0, At, B0); PG8_MMA(0, 1, At, B1); PG8_BAR; PG8_SCHED;
;             PG8_LDA(At, 0, 1); PG8_STAGE(PG8_SB(0, 0), b2, voffB); PG8_STAGE(PG8_SB(0, 1), b2 + hstepB, voffB); PG8_STAGE(PG8_SA(0, 0), a2, voffA);
;             PG8_WAIT_V(8); PG8_WAIT_L(0); PG8_BAR; PG8_MMA(1, 0, At, B0); PG8_MMA(1, 1, At, B1); PG8_BAR; PG8_SCHED;
.LBB0_1136:
	ds_read_b128 v[144:147], v151
	ds_read_b128 v[154:157], v151 offset:1024
	ds_read_b128 v[158:161], v151 offset:2048
	ds_read_b128 v[162:165], v151 offset:3072
	ds_read_b128 v[166:169], v152
	ds_read_b128 v[170:173], v152 offset:1024
	ds_read_b128 v[174:177], v152 offset:2048
	ds_read_b128 v[178:181], v152 offset:3072
	s_add_u32 s16, s14, 0xfff50080
	s_addc_u32 s17, s15, -1
	s_cmp_eq_u32 s41, 40
	s_cselect_b32 s19, s11, s17
	s_cselect_b32 s18, s10, s16
	s_cselect_b32 s17, s13, s40
	s_cselect_b32 s16, s12, s39
	s_add_i32 m0, s24, 0xc000
	ds_read_b128 v[182:185], v153
	ds_read_b128 v[186:189], v153 offset:1024
	ds_read_b128 v[190:193], v153 offset:2048
	ds_read_b128 v[194:197], v153 offset:3072
	ds_read_b128 v[198:201], v153 offset:4096
	ds_read_b128 v[202:205], v153 offset:5120
	ds_read_b128 v[206:209], v153 offset:6144
	ds_read_b128 v[210:213], v153 offset:7168
	global_load_lds_dwordx4 v136, s[14:15]
	s_add_i32 m0, s24, 0xe000
	s_nop 0
	global_load_lds_dwordx4 v138, s[14:15]
	s_waitcnt vmcnt(8)
	s_waitcnt lgkmcnt(0)
	s_barrier
	s_waitcnt lgkmcnt(0)
	v_mfma_f32_16x16x32_bf16 v[124:127], v[144:147], v[182:185], v[124:127]
	v_mfma_f32_16x16x32_bf16 v[120:123], v[158:161], v[182:185], v[120:123]
	v_mfma_f32_16x16x32_bf16 v[112:115], v[144:147], v[190:193], v[112:115]
	v_mfma_f32_16x16x32_bf16 v[104:107], v[158:161], v[190:193], v[104:107]
	v_mfma_f32_16x16x32_bf16 v[96:99], v[144:147], v[198:201], v[96:99]
	v_mfma_f32_16x16x32_bf16 v[88:91], v[158:161], v[198:201], v[88:91]
	v_mfma_f32_16x16x32_bf16 v[80:83], v[144:147], v[206:209], v[80:83]
	v_mfma_f32_16x16x32_bf16 v[72:75], v[158:161], v[206:209], v[72:75]
	v_mfma_f32_16x16x32_bf16 v[124:127], v[154:157], v[186:189], v[124:127]
	v_mfma_f32_16x16x32_bf16 v[120:123], v[162:165], v[186:189], v[120:123]
	v_mfma_f32_16x16x32_bf16 v[112:115], v[154:157], v[194:197], v[112:115]
	v_mfma_f32_16x16x32_bf16 v[104:107], v[162:165], v[194:197], v[104:107]
	v_mfma_f32_16x16x32_bf16 v[96:99], v[154:157], v[202:205], v[96:99]
	v_mfma_f32_16x16x32_bf16 v[88:91], v[162:165], v[202:205], v[88:91]
	v_mfma_f32_16x16x32_bf16 v[80:83], v[154:157], v[210:213], v[80:83]
	v_mfma_f32_16x16x32_bf16 v[72:75], v[162:165], v[210:213], v[72:75]
	v_mfma_f32_16x16x32_bf16 v[116:119], v[166:169], v[182:185], v[116:119]
	v_mfma_f32_16x16x32_bf16 v[108:111], v[174:177], v[182:185], v[108:111]
	v_mfma_f32_16x16x32_bf16 v[100:103], v[166:169], v[190:193], v[100:103]
	v_mfma_f32_16x16x32_bf16 v[92:95], v[174:177], v[190:193], v[92:95]
	v_mfma_f32_16x16x32_bf16 v[84:87], v[166:169], v[198:201], v[84:87]
	v_mfma_f32_16x16x32_bf16 v[76:79], v[174:177], v[198:201], v[76:79]
	v_mfma_f32_16x16x32_bf16 v[68:71], v[166:169], v[206:209], v[68:71]
	v_mfma_f32_16x16x32_bf16 v[64:67], v[174:177], v[206:209], v[64:67]
	v_mfma_f32_16x16x32_bf16 v[116:119], v[170:173], v[186:189], v[116:119]
	v_mfma_f32_16x16x32_bf16 v[108:111], v[178:181], v[186:189], v[108:111]
	v_mfma_f32_16x16x32_bf16 v[100:103], v[170:173], v[194:197], v[100:103]
	v_mfma_f32_16x16x32_bf16 v[92:95], v[178:181], v[194:197], v[92:95]
	v_mfma_f32_16x16x32_bf16 v[84:87], v[170:173], v[202:205], v[84:87]
	v_mfma_f32_16x16x32_bf16 v[76:79], v[178:181], v[202:205], v[76:79]
	v_mfma_f32_16x16x32_bf16 v[68:71], v[170:173], v[210:213], v[68:71]
	v_mfma_f32_16x16x32_bf16 v[64:67], v[178:181], v[210:213], v[64:67]
	s_barrier
	s_add_i32 s42, s33, s21
	s_mov_b32 m0, s42
	ds_read_b128 v[182:185], v153 offset:16384
	ds_read_b128 v[186:189], v153 offset:17408
	ds_read_b128 v[190:193], v153 offset:18432
	ds_read_b128 v[194:197], v153 offset:19456
	ds_read_b128 v[198:201], v153 offset:20480
	ds_read_b128 v[202:205], v153 offset:21504
	ds_read_b128 v[206:209], v153 offset:22528
	ds_read_b128 v[210:213], v153 offset:23552
	global_load_lds_dwordx4 v132, s[16:17]
	s_add_i32 m0, s42, 0x2000
	s_add_u32 s42, s16, 0xb0000
	s_mov_b64 s[98:99], s[16:17]
	s_addc_u32 s43, s17, 0
	s_add_i32 s44, s34, s21
	global_load_lds_dwordx4 v128, s[16:17]
	s_mov_b32 m0, s44
	s_mov_b64 s[100:101], s[18:19]
	global_load_lds_dwordx4 v132, s[42:43]
	s_add_i32 m0, s44, 0x2000
	s_nop 0
	global_load_lds_dwordx4 v128, s[42:43]
	s_mov_b32 m0, s24
	s_nop 0
	global_load_lds_dwordx4 v134, s[18:19]
	s_mov_b32 m0, s25
	s_nop 0
	global_load_lds_dwordx4 v130, s[18:19]
	s_waitcnt vmcnt(8)
	s_waitcnt lgkmcnt(0)
	s_barrier
	s_waitcnt lgkmcnt(0)
	v_mfma_f32_16x16x32_bf16 v[60:63], v[144:147], v[182:185], v[60:63]
	v_mfma_f32_16x16x32_bf16 v[56:59], v[158:161], v[182:185], v[56:59]
	v_mfma_f32_16x16x32_bf16 v[48:51], v[144:147], v[190:193], v[48:51]
	v_mfma_f32_16x16x32_bf16 v[40:43], v[158:161], v[190:193], v[40:43]
	v_mfma_f32_16x16x32_bf16 v[32:35], v[144:147], v[198:201], v[32:35]
	v_mfma_f32_16x16x32_bf16 v[24:27], v[158:161], v[198:201], v[24:27]
	v_mfma_f32_16x16x32_bf16 v[16:19], v[144:147], v[206:209], v[16:19]
	v_mfma_f32_16x16x32_bf16 v[8:11], v[158:161], v[206:209], v[8:11]
	v_mfma_f32_16x16x32_bf16 v[60:63], v[154:157], v[186:189], v[60:63]
	v_mfma_f32_16x16x32_bf16 v[56:59], v[162:165], v[186:189], v[56:59]
	v_mfma_f32_16x16x32_bf16 v[48:51], v[154:157], v[194:197], v[48:51]
	v_mfma_f32_16x16x32_bf16 v[40:43], v[162:165], v[194:197], v[40:43]
	v_mfma_f32_16x16x32_bf16 v[32:35], v[154:157], v[202:205], v[32:35]
	v_mfma_f32_16x16x32_bf16 v[24:27], v[162:165], v[202:205], v[24:27]
	v_mfma_f32_16x16x32_bf16 v[16:19], v[154:157], v[210:213], v[16:19]
	v_mfma_f32_16x16x32_bf16 v[8:11], v[162:165], v[210:213], v[8:11]
	v_mfma_f32_16x16x32_bf16 v[52:55], v[166:169], v[182:185], v[52:55]
	v_mfma_f32_16x16x32_bf16 v[44:47], v[174:177], v[182:185], v[44:47]
	v_mfma_f32_16x16x32_bf16 v[36:39], v[166:169], v[190:193], v[36:39]
	v_mfma_f32_16x16x32_bf16 v[28:31], v[174:177], v[190:193], v[28:31]
	v_mfma_f32_16x16x32_bf16 v[20:23], v[166:169], v[198:201], v[20:23]
	v_mfma_f32_16x16x32_bf16 v[12:15], v[174:177], v[198:201], v[12:15]
	v_mfma_f32_16x16x32_bf16 v[4:7], v[166:169], v[206:209], v[4:7]
	v_mfma_f32_16x16x32_bf16 v[0:3], v[174:177], v[206:209], v[0:3]
	v_mfma_f32_16x16x32_bf16 v[52:55], v[170:173], v[186:189], v[52:55]
	v_mfma_f32_16x16x32_bf16 v[44:47], v[178:181], v[186:189], v[44:47]
	v_mfma_f32_16x16x32_bf16 v[36:39], v[170:173], v[194:197], v[36:39]
	v_mfma_f32_16x16x32_bf16 v[28:31], v[178:181], v[194:197], v[28:31]
	v_mfma_f32_16x16x32_bf16 v[20:23], v[170:173], v[202:205], v[20:23]
	v_mfma_f32_16x16x32_bf16 v[12:15], v[178:181], v[202:205], v[12:15]
	v_mfma_f32_16x16x32_bf16 v[4:7], v[170:173], v[210:213], v[4:7]
	v_mfma_f32_16x16x32_bf16 v[0:3], v[178:181], v[210:213], v[0:3]
	s_barrier
; #define PG8_STAGE(bufoff, gbase, voff) do { _Pragma("unroll") for (int _i = 0; _i < 2; ++_i) \
;         __builtin_amdgcn_global_load_lds((const unsigned*)((const char*)(gbase) + (voff)[_i]), (LAS unsigned*)(lds + (bufoff) + ldsw + _i * 8192), 16, 0, 0); } while (0)
; #define PG8_LDA(dst, b, h) do { _Pragma("unroll") for (int m = 0; m < 4; ++m) _Pragma("unroll") for (int k = 0; k < 2; ++k) dst[m][k] = *(const LAS bf16x8*)(lds + PG8_SA(b, h) + aoff + m * 2048 + k * 1024); } while (0)
; #define PG8_LDB(dst, b, h) do { _Pragma("unroll") for (int n = 0; n < 2; ++n) _Pragma("unroll") for (int k = 0; k < 2; ++k) dst[n][k] = *(const LAS bf16x8*)(lds + PG8_SB(b, h) + boff + n * 2048 + k * 1024); } while (0)
; template <class Epi, class Sched>
; __device__ __forceinline__ void gemm_phase(LAS unsigned char* lds, const int lda, const int ldb, const int K, const Sched& S, const Epi& E) {
;     ...
;         for (int t = 0; t < nt; t += 2) {
;             const bool last = (t == nt - 2);
;             const char* a1 = cA + (size_t)(t + 1) * kstep;
;             const char* a2 = last ? nA : cA + (size_t)(t + 2) * kstep; const char* b2 = last ? nB : cB + (size_t)(t + 2) * kstep;
;             const char* a3 = a2 + kstep; const char* b3 = b2 + kstep;
;             PG8_LDB(B0, 0, 0); PG8_LDB(B1, 0, 1); PG8_SCHED; PG8_LDA(At, 0, 0); PG8_STAGE(PG8_SA(1, 1), a1 + hstepA, voffA);
;             PG8_WAIT_V(8); PG8_WAIT_L(0); PG8_BAR; PG8_MMA(0, 0, At, B0); PG8_MMA(0, 1, At, B1); PG8_BAR; PG8_SCHED;
;             PG8_LDA(At, 0, 1); PG8_STAGE(PG8_SB(0, 0), b2, voffB); PG8_STAGE(PG8_SB(0, 1), b2 + hstepB, voffB); PG8_STAGE(PG8_SA(0, 0), a2, voffA);
;             PG8_WAIT_V(8); PG8_WAIT_L(0); PG8_BAR; PG8_MMA(1, 0, At, B0); PG8_MMA(1, 1, At, B1); PG8_BAR; PG8_SCHED;
;             PG8_LDB(B0, 1, 0); PG8_LDB(B1, 1, 1); PG8_SCHED; PG8_LDA(At, 1, 0); PG8_STAGE(PG8_SA(0, 1), a2 + hstepA, voffA);
;             PG8_WAIT_V(8); PG8_WAIT_L(0); PG8_BAR; PG8_MMA(0, 0, At, B0); PG8_MMA(0, 1, At, B1); PG8_BAR; PG8_SCHED;
;             PG8_LDA(At, 1, 1); PG8_STAGE(PG8_SB(1, 0), b3, voffB); PG8_STAGE(PG8_SB(1, 1), b3 + hstepB, voffB); PG8_STAGE(PG8_SA(1, 0), a3, voffA);
;             PG8_WAIT_V(8); PG8_WAIT_L(0); PG8_BAR;
;             if (last) E.pre(cur, wr, fr, rsv);
;             PG8_MMA(1, 0, At, B0); PG8_MMA(1, 1, At, B1); PG8_BAR; PG8_SCHED;
;         }
;         if (wr == 0) PG8_BAR;
.Lpeel7_join:
	s_add_i32 s42, 0, 0x18000
	s_add_i32 s43, 0, 0x1c000
	v_add_u32_e32 v162, s42, v149
	v_add_u32_e32 v178, s43, v149
	ds_read_b128 v[144:147], v162
	ds_read_b128 v[154:157], v162 offset:1024
	ds_read_b128 v[158:161], v162 offset:2048
	ds_read_b128 v[162:165], v162 offset:3072
	ds_read_b128 v[166:169], v178
	ds_read_b128 v[170:173], v178 offset:1024
	ds_read_b128 v[174:177], v178 offset:2048
	ds_read_b128 v[178:181], v178 offset:3072
	s_add_u32 s18, s18, 0xb0000
	s_addc_u32 s19, s19, 0
	s_mov_b32 m0, s26
	ds_read_b128 v[182:185], v153 offset:32768
	ds_read_b128 v[186:189], v153 offset:33792
	ds_read_b128 v[190:193], v153 offset:34816
	ds_read_b128 v[194:197], v153 offset:35840
	ds_read_b128 v[198:201], v153 offset:36864
	ds_read_b128 v[202:205], v153 offset:37888
	ds_read_b128 v[206:209], v153 offset:38912
	ds_read_b128 v[210:213], v153 offset:39936
	global_load_lds_dwordx4 v134, s[18:19]
	s_mov_b32 m0, s27
	s_nop 0
	global_load_lds_dwordx4 v130, s[18:19]
	s_waitcnt vmcnt(8)
	s_waitcnt lgkmcnt(0)
	s_barrier
	s_waitcnt lgkmcnt(0)
	v_mfma_f32_16x16x32_bf16 v[124:127], v[144:147], v[182:185], v[124:127]
	v_mfma_f32_16x16x32_bf16 v[120:123], v[158:161], v[182:185], v[120:123]
	v_mfma_f32_16x16x32_bf16 v[112:115], v[144:147], v[190:193], v[112:115]
	v_mfma_f32_16x16x32_bf16 v[104:107], v[158:161], v[190:193], v[104:107]
	v_mfma_f32_16x16x32_bf16 v[96:99], v[144:147], v[198:201], v[96:99]
	v_mfma_f32_16x16x32_bf16 v[88:91], v[158:161], v[198:201], v[88:91]
	v_mfma_f32_16x16x32_bf16 v[80:83], v[144:147], v[206:209], v[80:83]
	v_mfma_f32_16x16x32_bf16 v[72:75], v[158:161], v[206:209], v[72:75]
	v_mfma_f32_16x16x32_bf16 v[124:127], v[154:157], v[186:189], v[124:127]
	v_mfma_f32_16x16x32_bf16 v[120:123], v[162:165], v[186:189], v[120:123]
	v_mfma_f32_16x16x32_bf16 v[112:115], v[154:157], v[194:197], v[112:115]
	v_mfma_f32_16x16x32_bf16 v[104:107], v[162:165], v[194:197], v[104:107]
	v_mfma_f32_16x16x32_bf16 v[96:99], v[154:157], v[202:205], v[96:99]
	v_mfma_f32_16x16x32_bf16 v[88:91], v[162:165], v[202:205], v[88:91]
	v_mfma_f32_16x16x32_bf16 v[80:83], v[154:157], v[210:213], v[80:83]
	v_mfma_f32_16x16x32_bf16 v[72:75], v[162:165], v[210:213], v[72:75]
	v_mfma_f32_16x16x32_bf16 v[116:119], v[166:169], v[182:185], v[116:119]
	v_mfma_f32_16x16x32_bf16 v[108:111], v[174:177], v[182:185], v[108:111]
	v_mfma_f32_16x16x32_bf16 v[100:103], v[166:169], v[190:193], v[100:103]
	v_mfma_f32_16x16x32_bf16 v[92:95], v[174:177], v[190:193], v[92:95]
	v_mfma_f32_16x16x32_bf16 v[84:87], v[166:169], v[198:201], v[84:87]
	v_mfma_f32_16x16x32_bf16 v[76:79], v[174:177], v[198:201], v[76:79]
	v_mfma_f32_16x16x32_bf16 v[68:71], v[166:169], v[206:209], v[68:71]
	v_mfma_f32_16x16x32_bf16 v[64:67], v[174:177], v[206:209], v[64:67]
	v_mfma_f32_16x16x32_bf16 v[116:119], v[170:173], v[186:189], v[116:119]
	v_mfma_f32_16x16x32_bf16 v[108:111], v[178:181], v[186:189], v[108:111]
	v_mfma_f32_16x16x32_bf16 v[100:103], v[170:173], v[194:197], v[100:103]
	v_mfma_f32_16x16x32_bf16 v[92:95], v[178:181], v[194:197], v[92:95]
	v_mfma_f32_16x16x32_bf16 v[84:87], v[170:173], v[202:205], v[84:87]
	v_mfma_f32_16x16x32_bf16 v[76:79], v[178:181], v[202:205], v[76:79]
	v_mfma_f32_16x16x32_bf16 v[68:71], v[170:173], v[210:213], v[68:71]
	v_mfma_f32_16x16x32_bf16 v[64:67], v[178:181], v[210:213], v[64:67]
	s_barrier
	s_add_i32 s18, s42, s21
	s_mov_b32 m0, s18
	ds_read_b128 v[182:185], v153 offset:49152
	ds_read_b128 v[186:189], v153 offset:50176
	ds_read_b128 v[190:193], v153 offset:51200
	ds_read_b128 v[194:197], v153 offset:52224
	ds_read_b128 v[198:201], v153 offset:53248
	ds_read_b128 v[202:205], v153 offset:54272
	ds_read_b128 v[206:209], v153 offset:55296
	ds_read_b128 v[210:213], v153 offset:56320
	global_load_lds_dwordx4 v214, s[16:17]
	s_add_i32 m0, s18, 0x2000
	s_add_u32 s16, s16, 0xb0080
	s_addc_u32 s17, s17, 0
	s_add_i32 s18, s43, s21
	global_load_lds_dwordx4 v215, s[98:99]
	s_mov_b32 m0, s18
	s_nop 0
	global_load_lds_dwordx4 v132, s[16:17]
	s_add_i32 m0, s18, 0x2000
	s_nop 0
	global_load_lds_dwordx4 v128, s[16:17]
	s_mov_b32 m0, s29
	s_nop 0
	global_load_lds_dwordx4 v216, s[100:101]
	s_mov_b32 m0, s30
	s_nop 0
	global_load_lds_dwordx4 v217, s[100:101]
	s_waitcnt vmcnt(8)
	s_waitcnt lgkmcnt(0)
	s_barrier
	s_waitcnt lgkmcnt(0)
	v_mfma_f32_16x16x32_bf16 v[60:63], v[144:147], v[182:185], v[60:63]
	v_mfma_f32_16x16x32_bf16 v[56:59], v[158:161], v[182:185], v[56:59]
	v_mfma_f32_16x16x32_bf16 v[48:51], v[144:147], v[190:193], v[48:51]
	v_mfma_f32_16x16x32_bf16 v[40:43], v[158:161], v[190:193], v[40:43]
	v_mfma_f32_16x16x32_bf16 v[32:35], v[144:147], v[198:201], v[32:35]
	v_mfma_f32_16x16x32_bf16 v[24:27], v[158:161], v[198:201], v[24:27]
	v_mfma_f32_16x16x32_bf16 v[16:19], v[144:147], v[206:209], v[16:19]
	v_mfma_f32_16x16x32_bf16 v[8:11], v[158:161], v[206:209], v[8:11]
	v_mfma_f32_16x16x32_bf16 v[60:63], v[154:157], v[186:189], v[60:63]
	v_mfma_f32_16x16x32_bf16 v[56:59], v[162:165], v[186:189], v[56:59]
	v_mfma_f32_16x16x32_bf16 v[48:51], v[154:157], v[194:197], v[48:51]
	v_mfma_f32_16x16x32_bf16 v[40:43], v[162:165], v[194:197], v[40:43]
	v_mfma_f32_16x16x32_bf16 v[32:35], v[154:157], v[202:205], v[32:35]
	v_mfma_f32_16x16x32_bf16 v[24:27], v[162:165], v[202:205], v[24:27]
	v_mfma_f32_16x16x32_bf16 v[16:19], v[154:157], v[210:213], v[16:19]
	v_mfma_f32_16x16x32_bf16 v[8:11], v[162:165], v[210:213], v[8:11]
	v_mfma_f32_16x16x32_bf16 v[52:55], v[166:169], v[182:185], v[52:55]
	v_mfma_f32_16x16x32_bf16 v[44:47], v[174:177], v[182:185], v[44:47]
	v_mfma_f32_16x16x32_bf16 v[36:39], v[166:169], v[190:193], v[36:39]
	v_mfma_f32_16x16x32_bf16 v[28:31], v[174:177], v[190:193], v[28:31]
	v_mfma_f32_16x16x32_bf16 v[20:23], v[166:169], v[198:201], v[20:23]
	v_mfma_f32_16x16x32_bf16 v[12:15], v[174:177], v[198:201], v[12:15]
	v_mfma_f32_16x16x32_bf16 v[4:7], v[166:169], v[206:209], v[4:7]
	v_mfma_f32_16x16x32_bf16 v[0:3], v[174:177], v[206:209], v[0:3]
	v_mfma_f32_16x16x32_bf16 v[52:55], v[170:173], v[186:189], v[52:55]
	v_mfma_f32_16x16x32_bf16 v[44:47], v[178:181], v[186:189], v[44:47]
	v_mfma_f32_16x16x32_bf16 v[36:39], v[170:173], v[194:197], v[36:39]
	v_mfma_f32_16x16x32_bf16 v[28:31], v[178:181], v[194:197], v[28:31]
	v_mfma_f32_16x16x32_bf16 v[20:23], v[170:173], v[202:205], v[20:23]
	v_mfma_f32_16x16x32_bf16 v[12:15], v[178:181], v[202:205], v[12:15]
	v_mfma_f32_16x16x32_bf16 v[4:7], v[170:173], v[210:213], v[4:7]
	v_mfma_f32_16x16x32_bf16 v[0:3], v[178:181], v[210:213], v[0:3]
	s_barrier
	s_add_i32 s41, s41, 2
	s_add_u32 s14, s14, 0x100
	s_addc_u32 s15, s15, 0
	s_add_u32 s39, s39, 0x100
	s_addc_u32 s40, s40, 0
	s_cmp_gt_u32 s41, 41
	s_cbranch_scc0 .LBB0_1136
	s_and_b64 vcc, exec, s[8:9]
	s_cbranch_vccz .LBB0_1139
	s_barrier
